# removed redundant post-barrier lgkmcnt(0) at the head of each MFMA segment
# baseline (speedup 1.0000x reference)
.LBB0_111:
	s_add_u32 s28, s26, 0xfffc0080
	s_addc_u32 s29, s27, -1
	s_add_i32 s57, 0, 0x10000
	s_cmp_eq_u32 s56, 12
	s_cselect_b32 s31, s19, s29
	s_cselect_b32 s30, s52, s28
	v_add_u32_e32 v150, s57, v1
	s_cselect_b32 s29, s17, s55
	s_cselect_b32 s28, s53, s54
	s_add_i32 s60, 0, 0x14000
	ds_read_b128 v[142:145], v150
	ds_read_b128 v[146:149], v150 offset:1024
	ds_read_b128 v[154:157], v150 offset:2048
	ds_read_b128 v[158:161], v150 offset:3072
	v_add_u32_e32 v150, s60, v1
	s_nop 0
	ds_read_b128 v[162:165], v150
	ds_read_b128 v[166:169], v150 offset:1024
	ds_read_b128 v[170:173], v150 offset:2048
	ds_read_b128 v[174:177], v150 offset:3072
	v_lshl_add_u64 v[150:151], s[26:27], 0, v[138:139]
	s_add_i32 m0, s43, 0xc000
	ds_read_b128 v[178:181], v152
	ds_read_b128 v[182:185], v152 offset:1024
	ds_read_b128 v[186:189], v152 offset:2048
	ds_read_b128 v[190:193], v152 offset:3072
	ds_read_b128 v[204:207], v152 offset:4096
	ds_read_b128 v[208:211], v152 offset:5120
	ds_read_b128 v[212:215], v152 offset:6144
	ds_read_b128 v[228:231], v152 offset:7168
	global_load_lds_dwordx4 v[150:151], off
	v_lshl_add_u64 v[150:151], s[26:27], 0, v[140:141]
	s_add_i32 m0, s43, 0xe000
	s_nop 0
	global_load_lds_dwordx4 v[150:151], off
	s_waitcnt vmcnt(8)
	s_waitcnt lgkmcnt(0)
	s_barrier
	s_setprio 1
	v_mfma_f32_16x16x32_bf16 v[126:129], v[142:145], v[178:181], v[126:129]
	v_mfma_f32_16x16x32_bf16 v[122:125], v[154:157], v[178:181], v[122:125]
	v_mfma_f32_16x16x32_bf16 v[110:113], v[142:145], v[186:189], v[110:113]
	v_mfma_f32_16x16x32_bf16 v[106:109], v[154:157], v[186:189], v[106:109]
	v_mfma_f32_16x16x32_bf16 v[94:97], v[142:145], v[204:207], v[94:97]
	v_mfma_f32_16x16x32_bf16 v[90:93], v[154:157], v[204:207], v[90:93]
	v_mfma_f32_16x16x32_bf16 v[78:81], v[142:145], v[212:215], v[78:81]
	v_mfma_f32_16x16x32_bf16 v[74:77], v[154:157], v[212:215], v[74:77]
	v_mfma_f32_16x16x32_bf16 v[126:129], v[146:149], v[182:185], v[126:129]
	v_mfma_f32_16x16x32_bf16 v[122:125], v[158:161], v[182:185], v[122:125]
	v_mfma_f32_16x16x32_bf16 v[110:113], v[146:149], v[190:193], v[110:113]
	v_mfma_f32_16x16x32_bf16 v[106:109], v[158:161], v[190:193], v[106:109]
	v_mfma_f32_16x16x32_bf16 v[94:97], v[146:149], v[208:211], v[94:97]
	v_mfma_f32_16x16x32_bf16 v[90:93], v[158:161], v[208:211], v[90:93]
	v_mfma_f32_16x16x32_bf16 v[78:81], v[146:149], v[228:231], v[78:81]
	v_mfma_f32_16x16x32_bf16 v[74:77], v[158:161], v[228:231], v[74:77]
	v_mfma_f32_16x16x32_bf16 v[118:121], v[162:165], v[178:181], v[118:121]
	v_mfma_f32_16x16x32_bf16 v[114:117], v[170:173], v[178:181], v[114:117]
	v_mfma_f32_16x16x32_bf16 v[102:105], v[162:165], v[186:189], v[102:105]
	v_mfma_f32_16x16x32_bf16 v[98:101], v[170:173], v[186:189], v[98:101]
	v_mfma_f32_16x16x32_bf16 v[86:89], v[162:165], v[204:207], v[86:89]
	v_mfma_f32_16x16x32_bf16 v[82:85], v[170:173], v[204:207], v[82:85]
	v_mfma_f32_16x16x32_bf16 v[70:73], v[162:165], v[212:215], v[70:73]
	v_mfma_f32_16x16x32_bf16 v[66:69], v[170:173], v[212:215], v[66:69]
	v_mfma_f32_16x16x32_bf16 v[118:121], v[166:169], v[182:185], v[118:121]
	v_mfma_f32_16x16x32_bf16 v[114:117], v[174:177], v[182:185], v[114:117]
	v_mfma_f32_16x16x32_bf16 v[102:105], v[166:169], v[190:193], v[102:105]
	v_mfma_f32_16x16x32_bf16 v[98:101], v[174:177], v[190:193], v[98:101]
	v_mfma_f32_16x16x32_bf16 v[86:89], v[166:169], v[208:211], v[86:89]
	v_mfma_f32_16x16x32_bf16 v[82:85], v[174:177], v[208:211], v[82:85]
	v_mfma_f32_16x16x32_bf16 v[70:73], v[166:169], v[228:231], v[70:73]
	v_mfma_f32_16x16x32_bf16 v[66:69], v[174:177], v[228:231], v[66:69]
	s_setprio 0
	s_barrier
	s_add_i32 s57, s57, s42
	v_lshl_add_u64 v[150:151], s[28:29], 0, v[134:135]
	s_mov_b32 m0, s57
	ds_read_b128 v[178:181], v152 offset:16384
	ds_read_b128 v[182:185], v152 offset:17408
	ds_read_b128 v[186:189], v152 offset:18432
	ds_read_b128 v[190:193], v152 offset:19456
	ds_read_b128 v[204:207], v152 offset:20480
	ds_read_b128 v[208:211], v152 offset:21504
	ds_read_b128 v[212:215], v152 offset:22528
	ds_read_b128 v[228:231], v152 offset:23552
	global_load_lds_dwordx4 v[150:151], off
	s_add_i32 m0, s57, 0x2000
	s_add_u32 s58, s28, 0x40000
	v_lshl_add_u64 v[194:195], s[28:29], 0, v[130:131]
	s_addc_u32 s59, s29, 0
	s_add_i32 s57, s60, s42
	global_load_lds_dwordx4 v[194:195], off
	v_lshl_add_u64 v[216:217], s[58:59], 0, v[134:135]
	s_mov_b32 m0, s57
	v_lshl_add_u64 v[232:233], s[30:31], 0, v[132:133]
	global_load_lds_dwordx4 v[216:217], off
	v_lshl_add_u64 v[216:217], s[58:59], 0, v[130:131]
	s_add_i32 m0, s57, 0x2000
	s_nop 0
	global_load_lds_dwordx4 v[216:217], off
	v_lshl_add_u64 v[216:217], s[30:31], 0, v[136:137]
	s_mov_b32 m0, s43
	s_nop 0
	global_load_lds_dwordx4 v[216:217], off
	s_mov_b32 m0, s44
	s_nop 0
	global_load_lds_dwordx4 v[232:233], off
	s_waitcnt vmcnt(8)
	s_waitcnt lgkmcnt(0)
	s_barrier
	s_setprio 1
	v_mfma_f32_16x16x32_bf16 v[62:65], v[142:145], v[178:181], v[62:65]
	v_mfma_f32_16x16x32_bf16 v[58:61], v[154:157], v[178:181], v[58:61]
	v_mfma_f32_16x16x32_bf16 v[46:49], v[142:145], v[186:189], v[46:49]
	v_mfma_f32_16x16x32_bf16 v[42:45], v[154:157], v[186:189], v[42:45]
	v_mfma_f32_16x16x32_bf16 v[30:33], v[142:145], v[204:207], v[30:33]
	v_mfma_f32_16x16x32_bf16 v[26:29], v[154:157], v[204:207], v[26:29]
	v_mfma_f32_16x16x32_bf16 v[14:17], v[142:145], v[212:215], v[14:17]
	v_mfma_f32_16x16x32_bf16 v[10:13], v[154:157], v[212:215], v[10:13]
	v_mfma_f32_16x16x32_bf16 v[62:65], v[146:149], v[182:185], v[62:65]
	v_mfma_f32_16x16x32_bf16 v[58:61], v[158:161], v[182:185], v[58:61]
	v_mfma_f32_16x16x32_bf16 v[46:49], v[146:149], v[190:193], v[46:49]
	v_mfma_f32_16x16x32_bf16 v[42:45], v[158:161], v[190:193], v[42:45]
	v_mfma_f32_16x16x32_bf16 v[30:33], v[146:149], v[208:211], v[30:33]
	v_mfma_f32_16x16x32_bf16 v[26:29], v[158:161], v[208:211], v[26:29]
	v_mfma_f32_16x16x32_bf16 v[14:17], v[146:149], v[228:231], v[14:17]
	v_mfma_f32_16x16x32_bf16 v[10:13], v[158:161], v[228:231], v[10:13]
	v_mfma_f32_16x16x32_bf16 v[54:57], v[162:165], v[178:181], v[54:57]
	v_mfma_f32_16x16x32_bf16 v[50:53], v[170:173], v[178:181], v[50:53]
	v_mfma_f32_16x16x32_bf16 v[38:41], v[162:165], v[186:189], v[38:41]
	v_mfma_f32_16x16x32_bf16 v[34:37], v[170:173], v[186:189], v[34:37]
	v_mfma_f32_16x16x32_bf16 v[22:25], v[162:165], v[204:207], v[22:25]
	v_mfma_f32_16x16x32_bf16 v[18:21], v[170:173], v[204:207], v[18:21]
	v_mfma_f32_16x16x32_bf16 v[6:9], v[162:165], v[212:215], v[6:9]
	v_mfma_f32_16x16x32_bf16 v[2:5], v[170:173], v[212:215], v[2:5]
	v_mfma_f32_16x16x32_bf16 v[54:57], v[166:169], v[182:185], v[54:57]
	v_mfma_f32_16x16x32_bf16 v[50:53], v[174:177], v[182:185], v[50:53]
	v_mfma_f32_16x16x32_bf16 v[38:41], v[166:169], v[190:193], v[38:41]
	v_mfma_f32_16x16x32_bf16 v[34:37], v[174:177], v[190:193], v[34:37]
	v_mfma_f32_16x16x32_bf16 v[22:25], v[166:169], v[208:211], v[22:25]
	v_mfma_f32_16x16x32_bf16 v[18:21], v[174:177], v[208:211], v[18:21]
	v_mfma_f32_16x16x32_bf16 v[6:9], v[166:169], v[228:231], v[6:9]
	v_mfma_f32_16x16x32_bf16 v[2:5], v[174:177], v[228:231], v[2:5]
	s_setprio 0
	s_barrier
	s_add_i32 s57, 0, 0x18000
	v_add_u32_e32 v153, s57, v1
	s_add_i32 s58, 0, 0x1c000
	ds_read_b128 v[142:145], v153
	ds_read_b128 v[146:149], v153 offset:1024
	ds_read_b128 v[154:157], v153 offset:2048
	ds_read_b128 v[158:161], v153 offset:3072
	v_add_u32_e32 v153, s58, v1
	ds_read_b128 v[162:165], v153
	ds_read_b128 v[166:169], v153 offset:1024
	ds_read_b128 v[170:173], v153 offset:2048
	ds_read_b128 v[174:177], v153 offset:3072
	s_add_u32 s30, s30, 0x40000
	s_addc_u32 s31, s31, 0
	s_mov_b32 m0, s45
	v_lshl_add_u64 v[234:235], s[30:31], 0, v[136:137]
	ds_read_b128 v[178:181], v152 offset:32768
	ds_read_b128 v[182:185], v152 offset:33792
	ds_read_b128 v[186:189], v152 offset:34816
	ds_read_b128 v[190:193], v152 offset:35840
	ds_read_b128 v[204:207], v152 offset:36864
	ds_read_b128 v[208:211], v152 offset:37888
	ds_read_b128 v[212:215], v152 offset:38912
	ds_read_b128 v[228:231], v152 offset:39936
	global_load_lds_dwordx4 v[234:235], off
	v_lshl_add_u64 v[234:235], s[30:31], 0, v[132:133]
	s_mov_b32 m0, s46
	s_nop 0
	global_load_lds_dwordx4 v[234:235], off
	s_waitcnt vmcnt(8)
	s_waitcnt lgkmcnt(0)
	s_barrier
	s_setprio 1
	v_mfma_f32_16x16x32_bf16 v[126:129], v[142:145], v[178:181], v[126:129]
	v_mfma_f32_16x16x32_bf16 v[122:125], v[154:157], v[178:181], v[122:125]
	v_mfma_f32_16x16x32_bf16 v[110:113], v[142:145], v[186:189], v[110:113]
	v_mfma_f32_16x16x32_bf16 v[106:109], v[154:157], v[186:189], v[106:109]
	v_mfma_f32_16x16x32_bf16 v[94:97], v[142:145], v[204:207], v[94:97]
	v_mfma_f32_16x16x32_bf16 v[90:93], v[154:157], v[204:207], v[90:93]
	v_mfma_f32_16x16x32_bf16 v[78:81], v[142:145], v[212:215], v[78:81]
	v_mfma_f32_16x16x32_bf16 v[74:77], v[154:157], v[212:215], v[74:77]
	v_mfma_f32_16x16x32_bf16 v[126:129], v[146:149], v[182:185], v[126:129]
	v_mfma_f32_16x16x32_bf16 v[122:125], v[158:161], v[182:185], v[122:125]
	v_mfma_f32_16x16x32_bf16 v[110:113], v[146:149], v[190:193], v[110:113]
	v_mfma_f32_16x16x32_bf16 v[106:109], v[158:161], v[190:193], v[106:109]
	v_mfma_f32_16x16x32_bf16 v[94:97], v[146:149], v[208:211], v[94:97]
	v_mfma_f32_16x16x32_bf16 v[90:93], v[158:161], v[208:211], v[90:93]
	v_mfma_f32_16x16x32_bf16 v[78:81], v[146:149], v[228:231], v[78:81]
	v_mfma_f32_16x16x32_bf16 v[74:77], v[158:161], v[228:231], v[74:77]
	v_mfma_f32_16x16x32_bf16 v[118:121], v[162:165], v[178:181], v[118:121]
	v_mfma_f32_16x16x32_bf16 v[114:117], v[170:173], v[178:181], v[114:117]
	v_mfma_f32_16x16x32_bf16 v[102:105], v[162:165], v[186:189], v[102:105]
	v_mfma_f32_16x16x32_bf16 v[98:101], v[170:173], v[186:189], v[98:101]
	v_mfma_f32_16x16x32_bf16 v[86:89], v[162:165], v[204:207], v[86:89]
	v_mfma_f32_16x16x32_bf16 v[82:85], v[170:173], v[204:207], v[82:85]
	v_mfma_f32_16x16x32_bf16 v[70:73], v[162:165], v[212:215], v[70:73]
	v_mfma_f32_16x16x32_bf16 v[66:69], v[170:173], v[212:215], v[66:69]
	v_mfma_f32_16x16x32_bf16 v[118:121], v[166:169], v[182:185], v[118:121]
	v_mfma_f32_16x16x32_bf16 v[114:117], v[174:177], v[182:185], v[114:117]
	v_mfma_f32_16x16x32_bf16 v[102:105], v[166:169], v[190:193], v[102:105]
	v_mfma_f32_16x16x32_bf16 v[98:101], v[174:177], v[190:193], v[98:101]
	v_mfma_f32_16x16x32_bf16 v[86:89], v[166:169], v[208:211], v[86:89]
	v_mfma_f32_16x16x32_bf16 v[82:85], v[174:177], v[208:211], v[82:85]
	v_mfma_f32_16x16x32_bf16 v[70:73], v[166:169], v[228:231], v[70:73]
	v_mfma_f32_16x16x32_bf16 v[66:69], v[174:177], v[228:231], v[66:69]
	s_setprio 0
	s_barrier
	s_add_i32 s30, s57, s42
	v_lshl_add_u64 v[150:151], v[150:151], 0, s[94:95]
	s_mov_b32 m0, s30
	ds_read_b128 v[178:181], v152 offset:49152
	ds_read_b128 v[182:185], v152 offset:50176
	ds_read_b128 v[186:189], v152 offset:51200
	ds_read_b128 v[190:193], v152 offset:52224
	ds_read_b128 v[204:207], v152 offset:53248
	ds_read_b128 v[208:211], v152 offset:54272
	ds_read_b128 v[212:215], v152 offset:55296
	ds_read_b128 v[228:231], v152 offset:56320
	global_load_lds_dwordx4 v[150:151], off
	s_add_i32 m0, s30, 0x2000
	s_add_u32 s28, s28, 0x40080
	v_lshl_add_u64 v[150:151], v[194:195], 0, s[94:95]
	s_addc_u32 s29, s29, 0
	s_add_i32 s30, s58, s42
	global_load_lds_dwordx4 v[150:151], off
	v_lshl_add_u64 v[150:151], s[28:29], 0, v[134:135]
	s_mov_b32 m0, s30
	s_nop 0
	global_load_lds_dwordx4 v[150:151], off
	v_lshl_add_u64 v[150:151], s[28:29], 0, v[130:131]
	s_add_i32 m0, s30, 0x2000
	s_nop 0
	global_load_lds_dwordx4 v[150:151], off
	v_lshl_add_u64 v[150:151], v[216:217], 0, s[94:95]
	s_mov_b32 m0, s49
	s_nop 0
	global_load_lds_dwordx4 v[150:151], off
	v_lshl_add_u64 v[150:151], v[232:233], 0, s[94:95]
	s_mov_b32 m0, s50
	s_nop 0
	global_load_lds_dwordx4 v[150:151], off
	s_waitcnt vmcnt(8)
	s_waitcnt lgkmcnt(0)
	s_barrier
	s_setprio 1
	v_mfma_f32_16x16x32_bf16 v[62:65], v[142:145], v[178:181], v[62:65]
	v_mfma_f32_16x16x32_bf16 v[58:61], v[154:157], v[178:181], v[58:61]
	v_mfma_f32_16x16x32_bf16 v[46:49], v[142:145], v[186:189], v[46:49]
	v_mfma_f32_16x16x32_bf16 v[42:45], v[154:157], v[186:189], v[42:45]
	v_mfma_f32_16x16x32_bf16 v[30:33], v[142:145], v[204:207], v[30:33]
	v_mfma_f32_16x16x32_bf16 v[26:29], v[154:157], v[204:207], v[26:29]
	v_mfma_f32_16x16x32_bf16 v[14:17], v[142:145], v[212:215], v[14:17]
	v_mfma_f32_16x16x32_bf16 v[10:13], v[154:157], v[212:215], v[10:13]
	v_mfma_f32_16x16x32_bf16 v[62:65], v[146:149], v[182:185], v[62:65]
	v_mfma_f32_16x16x32_bf16 v[58:61], v[158:161], v[182:185], v[58:61]
	v_mfma_f32_16x16x32_bf16 v[46:49], v[146:149], v[190:193], v[46:49]
	v_mfma_f32_16x16x32_bf16 v[42:45], v[158:161], v[190:193], v[42:45]
	v_mfma_f32_16x16x32_bf16 v[30:33], v[146:149], v[208:211], v[30:33]
	v_mfma_f32_16x16x32_bf16 v[26:29], v[158:161], v[208:211], v[26:29]
	v_mfma_f32_16x16x32_bf16 v[14:17], v[146:149], v[228:231], v[14:17]
	v_mfma_f32_16x16x32_bf16 v[10:13], v[158:161], v[228:231], v[10:13]
	v_mfma_f32_16x16x32_bf16 v[54:57], v[162:165], v[178:181], v[54:57]
	v_mfma_f32_16x16x32_bf16 v[50:53], v[170:173], v[178:181], v[50:53]
	v_mfma_f32_16x16x32_bf16 v[38:41], v[162:165], v[186:189], v[38:41]
	v_mfma_f32_16x16x32_bf16 v[34:37], v[170:173], v[186:189], v[34:37]
	v_mfma_f32_16x16x32_bf16 v[22:25], v[162:165], v[204:207], v[22:25]
	v_mfma_f32_16x16x32_bf16 v[18:21], v[170:173], v[204:207], v[18:21]
	v_mfma_f32_16x16x32_bf16 v[6:9], v[162:165], v[212:215], v[6:9]
	v_mfma_f32_16x16x32_bf16 v[2:5], v[170:173], v[212:215], v[2:5]
	v_mfma_f32_16x16x32_bf16 v[54:57], v[166:169], v[182:185], v[54:57]
	v_mfma_f32_16x16x32_bf16 v[50:53], v[174:177], v[182:185], v[50:53]
	v_mfma_f32_16x16x32_bf16 v[38:41], v[166:169], v[190:193], v[38:41]
	v_mfma_f32_16x16x32_bf16 v[34:37], v[174:177], v[190:193], v[34:37]
	v_mfma_f32_16x16x32_bf16 v[22:25], v[166:169], v[208:211], v[22:25]
	v_mfma_f32_16x16x32_bf16 v[18:21], v[174:177], v[208:211], v[18:21]
	v_mfma_f32_16x16x32_bf16 v[6:9], v[166:169], v[228:231], v[6:9]
	v_mfma_f32_16x16x32_bf16 v[2:5], v[174:177], v[228:231], v[2:5]
	s_setprio 0
	s_barrier
	s_add_i32 s56, s56, 2
	s_add_u32 s26, s26, 0x100
	s_addc_u32 s27, s27, 0
	s_add_u32 s54, s54, 0x100
	s_addc_u32 s55, s55, 0
	s_cmp_gt_u32 s56, 13
	s_cbranch_scc0 .LBB0_111
	s_and_b64 vcc, exec, s[14:15]
	s_cbranch_vccz .LBB0_114
	s_barrier

.LBB0_139:
	s_add_u32 s28, s26, 0xfffc0080
	s_addc_u32 s29, s27, -1
	s_add_i32 s64, 0, 0x10000
	s_cmp_eq_u32 s63, 12
	s_cselect_b32 s31, s21, s29
	s_cselect_b32 s30, s59, s28
	v_add_u32_e32 v143, s64, v1
	s_cselect_b32 s29, s19, s62
	s_cselect_b32 s28, s60, s61
	s_add_i32 s66, 0, 0x14000
	ds_read_b128 v[144:147], v143
	ds_read_b128 v[148:151], v143 offset:1024
	ds_read_b128 v[152:155], v143 offset:2048
	ds_read_b128 v[156:159], v143 offset:3072
	v_add_u32_e32 v143, s66, v1
	ds_read_b128 v[160:163], v143
	ds_read_b128 v[164:167], v143 offset:1024
	ds_read_b128 v[168:171], v143 offset:2048
	ds_read_b128 v[172:175], v143 offset:3072
	v_lshl_add_u64 v[216:217], s[26:27], 0, v[138:139]
	s_add_i32 m0, s50, 0xc000
	ds_read_b128 v[176:179], v142
	ds_read_b128 v[180:183], v142 offset:1024
	ds_read_b128 v[184:187], v142 offset:2048
	ds_read_b128 v[188:191], v142 offset:3072
	ds_read_b128 v[192:195], v142 offset:4096
	ds_read_b128 v[204:207], v142 offset:5120
	ds_read_b128 v[208:211], v142 offset:6144
	ds_read_b128 v[212:215], v142 offset:7168
	global_load_lds_dwordx4 v[216:217], off
	v_lshl_add_u64 v[216:217], s[26:27], 0, v[140:141]
	s_add_i32 m0, s50, 0xe000
	s_nop 0
	global_load_lds_dwordx4 v[216:217], off
	s_waitcnt vmcnt(8)
	s_waitcnt lgkmcnt(0)
	s_barrier
	s_setprio 1
	v_mfma_f32_16x16x32_bf16 v[126:129], v[144:147], v[176:179], v[126:129]
	v_mfma_f32_16x16x32_bf16 v[122:125], v[152:155], v[176:179], v[122:125]
	v_mfma_f32_16x16x32_bf16 v[118:121], v[144:147], v[184:187], v[118:121]
	v_mfma_f32_16x16x32_bf16 v[114:117], v[152:155], v[184:187], v[114:117]
	v_mfma_f32_16x16x32_bf16 v[102:105], v[144:147], v[192:195], v[102:105]
	v_mfma_f32_16x16x32_bf16 v[98:101], v[152:155], v[192:195], v[98:101]
	v_mfma_f32_16x16x32_bf16 v[86:89], v[144:147], v[208:211], v[86:89]
	v_mfma_f32_16x16x32_bf16 v[82:85], v[152:155], v[208:211], v[82:85]
	v_mfma_f32_16x16x32_bf16 v[126:129], v[148:151], v[180:183], v[126:129]
	v_mfma_f32_16x16x32_bf16 v[122:125], v[156:159], v[180:183], v[122:125]
	v_mfma_f32_16x16x32_bf16 v[118:121], v[148:151], v[188:191], v[118:121]
	v_mfma_f32_16x16x32_bf16 v[114:117], v[156:159], v[188:191], v[114:117]
	v_mfma_f32_16x16x32_bf16 v[102:105], v[148:151], v[204:207], v[102:105]
	v_mfma_f32_16x16x32_bf16 v[98:101], v[156:159], v[204:207], v[98:101]
	v_mfma_f32_16x16x32_bf16 v[86:89], v[148:151], v[212:215], v[86:89]
	v_mfma_f32_16x16x32_bf16 v[82:85], v[156:159], v[212:215], v[82:85]
	v_mfma_f32_16x16x32_bf16 v[110:113], v[160:163], v[176:179], v[110:113]
	v_mfma_f32_16x16x32_bf16 v[106:109], v[168:171], v[176:179], v[106:109]
	v_mfma_f32_16x16x32_bf16 v[94:97], v[160:163], v[184:187], v[94:97]
	v_mfma_f32_16x16x32_bf16 v[90:93], v[168:171], v[184:187], v[90:93]
	v_mfma_f32_16x16x32_bf16 v[78:81], v[160:163], v[192:195], v[78:81]
	v_mfma_f32_16x16x32_bf16 v[74:77], v[168:171], v[192:195], v[74:77]
	v_mfma_f32_16x16x32_bf16 v[70:73], v[160:163], v[208:211], v[70:73]
	v_mfma_f32_16x16x32_bf16 v[66:69], v[168:171], v[208:211], v[66:69]
	v_mfma_f32_16x16x32_bf16 v[110:113], v[164:167], v[180:183], v[110:113]
	v_mfma_f32_16x16x32_bf16 v[106:109], v[172:175], v[180:183], v[106:109]
	v_mfma_f32_16x16x32_bf16 v[94:97], v[164:167], v[188:191], v[94:97]
	v_mfma_f32_16x16x32_bf16 v[90:93], v[172:175], v[188:191], v[90:93]
	v_mfma_f32_16x16x32_bf16 v[78:81], v[164:167], v[204:207], v[78:81]
	v_mfma_f32_16x16x32_bf16 v[74:77], v[172:175], v[204:207], v[74:77]
	v_mfma_f32_16x16x32_bf16 v[70:73], v[164:167], v[212:215], v[70:73]
	v_mfma_f32_16x16x32_bf16 v[66:69], v[172:175], v[212:215], v[66:69]
	s_setprio 0
	s_barrier
	s_add_i32 s64, s64, s49
	v_lshl_add_u64 v[216:217], s[28:29], 0, v[132:133]
	s_mov_b32 m0, s64
	ds_read_b128 v[176:179], v142 offset:16384
	ds_read_b128 v[180:183], v142 offset:17408
	ds_read_b128 v[184:187], v142 offset:18432
	ds_read_b128 v[188:191], v142 offset:19456
	ds_read_b128 v[192:195], v142 offset:20480
	ds_read_b128 v[204:207], v142 offset:21504
	ds_read_b128 v[208:211], v142 offset:22528
	ds_read_b128 v[212:215], v142 offset:23552
	global_load_lds_dwordx4 v[216:217], off
	s_add_i32 m0, s64, 0x2000
	s_add_u32 s64, s28, 0x40000
	v_lshl_add_u64 v[228:229], s[28:29], 0, v[136:137]
	s_addc_u32 s65, s29, 0
	s_add_i32 s66, s66, s49
	global_load_lds_dwordx4 v[228:229], off
	v_lshl_add_u64 v[230:231], s[64:65], 0, v[132:133]
	s_mov_b32 m0, s66
	v_lshl_add_u64 v[232:233], s[30:31], 0, v[134:135]
	global_load_lds_dwordx4 v[230:231], off
	v_lshl_add_u64 v[230:231], s[64:65], 0, v[136:137]
	s_add_i32 m0, s66, 0x2000
	s_nop 0
	global_load_lds_dwordx4 v[230:231], off
	v_lshl_add_u64 v[230:231], s[30:31], 0, v[130:131]
	s_mov_b32 m0, s50
	s_nop 0
	global_load_lds_dwordx4 v[230:231], off
	s_mov_b32 m0, s51
	s_nop 0
	global_load_lds_dwordx4 v[232:233], off
	s_waitcnt vmcnt(8)
	s_waitcnt lgkmcnt(0)
	s_barrier
	s_setprio 1
	v_mfma_f32_16x16x32_bf16 v[62:65], v[144:147], v[176:179], v[62:65]
	v_mfma_f32_16x16x32_bf16 v[58:61], v[152:155], v[176:179], v[58:61]
	v_mfma_f32_16x16x32_bf16 v[54:57], v[144:147], v[184:187], v[54:57]
	v_mfma_f32_16x16x32_bf16 v[50:53], v[152:155], v[184:187], v[50:53]
	v_mfma_f32_16x16x32_bf16 v[38:41], v[144:147], v[192:195], v[38:41]
	v_mfma_f32_16x16x32_bf16 v[34:37], v[152:155], v[192:195], v[34:37]
	v_mfma_f32_16x16x32_bf16 v[22:25], v[144:147], v[208:211], v[22:25]
	v_mfma_f32_16x16x32_bf16 v[18:21], v[152:155], v[208:211], v[18:21]
	v_mfma_f32_16x16x32_bf16 v[62:65], v[148:151], v[180:183], v[62:65]
	v_mfma_f32_16x16x32_bf16 v[58:61], v[156:159], v[180:183], v[58:61]
	v_mfma_f32_16x16x32_bf16 v[54:57], v[148:151], v[188:191], v[54:57]
	v_mfma_f32_16x16x32_bf16 v[50:53], v[156:159], v[188:191], v[50:53]
	v_mfma_f32_16x16x32_bf16 v[38:41], v[148:151], v[204:207], v[38:41]
	v_mfma_f32_16x16x32_bf16 v[34:37], v[156:159], v[204:207], v[34:37]
	v_mfma_f32_16x16x32_bf16 v[22:25], v[148:151], v[212:215], v[22:25]
	v_mfma_f32_16x16x32_bf16 v[18:21], v[156:159], v[212:215], v[18:21]
	v_mfma_f32_16x16x32_bf16 v[46:49], v[160:163], v[176:179], v[46:49]
	v_mfma_f32_16x16x32_bf16 v[42:45], v[168:171], v[176:179], v[42:45]
	v_mfma_f32_16x16x32_bf16 v[30:33], v[160:163], v[184:187], v[30:33]
	v_mfma_f32_16x16x32_bf16 v[26:29], v[168:171], v[184:187], v[26:29]
	v_mfma_f32_16x16x32_bf16 v[14:17], v[160:163], v[192:195], v[14:17]
	v_mfma_f32_16x16x32_bf16 v[10:13], v[168:171], v[192:195], v[10:13]
	v_mfma_f32_16x16x32_bf16 v[6:9], v[160:163], v[208:211], v[6:9]
	v_mfma_f32_16x16x32_bf16 v[2:5], v[168:171], v[208:211], v[2:5]
	v_mfma_f32_16x16x32_bf16 v[46:49], v[164:167], v[180:183], v[46:49]
	v_mfma_f32_16x16x32_bf16 v[42:45], v[172:175], v[180:183], v[42:45]
	v_mfma_f32_16x16x32_bf16 v[30:33], v[164:167], v[188:191], v[30:33]
	v_mfma_f32_16x16x32_bf16 v[26:29], v[172:175], v[188:191], v[26:29]
	v_mfma_f32_16x16x32_bf16 v[14:17], v[164:167], v[204:207], v[14:17]
	v_mfma_f32_16x16x32_bf16 v[10:13], v[172:175], v[204:207], v[10:13]
	v_mfma_f32_16x16x32_bf16 v[6:9], v[164:167], v[212:215], v[6:9]
	v_mfma_f32_16x16x32_bf16 v[2:5], v[172:175], v[212:215], v[2:5]
	s_setprio 0
	s_barrier
	s_add_i32 s64, 0, 0x18000
	v_add_u32_e32 v143, s64, v1
	s_add_i32 s65, 0, 0x1c000
	ds_read_b128 v[144:147], v143
	ds_read_b128 v[148:151], v143 offset:1024
	ds_read_b128 v[152:155], v143 offset:2048
	ds_read_b128 v[156:159], v143 offset:3072
	v_add_u32_e32 v143, s65, v1
	ds_read_b128 v[160:163], v143
	ds_read_b128 v[164:167], v143 offset:1024
	ds_read_b128 v[168:171], v143 offset:2048
	ds_read_b128 v[172:175], v143 offset:3072
	s_add_u32 s30, s30, 0x40000
	s_addc_u32 s31, s31, 0
	s_mov_b32 m0, s52
	v_lshl_add_u64 v[234:235], s[30:31], 0, v[130:131]
	ds_read_b128 v[176:179], v142 offset:32768
	ds_read_b128 v[180:183], v142 offset:33792
	ds_read_b128 v[184:187], v142 offset:34816
	ds_read_b128 v[188:191], v142 offset:35840
	ds_read_b128 v[192:195], v142 offset:36864
	ds_read_b128 v[204:207], v142 offset:37888
	ds_read_b128 v[208:211], v142 offset:38912
	ds_read_b128 v[212:215], v142 offset:39936
	global_load_lds_dwordx4 v[234:235], off
	v_lshl_add_u64 v[234:235], s[30:31], 0, v[134:135]
	s_mov_b32 m0, s53
	s_nop 0
	global_load_lds_dwordx4 v[234:235], off
	s_waitcnt vmcnt(8)
	s_waitcnt lgkmcnt(0)
	s_barrier
	s_setprio 1
	v_mfma_f32_16x16x32_bf16 v[126:129], v[144:147], v[176:179], v[126:129]
	v_mfma_f32_16x16x32_bf16 v[122:125], v[152:155], v[176:179], v[122:125]
	v_mfma_f32_16x16x32_bf16 v[118:121], v[144:147], v[184:187], v[118:121]
	v_mfma_f32_16x16x32_bf16 v[114:117], v[152:155], v[184:187], v[114:117]
	v_mfma_f32_16x16x32_bf16 v[102:105], v[144:147], v[192:195], v[102:105]
	v_mfma_f32_16x16x32_bf16 v[98:101], v[152:155], v[192:195], v[98:101]
	v_mfma_f32_16x16x32_bf16 v[86:89], v[144:147], v[208:211], v[86:89]
	v_mfma_f32_16x16x32_bf16 v[82:85], v[152:155], v[208:211], v[82:85]
	v_mfma_f32_16x16x32_bf16 v[126:129], v[148:151], v[180:183], v[126:129]
	v_mfma_f32_16x16x32_bf16 v[122:125], v[156:159], v[180:183], v[122:125]
	v_mfma_f32_16x16x32_bf16 v[118:121], v[148:151], v[188:191], v[118:121]
	v_mfma_f32_16x16x32_bf16 v[114:117], v[156:159], v[188:191], v[114:117]
	v_mfma_f32_16x16x32_bf16 v[102:105], v[148:151], v[204:207], v[102:105]
	v_mfma_f32_16x16x32_bf16 v[98:101], v[156:159], v[204:207], v[98:101]
	v_mfma_f32_16x16x32_bf16 v[86:89], v[148:151], v[212:215], v[86:89]
	v_mfma_f32_16x16x32_bf16 v[82:85], v[156:159], v[212:215], v[82:85]
	v_mfma_f32_16x16x32_bf16 v[110:113], v[160:163], v[176:179], v[110:113]
	v_mfma_f32_16x16x32_bf16 v[106:109], v[168:171], v[176:179], v[106:109]
	v_mfma_f32_16x16x32_bf16 v[94:97], v[160:163], v[184:187], v[94:97]
	v_mfma_f32_16x16x32_bf16 v[90:93], v[168:171], v[184:187], v[90:93]
	v_mfma_f32_16x16x32_bf16 v[78:81], v[160:163], v[192:195], v[78:81]
	v_mfma_f32_16x16x32_bf16 v[74:77], v[168:171], v[192:195], v[74:77]
	v_mfma_f32_16x16x32_bf16 v[70:73], v[160:163], v[208:211], v[70:73]
	v_mfma_f32_16x16x32_bf16 v[66:69], v[168:171], v[208:211], v[66:69]
	v_mfma_f32_16x16x32_bf16 v[110:113], v[164:167], v[180:183], v[110:113]
	v_mfma_f32_16x16x32_bf16 v[106:109], v[172:175], v[180:183], v[106:109]
	v_mfma_f32_16x16x32_bf16 v[94:97], v[164:167], v[188:191], v[94:97]
	v_mfma_f32_16x16x32_bf16 v[90:93], v[172:175], v[188:191], v[90:93]
	v_mfma_f32_16x16x32_bf16 v[78:81], v[164:167], v[204:207], v[78:81]
	v_mfma_f32_16x16x32_bf16 v[74:77], v[172:175], v[204:207], v[74:77]
	v_mfma_f32_16x16x32_bf16 v[70:73], v[164:167], v[212:215], v[70:73]
	v_mfma_f32_16x16x32_bf16 v[66:69], v[172:175], v[212:215], v[66:69]
	s_setprio 0
	s_barrier
	s_add_i32 s30, s64, s49
	v_lshl_add_u64 v[216:217], v[216:217], 0, s[94:95]
	s_mov_b32 m0, s30
	ds_read_b128 v[176:179], v142 offset:49152
	ds_read_b128 v[180:183], v142 offset:50176
	ds_read_b128 v[184:187], v142 offset:51200
	ds_read_b128 v[188:191], v142 offset:52224
	ds_read_b128 v[192:195], v142 offset:53248
	ds_read_b128 v[204:207], v142 offset:54272
	ds_read_b128 v[208:211], v142 offset:55296
	ds_read_b128 v[212:215], v142 offset:56320
	global_load_lds_dwordx4 v[216:217], off
	s_add_i32 m0, s30, 0x2000
	s_add_u32 s28, s28, 0x40080
	v_lshl_add_u64 v[216:217], v[228:229], 0, s[94:95]
	s_addc_u32 s29, s29, 0
	s_add_i32 s30, s65, s49
	global_load_lds_dwordx4 v[216:217], off
	v_lshl_add_u64 v[216:217], s[28:29], 0, v[132:133]
	s_mov_b32 m0, s30
	s_nop 0
	global_load_lds_dwordx4 v[216:217], off
	v_lshl_add_u64 v[216:217], s[28:29], 0, v[136:137]
	s_add_i32 m0, s30, 0x2000
	s_nop 0
	global_load_lds_dwordx4 v[216:217], off
	v_lshl_add_u64 v[216:217], v[230:231], 0, s[94:95]
	s_mov_b32 m0, s56
	s_nop 0
	global_load_lds_dwordx4 v[216:217], off
	v_lshl_add_u64 v[216:217], v[232:233], 0, s[94:95]
	s_mov_b32 m0, s57
	s_nop 0
	global_load_lds_dwordx4 v[216:217], off
	s_waitcnt vmcnt(8)
	s_waitcnt lgkmcnt(0)
	s_barrier
	s_setprio 1
	v_mfma_f32_16x16x32_bf16 v[62:65], v[144:147], v[176:179], v[62:65]
	v_mfma_f32_16x16x32_bf16 v[58:61], v[152:155], v[176:179], v[58:61]
	v_mfma_f32_16x16x32_bf16 v[54:57], v[144:147], v[184:187], v[54:57]
	v_mfma_f32_16x16x32_bf16 v[50:53], v[152:155], v[184:187], v[50:53]
	v_mfma_f32_16x16x32_bf16 v[38:41], v[144:147], v[192:195], v[38:41]
	v_mfma_f32_16x16x32_bf16 v[34:37], v[152:155], v[192:195], v[34:37]
	v_mfma_f32_16x16x32_bf16 v[22:25], v[144:147], v[208:211], v[22:25]
	v_mfma_f32_16x16x32_bf16 v[18:21], v[152:155], v[208:211], v[18:21]
	v_mfma_f32_16x16x32_bf16 v[62:65], v[148:151], v[180:183], v[62:65]
	v_mfma_f32_16x16x32_bf16 v[58:61], v[156:159], v[180:183], v[58:61]
	v_mfma_f32_16x16x32_bf16 v[54:57], v[148:151], v[188:191], v[54:57]
	v_mfma_f32_16x16x32_bf16 v[50:53], v[156:159], v[188:191], v[50:53]
	v_mfma_f32_16x16x32_bf16 v[38:41], v[148:151], v[204:207], v[38:41]
	v_mfma_f32_16x16x32_bf16 v[34:37], v[156:159], v[204:207], v[34:37]
	v_mfma_f32_16x16x32_bf16 v[22:25], v[148:151], v[212:215], v[22:25]
	v_mfma_f32_16x16x32_bf16 v[18:21], v[156:159], v[212:215], v[18:21]
	v_mfma_f32_16x16x32_bf16 v[46:49], v[160:163], v[176:179], v[46:49]
	v_mfma_f32_16x16x32_bf16 v[42:45], v[168:171], v[176:179], v[42:45]
	v_mfma_f32_16x16x32_bf16 v[30:33], v[160:163], v[184:187], v[30:33]
	v_mfma_f32_16x16x32_bf16 v[26:29], v[168:171], v[184:187], v[26:29]
	v_mfma_f32_16x16x32_bf16 v[14:17], v[160:163], v[192:195], v[14:17]
	v_mfma_f32_16x16x32_bf16 v[10:13], v[168:171], v[192:195], v[10:13]
	v_mfma_f32_16x16x32_bf16 v[6:9], v[160:163], v[208:211], v[6:9]
	v_mfma_f32_16x16x32_bf16 v[2:5], v[168:171], v[208:211], v[2:5]
	v_mfma_f32_16x16x32_bf16 v[46:49], v[164:167], v[180:183], v[46:49]
	v_mfma_f32_16x16x32_bf16 v[42:45], v[172:175], v[180:183], v[42:45]
	v_mfma_f32_16x16x32_bf16 v[30:33], v[164:167], v[188:191], v[30:33]
	v_mfma_f32_16x16x32_bf16 v[26:29], v[172:175], v[188:191], v[26:29]
	v_mfma_f32_16x16x32_bf16 v[14:17], v[164:167], v[204:207], v[14:17]
	v_mfma_f32_16x16x32_bf16 v[10:13], v[172:175], v[204:207], v[10:13]
	v_mfma_f32_16x16x32_bf16 v[6:9], v[164:167], v[212:215], v[6:9]
	v_mfma_f32_16x16x32_bf16 v[2:5], v[172:175], v[212:215], v[2:5]
	s_setprio 0
	s_barrier
	s_add_i32 s63, s63, 2
	s_add_u32 s26, s26, 0x100
	s_addc_u32 s27, s27, 0
	s_add_u32 s61, s61, 0x100
	s_addc_u32 s62, s62, 0
	s_cmp_gt_u32 s63, 13
	s_cbranch_scc0 .LBB0_139
	s_and_b64 vcc, exec, s[10:11]
	s_cbranch_vccz .LBB0_142
	s_barrier

.LBB0_220:
	s_add_u32 s26, s24, 0x100
	s_addc_u32 s27, s25, 0
	s_add_i32 s59, 0, 0x10000
	s_cmp_eq_u32 s58, 40
	s_cselect_b32 s31, s7, s27
	s_cselect_b32 s30, s6, s26
	s_cselect_b32 s29, s23, s57
	s_cselect_b32 s28, s22, s56
	s_add_i32 s60, 0, 0x14000
	v_add_u32_e32 v134, s59, v1
	v_add_u32_e32 v154, s60, v1
	ds_read_b128 v[110:113], v134
	ds_read_b128 v[118:121], v134 offset:1024
	ds_read_b128 v[122:125], v134 offset:2048
	ds_read_b128 v[134:137], v134 offset:3072
	ds_read_b128 v[138:141], v154
	ds_read_b128 v[142:145], v154 offset:1024
	ds_read_b128 v[146:149], v154 offset:2048
	ds_read_b128 v[154:157], v154 offset:3072
	v_lshl_add_u64 v[216:217], s[24:25], 0, v[206:207]
	s_add_i32 m0, s41, 0xc000
	ds_read_b128 v[162:165], v214
	ds_read_b128 v[166:169], v214 offset:1024
	ds_read_b128 v[170:173], v214 offset:2048
	ds_read_b128 v[174:177], v214 offset:3072
	ds_read_b128 v[178:181], v214 offset:4096
	ds_read_b128 v[182:185], v214 offset:5120
	ds_read_b128 v[186:189], v214 offset:6144
	ds_read_b128 v[210:213], v214 offset:7168
	global_load_lds_dwordx4 v[216:217], off
	v_lshl_add_u64 v[216:217], s[24:25], 0, v[208:209]
	s_add_i32 m0, s41, 0xe000
	s_nop 0
	global_load_lds_dwordx4 v[216:217], off
	s_waitcnt vmcnt(8)
	s_waitcnt lgkmcnt(0)
	s_barrier
	s_setprio 1
	v_mfma_f32_16x16x32_bf16 v[158:161], v[110:113], v[162:165], v[158:161]
	v_mfma_f32_16x16x32_bf16 v[150:153], v[122:125], v[162:165], v[150:153]
	v_mfma_f32_16x16x32_bf16 v[114:117], v[110:113], v[170:173], v[114:117]
	v_mfma_f32_16x16x32_bf16 v[106:109], v[122:125], v[170:173], v[106:109]
	v_mfma_f32_16x16x32_bf16 v[94:97], v[110:113], v[178:181], v[94:97]
	v_mfma_f32_16x16x32_bf16 v[90:93], v[122:125], v[178:181], v[90:93]
	v_mfma_f32_16x16x32_bf16 v[78:81], v[110:113], v[186:189], v[78:81]
	v_mfma_f32_16x16x32_bf16 v[74:77], v[122:125], v[186:189], v[74:77]
	v_mfma_f32_16x16x32_bf16 v[158:161], v[118:121], v[166:169], v[158:161]
	v_mfma_f32_16x16x32_bf16 v[150:153], v[134:137], v[166:169], v[150:153]
	v_mfma_f32_16x16x32_bf16 v[114:117], v[118:121], v[174:177], v[114:117]
	v_mfma_f32_16x16x32_bf16 v[106:109], v[134:137], v[174:177], v[106:109]
	v_mfma_f32_16x16x32_bf16 v[94:97], v[118:121], v[182:185], v[94:97]
	v_mfma_f32_16x16x32_bf16 v[90:93], v[134:137], v[182:185], v[90:93]
	v_mfma_f32_16x16x32_bf16 v[78:81], v[118:121], v[210:213], v[78:81]
	v_mfma_f32_16x16x32_bf16 v[74:77], v[134:137], v[210:213], v[74:77]
	v_mfma_f32_16x16x32_bf16 v[130:133], v[138:141], v[162:165], v[130:133]
	v_mfma_f32_16x16x32_bf16 v[126:129], v[146:149], v[162:165], v[126:129]
	v_mfma_f32_16x16x32_bf16 v[102:105], v[138:141], v[170:173], v[102:105]
	v_mfma_f32_16x16x32_bf16 v[98:101], v[146:149], v[170:173], v[98:101]
	v_mfma_f32_16x16x32_bf16 v[86:89], v[138:141], v[178:181], v[86:89]
	v_mfma_f32_16x16x32_bf16 v[82:85], v[146:149], v[178:181], v[82:85]
	v_mfma_f32_16x16x32_bf16 v[70:73], v[138:141], v[186:189], v[70:73]
	v_mfma_f32_16x16x32_bf16 v[66:69], v[146:149], v[186:189], v[66:69]
	v_mfma_f32_16x16x32_bf16 v[130:133], v[142:145], v[166:169], v[130:133]
	v_mfma_f32_16x16x32_bf16 v[126:129], v[154:157], v[166:169], v[126:129]
	v_mfma_f32_16x16x32_bf16 v[102:105], v[142:145], v[174:177], v[102:105]
	v_mfma_f32_16x16x32_bf16 v[98:101], v[154:157], v[174:177], v[98:101]
	v_mfma_f32_16x16x32_bf16 v[86:89], v[142:145], v[182:185], v[86:89]
	v_mfma_f32_16x16x32_bf16 v[82:85], v[154:157], v[182:185], v[82:85]
	v_mfma_f32_16x16x32_bf16 v[70:73], v[142:145], v[210:213], v[70:73]
	v_mfma_f32_16x16x32_bf16 v[66:69], v[154:157], v[210:213], v[66:69]
	s_setprio 0
	s_barrier
	s_add_i32 s24, s59, s40
	v_lshl_add_u64 v[216:217], s[28:29], 0, v[192:193]
	s_mov_b32 m0, s24
	ds_read_b128 v[162:165], v214 offset:16384
	ds_read_b128 v[166:169], v214 offset:17408
	ds_read_b128 v[170:173], v214 offset:18432
	ds_read_b128 v[174:177], v214 offset:19456
	ds_read_b128 v[178:181], v214 offset:20480
	ds_read_b128 v[182:185], v214 offset:21504
	ds_read_b128 v[186:189], v214 offset:22528
	ds_read_b128 v[210:213], v214 offset:23552
	global_load_lds_dwordx4 v[216:217], off
	s_add_i32 m0, s24, 0x2000
	s_add_u32 s24, s28, 0xb0000
	v_lshl_add_u64 v[228:229], s[28:29], 0, v[204:205]
	s_addc_u32 s25, s29, 0
	s_add_i32 s59, s60, s40
	global_load_lds_dwordx4 v[228:229], off
	v_lshl_add_u64 v[230:231], s[24:25], 0, v[192:193]
	s_mov_b32 m0, s59
	v_lshl_add_u64 v[232:233], s[30:31], 0, v[194:195]
	global_load_lds_dwordx4 v[230:231], off
	v_lshl_add_u64 v[230:231], s[24:25], 0, v[204:205]
	s_add_i32 m0, s59, 0x2000
	s_nop 0
	global_load_lds_dwordx4 v[230:231], off
	v_lshl_add_u64 v[230:231], s[30:31], 0, v[190:191]
	s_mov_b32 m0, s41
	s_nop 0
	global_load_lds_dwordx4 v[230:231], off
	s_mov_b32 m0, s42
	s_nop 0
	global_load_lds_dwordx4 v[232:233], off
	s_waitcnt vmcnt(8)
	s_waitcnt lgkmcnt(0)
	s_barrier
	s_setprio 1
	v_mfma_f32_16x16x32_bf16 v[62:65], v[110:113], v[162:165], v[62:65]
	v_mfma_f32_16x16x32_bf16 v[58:61], v[122:125], v[162:165], v[58:61]
	v_mfma_f32_16x16x32_bf16 v[46:49], v[110:113], v[170:173], v[46:49]
	v_mfma_f32_16x16x32_bf16 v[42:45], v[122:125], v[170:173], v[42:45]
	v_mfma_f32_16x16x32_bf16 v[30:33], v[110:113], v[178:181], v[30:33]
	v_mfma_f32_16x16x32_bf16 v[26:29], v[122:125], v[178:181], v[26:29]
	v_mfma_f32_16x16x32_bf16 v[14:17], v[110:113], v[186:189], v[14:17]
	v_mfma_f32_16x16x32_bf16 v[10:13], v[122:125], v[186:189], v[10:13]
	v_mfma_f32_16x16x32_bf16 v[62:65], v[118:121], v[166:169], v[62:65]
	v_mfma_f32_16x16x32_bf16 v[58:61], v[134:137], v[166:169], v[58:61]
	v_mfma_f32_16x16x32_bf16 v[46:49], v[118:121], v[174:177], v[46:49]
	v_mfma_f32_16x16x32_bf16 v[42:45], v[134:137], v[174:177], v[42:45]
	v_mfma_f32_16x16x32_bf16 v[30:33], v[118:121], v[182:185], v[30:33]
	v_mfma_f32_16x16x32_bf16 v[26:29], v[134:137], v[182:185], v[26:29]
	v_mfma_f32_16x16x32_bf16 v[14:17], v[118:121], v[210:213], v[14:17]
	v_mfma_f32_16x16x32_bf16 v[10:13], v[134:137], v[210:213], v[10:13]
	v_mfma_f32_16x16x32_bf16 v[54:57], v[138:141], v[162:165], v[54:57]
	v_mfma_f32_16x16x32_bf16 v[50:53], v[146:149], v[162:165], v[50:53]
	v_mfma_f32_16x16x32_bf16 v[38:41], v[138:141], v[170:173], v[38:41]
	v_mfma_f32_16x16x32_bf16 v[34:37], v[146:149], v[170:173], v[34:37]
	v_mfma_f32_16x16x32_bf16 v[22:25], v[138:141], v[178:181], v[22:25]
	v_mfma_f32_16x16x32_bf16 v[18:21], v[146:149], v[178:181], v[18:21]
	v_mfma_f32_16x16x32_bf16 v[6:9], v[138:141], v[186:189], v[6:9]
	v_mfma_f32_16x16x32_bf16 v[2:5], v[146:149], v[186:189], v[2:5]
	v_mfma_f32_16x16x32_bf16 v[54:57], v[142:145], v[166:169], v[54:57]
	v_mfma_f32_16x16x32_bf16 v[50:53], v[154:157], v[166:169], v[50:53]
	v_mfma_f32_16x16x32_bf16 v[38:41], v[142:145], v[174:177], v[38:41]
	v_mfma_f32_16x16x32_bf16 v[34:37], v[154:157], v[174:177], v[34:37]
	v_mfma_f32_16x16x32_bf16 v[22:25], v[142:145], v[182:185], v[22:25]
	v_mfma_f32_16x16x32_bf16 v[18:21], v[154:157], v[182:185], v[18:21]
	v_mfma_f32_16x16x32_bf16 v[6:9], v[142:145], v[210:213], v[6:9]
	v_mfma_f32_16x16x32_bf16 v[2:5], v[154:157], v[210:213], v[2:5]
	s_setprio 0
	s_barrier
	s_add_i32 s59, 0, 0x18000
	s_add_i32 s60, 0, 0x1c000
	v_add_u32_e32 v134, s59, v1
	v_add_u32_e32 v154, s60, v1
	ds_read_b128 v[110:113], v134
	ds_read_b128 v[118:121], v134 offset:1024
	ds_read_b128 v[122:125], v134 offset:2048
	ds_read_b128 v[134:137], v134 offset:3072
	ds_read_b128 v[138:141], v154
	ds_read_b128 v[142:145], v154 offset:1024
	ds_read_b128 v[146:149], v154 offset:2048
	ds_read_b128 v[154:157], v154 offset:3072
	s_add_u32 s24, s30, 0xb0000
	s_addc_u32 s25, s31, 0
	s_mov_b32 m0, s43
	v_lshl_add_u64 v[234:235], s[24:25], 0, v[190:191]
	ds_read_b128 v[162:165], v214 offset:32768
	ds_read_b128 v[166:169], v214 offset:33792
	ds_read_b128 v[170:173], v214 offset:34816
	ds_read_b128 v[174:177], v214 offset:35840
	ds_read_b128 v[178:181], v214 offset:36864
	ds_read_b128 v[182:185], v214 offset:37888
	ds_read_b128 v[186:189], v214 offset:38912
	ds_read_b128 v[210:213], v214 offset:39936
	global_load_lds_dwordx4 v[234:235], off
	v_lshl_add_u64 v[234:235], s[24:25], 0, v[194:195]
	s_mov_b32 m0, s44
	s_nop 0
	global_load_lds_dwordx4 v[234:235], off
	s_waitcnt vmcnt(8)
	s_waitcnt lgkmcnt(0)
	s_barrier
	s_setprio 1
	v_mfma_f32_16x16x32_bf16 v[158:161], v[110:113], v[162:165], v[158:161]
	v_mfma_f32_16x16x32_bf16 v[150:153], v[122:125], v[162:165], v[150:153]
	v_mfma_f32_16x16x32_bf16 v[114:117], v[110:113], v[170:173], v[114:117]
	v_mfma_f32_16x16x32_bf16 v[106:109], v[122:125], v[170:173], v[106:109]
	v_mfma_f32_16x16x32_bf16 v[94:97], v[110:113], v[178:181], v[94:97]
	v_mfma_f32_16x16x32_bf16 v[90:93], v[122:125], v[178:181], v[90:93]
	v_mfma_f32_16x16x32_bf16 v[78:81], v[110:113], v[186:189], v[78:81]
	v_mfma_f32_16x16x32_bf16 v[74:77], v[122:125], v[186:189], v[74:77]
	v_mfma_f32_16x16x32_bf16 v[158:161], v[118:121], v[166:169], v[158:161]
	v_mfma_f32_16x16x32_bf16 v[150:153], v[134:137], v[166:169], v[150:153]
	v_mfma_f32_16x16x32_bf16 v[114:117], v[118:121], v[174:177], v[114:117]
	v_mfma_f32_16x16x32_bf16 v[106:109], v[134:137], v[174:177], v[106:109]
	v_mfma_f32_16x16x32_bf16 v[94:97], v[118:121], v[182:185], v[94:97]
	v_mfma_f32_16x16x32_bf16 v[90:93], v[134:137], v[182:185], v[90:93]
	v_mfma_f32_16x16x32_bf16 v[78:81], v[118:121], v[210:213], v[78:81]
	v_mfma_f32_16x16x32_bf16 v[74:77], v[134:137], v[210:213], v[74:77]
	v_mfma_f32_16x16x32_bf16 v[130:133], v[138:141], v[162:165], v[130:133]
	v_mfma_f32_16x16x32_bf16 v[126:129], v[146:149], v[162:165], v[126:129]
	v_mfma_f32_16x16x32_bf16 v[102:105], v[138:141], v[170:173], v[102:105]
	v_mfma_f32_16x16x32_bf16 v[98:101], v[146:149], v[170:173], v[98:101]
	v_mfma_f32_16x16x32_bf16 v[86:89], v[138:141], v[178:181], v[86:89]
	v_mfma_f32_16x16x32_bf16 v[82:85], v[146:149], v[178:181], v[82:85]
	v_mfma_f32_16x16x32_bf16 v[70:73], v[138:141], v[186:189], v[70:73]
	v_mfma_f32_16x16x32_bf16 v[66:69], v[146:149], v[186:189], v[66:69]
	v_mfma_f32_16x16x32_bf16 v[130:133], v[142:145], v[166:169], v[130:133]
	v_mfma_f32_16x16x32_bf16 v[126:129], v[154:157], v[166:169], v[126:129]
	v_mfma_f32_16x16x32_bf16 v[102:105], v[142:145], v[174:177], v[102:105]
	v_mfma_f32_16x16x32_bf16 v[98:101], v[154:157], v[174:177], v[98:101]
	v_mfma_f32_16x16x32_bf16 v[86:89], v[142:145], v[182:185], v[86:89]
	v_mfma_f32_16x16x32_bf16 v[82:85], v[154:157], v[182:185], v[82:85]
	v_mfma_f32_16x16x32_bf16 v[70:73], v[142:145], v[210:213], v[70:73]
	v_mfma_f32_16x16x32_bf16 v[66:69], v[154:157], v[210:213], v[66:69]
	s_setprio 0
	s_barrier
	s_add_i32 s24, s59, s40
	v_lshl_add_u64 v[216:217], v[216:217], 0, s[94:95]
	s_mov_b32 m0, s24
	ds_read_b128 v[162:165], v214 offset:49152
	ds_read_b128 v[166:169], v214 offset:50176
	ds_read_b128 v[170:173], v214 offset:51200
	ds_read_b128 v[174:177], v214 offset:52224
	ds_read_b128 v[178:181], v214 offset:53248
	ds_read_b128 v[182:185], v214 offset:54272
	ds_read_b128 v[186:189], v214 offset:55296
	ds_read_b128 v[210:213], v214 offset:56320
	global_load_lds_dwordx4 v[216:217], off
	s_add_i32 m0, s24, 0x2000
	s_add_u32 s24, s28, 0xb0080
	v_lshl_add_u64 v[216:217], v[228:229], 0, s[94:95]
	s_addc_u32 s25, s29, 0
	s_add_i32 s28, s60, s40
	global_load_lds_dwordx4 v[216:217], off
	v_lshl_add_u64 v[216:217], s[24:25], 0, v[192:193]
	s_mov_b32 m0, s28
	s_nop 0
	global_load_lds_dwordx4 v[216:217], off
	v_lshl_add_u64 v[216:217], s[24:25], 0, v[204:205]
	s_add_i32 m0, s28, 0x2000
	s_nop 0
	global_load_lds_dwordx4 v[216:217], off
	v_lshl_add_u64 v[216:217], v[230:231], 0, s[94:95]
	s_mov_b32 m0, s47
	s_nop 0
	global_load_lds_dwordx4 v[216:217], off
	v_lshl_add_u64 v[216:217], v[232:233], 0, s[94:95]
	s_mov_b32 m0, s48
	s_nop 0
	global_load_lds_dwordx4 v[216:217], off
	s_waitcnt vmcnt(8)
	s_waitcnt lgkmcnt(0)
	s_barrier
	s_setprio 1
	v_mfma_f32_16x16x32_bf16 v[62:65], v[110:113], v[162:165], v[62:65]
	v_mfma_f32_16x16x32_bf16 v[58:61], v[122:125], v[162:165], v[58:61]
	v_mfma_f32_16x16x32_bf16 v[46:49], v[110:113], v[170:173], v[46:49]
	v_mfma_f32_16x16x32_bf16 v[42:45], v[122:125], v[170:173], v[42:45]
	v_mfma_f32_16x16x32_bf16 v[30:33], v[110:113], v[178:181], v[30:33]
	v_mfma_f32_16x16x32_bf16 v[26:29], v[122:125], v[178:181], v[26:29]
	v_mfma_f32_16x16x32_bf16 v[14:17], v[110:113], v[186:189], v[14:17]
	v_mfma_f32_16x16x32_bf16 v[10:13], v[122:125], v[186:189], v[10:13]
	v_mfma_f32_16x16x32_bf16 v[62:65], v[118:121], v[166:169], v[62:65]
	v_mfma_f32_16x16x32_bf16 v[58:61], v[134:137], v[166:169], v[58:61]
	v_mfma_f32_16x16x32_bf16 v[46:49], v[118:121], v[174:177], v[46:49]
	v_mfma_f32_16x16x32_bf16 v[42:45], v[134:137], v[174:177], v[42:45]
	v_mfma_f32_16x16x32_bf16 v[30:33], v[118:121], v[182:185], v[30:33]
	v_mfma_f32_16x16x32_bf16 v[26:29], v[134:137], v[182:185], v[26:29]
	v_mfma_f32_16x16x32_bf16 v[14:17], v[118:121], v[210:213], v[14:17]
	v_mfma_f32_16x16x32_bf16 v[10:13], v[134:137], v[210:213], v[10:13]
	v_mfma_f32_16x16x32_bf16 v[54:57], v[138:141], v[162:165], v[54:57]
	v_mfma_f32_16x16x32_bf16 v[50:53], v[146:149], v[162:165], v[50:53]
	v_mfma_f32_16x16x32_bf16 v[38:41], v[138:141], v[170:173], v[38:41]
	v_mfma_f32_16x16x32_bf16 v[34:37], v[146:149], v[170:173], v[34:37]
	v_mfma_f32_16x16x32_bf16 v[22:25], v[138:141], v[178:181], v[22:25]
	v_mfma_f32_16x16x32_bf16 v[18:21], v[146:149], v[178:181], v[18:21]
	v_mfma_f32_16x16x32_bf16 v[6:9], v[138:141], v[186:189], v[6:9]
	v_mfma_f32_16x16x32_bf16 v[2:5], v[146:149], v[186:189], v[2:5]
	v_mfma_f32_16x16x32_bf16 v[54:57], v[142:145], v[166:169], v[54:57]
	v_mfma_f32_16x16x32_bf16 v[50:53], v[154:157], v[166:169], v[50:53]
	v_mfma_f32_16x16x32_bf16 v[38:41], v[142:145], v[174:177], v[38:41]
	v_mfma_f32_16x16x32_bf16 v[34:37], v[154:157], v[174:177], v[34:37]
	v_mfma_f32_16x16x32_bf16 v[22:25], v[142:145], v[182:185], v[22:25]
	v_mfma_f32_16x16x32_bf16 v[18:21], v[154:157], v[182:185], v[18:21]
	v_mfma_f32_16x16x32_bf16 v[6:9], v[142:145], v[210:213], v[6:9]
	v_mfma_f32_16x16x32_bf16 v[2:5], v[154:157], v[210:213], v[2:5]
	s_setprio 0
	s_barrier
	s_add_i32 s58, s58, 2
	s_add_u32 s56, s56, 0x100
	s_addc_u32 s57, s57, 0
	s_cmp_gt_u32 s58, 41
	s_mov_b64 s[24:25], s[26:27]
	s_cbranch_scc0 .LBB0_220
	s_and_b64 vcc, exec, s[20:21]
	s_cbranch_vccz .LBB0_223
	s_barrier

.LBB0_252:
	s_add_i32 s15, s14, 0x100
	s_and_b64 s[12:13], s[12:13], exec
	s_cselect_b32 s13, 0, s15
	s_cselect_b32 s12, 0, 0
	s_add_u32 s16, s4, s13
	s_addc_u32 s17, s5, s12
	s_add_i32 s61, 0, 0x10000
	s_add_u32 s18, s2, s13
	s_addc_u32 s19, s3, s12
	s_add_i32 s13, 0, 0x14000
	s_add_u32 s22, s6, s14
	s_addc_u32 s23, s7, 0
	s_add_i32 s60, s61, s43
	s_add_i32 m0, s44, 0xc000
	s_add_i32 s63, s44, 0xe000
	s_add_i32 s57, s60, 0x2000
	v_add_u32_e32 v139, s61, v1
	s_add_u32 s20, s18, 0x80800
	ds_read_b128 v[140:143], v139
	ds_read_b128 v[144:147], v139 offset:1024
	ds_read_b128 v[148:151], v139 offset:2048
	ds_read_b128 v[152:155], v139 offset:3072
	v_add_u32_e32 v139, s13, v1
	s_addc_u32 s21, s19, 0
	s_add_i32 s59, s13, s43
	ds_read_b128 v[156:159], v139
	ds_read_b128 v[160:163], v139 offset:1024
	ds_read_b128 v[164:167], v139 offset:2048
	ds_read_b128 v[168:171], v139 offset:3072
	s_add_i32 s58, s59, 0x2000
	s_add_i32 s56, 0, 0x18000
	s_add_i32 s55, 0, 0x1c000
	s_add_u32 s14, s16, 0x40000
	s_addc_u32 s15, s17, 0
	s_add_i32 s54, s56, s43
	s_add_i32 s53, s54, 0x2000
	s_add_u32 s12, s18, 0x80880
	s_addc_u32 s13, s19, 0
	s_add_i32 s62, s55, s43
	s_add_i32 s61, s62, 0x2000
	v_lshl_add_u64 v[212:213], s[22:23], 0, v[130:131]
	v_lshl_add_u64 v[212:213], v[212:213], 0, s[94:95]
	ds_read_b128 v[172:175], v138
	ds_read_b128 v[176:179], v138 offset:1024
	ds_read_b128 v[180:183], v138 offset:2048
	ds_read_b128 v[184:187], v138 offset:3072
	ds_read_b128 v[188:191], v138 offset:4096
	ds_read_b128 v[192:195], v138 offset:5120
	ds_read_b128 v[204:207], v138 offset:6144
	ds_read_b128 v[208:211], v138 offset:7168
	global_load_lds_dwordx4 v[212:213], off
	v_lshl_add_u64 v[212:213], s[22:23], 0, v[134:135]
	v_lshl_add_u64 v[212:213], v[212:213], 0, s[94:95]
	s_mov_b32 m0, s63
	s_nop 0
	global_load_lds_dwordx4 v[212:213], off
	s_waitcnt vmcnt(8)
	s_waitcnt lgkmcnt(0)
	s_barrier
	s_setprio 1
	v_mfma_f32_16x16x32_bf16 v[126:129], v[140:143], v[172:175], v[126:129]
	v_mfma_f32_16x16x32_bf16 v[122:125], v[148:151], v[172:175], v[122:125]
	v_mfma_f32_16x16x32_bf16 v[118:121], v[140:143], v[180:183], v[118:121]
	v_mfma_f32_16x16x32_bf16 v[114:117], v[148:151], v[180:183], v[114:117]
	v_mfma_f32_16x16x32_bf16 v[102:105], v[140:143], v[188:191], v[102:105]
	v_mfma_f32_16x16x32_bf16 v[98:101], v[148:151], v[188:191], v[98:101]
	v_mfma_f32_16x16x32_bf16 v[86:89], v[140:143], v[204:207], v[86:89]
	v_mfma_f32_16x16x32_bf16 v[82:85], v[148:151], v[204:207], v[82:85]
	v_mfma_f32_16x16x32_bf16 v[126:129], v[144:147], v[176:179], v[126:129]
	v_mfma_f32_16x16x32_bf16 v[122:125], v[152:155], v[176:179], v[122:125]
	v_mfma_f32_16x16x32_bf16 v[118:121], v[144:147], v[184:187], v[118:121]
	v_mfma_f32_16x16x32_bf16 v[114:117], v[152:155], v[184:187], v[114:117]
	v_mfma_f32_16x16x32_bf16 v[102:105], v[144:147], v[192:195], v[102:105]
	v_mfma_f32_16x16x32_bf16 v[98:101], v[152:155], v[192:195], v[98:101]
	v_mfma_f32_16x16x32_bf16 v[86:89], v[144:147], v[208:211], v[86:89]
	v_mfma_f32_16x16x32_bf16 v[82:85], v[152:155], v[208:211], v[82:85]
	v_mfma_f32_16x16x32_bf16 v[110:113], v[156:159], v[172:175], v[110:113]
	v_mfma_f32_16x16x32_bf16 v[106:109], v[164:167], v[172:175], v[106:109]
	v_mfma_f32_16x16x32_bf16 v[94:97], v[156:159], v[180:183], v[94:97]
	v_mfma_f32_16x16x32_bf16 v[90:93], v[164:167], v[180:183], v[90:93]
	v_mfma_f32_16x16x32_bf16 v[78:81], v[156:159], v[188:191], v[78:81]
	v_mfma_f32_16x16x32_bf16 v[74:77], v[164:167], v[188:191], v[74:77]
	v_mfma_f32_16x16x32_bf16 v[70:73], v[156:159], v[204:207], v[70:73]
	v_mfma_f32_16x16x32_bf16 v[66:69], v[164:167], v[204:207], v[66:69]
	v_mfma_f32_16x16x32_bf16 v[110:113], v[160:163], v[176:179], v[110:113]
	v_mfma_f32_16x16x32_bf16 v[106:109], v[168:171], v[176:179], v[106:109]
	v_mfma_f32_16x16x32_bf16 v[94:97], v[160:163], v[184:187], v[94:97]
	v_mfma_f32_16x16x32_bf16 v[90:93], v[168:171], v[184:187], v[90:93]
	v_mfma_f32_16x16x32_bf16 v[78:81], v[160:163], v[192:195], v[78:81]
	v_mfma_f32_16x16x32_bf16 v[74:77], v[168:171], v[192:195], v[74:77]
	v_mfma_f32_16x16x32_bf16 v[70:73], v[160:163], v[208:211], v[70:73]
	v_mfma_f32_16x16x32_bf16 v[66:69], v[168:171], v[208:211], v[66:69]
	s_setprio 0
	s_barrier
	v_lshl_add_u64 v[212:213], s[18:19], 0, v[132:133]
	s_mov_b32 m0, s60
	v_lshl_add_u64 v[214:215], v[212:213], 0, s[90:91]
	ds_read_b128 v[172:175], v138 offset:16384
	ds_read_b128 v[176:179], v138 offset:17408
	ds_read_b128 v[180:183], v138 offset:18432
	ds_read_b128 v[184:187], v138 offset:19456
	ds_read_b128 v[188:191], v138 offset:20480
	ds_read_b128 v[192:195], v138 offset:21504
	ds_read_b128 v[204:207], v138 offset:22528
	ds_read_b128 v[208:211], v138 offset:23552
	global_load_lds_dwordx4 v[214:215], off
	v_lshl_add_u64 v[214:215], s[18:19], 0, v[136:137]
	v_lshl_add_u64 v[216:217], v[214:215], 0, s[90:91]
	s_mov_b32 m0, s57
	v_lshl_add_u64 v[228:229], s[16:17], 0, v[134:135]
	global_load_lds_dwordx4 v[216:217], off
	v_lshl_add_u64 v[216:217], s[20:21], 0, v[132:133]
	s_mov_b32 m0, s59
	s_nop 0
	global_load_lds_dwordx4 v[216:217], off
	v_lshl_add_u64 v[216:217], s[20:21], 0, v[136:137]
	s_mov_b32 m0, s58
	s_nop 0
	global_load_lds_dwordx4 v[216:217], off
	v_lshl_add_u64 v[216:217], s[16:17], 0, v[130:131]
	s_mov_b32 m0, s44
	s_nop 0
	global_load_lds_dwordx4 v[216:217], off
	s_mov_b32 m0, s45
	s_nop 0
	global_load_lds_dwordx4 v[228:229], off
	s_waitcnt vmcnt(8)
	s_waitcnt lgkmcnt(0)
	s_barrier
	s_setprio 1
	v_mfma_f32_16x16x32_bf16 v[62:65], v[140:143], v[172:175], v[62:65]
	v_mfma_f32_16x16x32_bf16 v[58:61], v[148:151], v[172:175], v[58:61]
	v_mfma_f32_16x16x32_bf16 v[54:57], v[140:143], v[180:183], v[54:57]
	v_mfma_f32_16x16x32_bf16 v[50:53], v[148:151], v[180:183], v[50:53]
	v_mfma_f32_16x16x32_bf16 v[38:41], v[140:143], v[188:191], v[38:41]
	v_mfma_f32_16x16x32_bf16 v[34:37], v[148:151], v[188:191], v[34:37]
	v_mfma_f32_16x16x32_bf16 v[22:25], v[140:143], v[204:207], v[22:25]
	v_mfma_f32_16x16x32_bf16 v[18:21], v[148:151], v[204:207], v[18:21]
	v_mfma_f32_16x16x32_bf16 v[62:65], v[144:147], v[176:179], v[62:65]
	v_mfma_f32_16x16x32_bf16 v[58:61], v[152:155], v[176:179], v[58:61]
	v_mfma_f32_16x16x32_bf16 v[54:57], v[144:147], v[184:187], v[54:57]
	v_mfma_f32_16x16x32_bf16 v[50:53], v[152:155], v[184:187], v[50:53]
	v_mfma_f32_16x16x32_bf16 v[38:41], v[144:147], v[192:195], v[38:41]
	v_mfma_f32_16x16x32_bf16 v[34:37], v[152:155], v[192:195], v[34:37]
	v_mfma_f32_16x16x32_bf16 v[22:25], v[144:147], v[208:211], v[22:25]
	v_mfma_f32_16x16x32_bf16 v[18:21], v[152:155], v[208:211], v[18:21]
	v_mfma_f32_16x16x32_bf16 v[46:49], v[156:159], v[172:175], v[46:49]
	v_mfma_f32_16x16x32_bf16 v[42:45], v[164:167], v[172:175], v[42:45]
	v_mfma_f32_16x16x32_bf16 v[30:33], v[156:159], v[180:183], v[30:33]
	v_mfma_f32_16x16x32_bf16 v[26:29], v[164:167], v[180:183], v[26:29]
	v_mfma_f32_16x16x32_bf16 v[14:17], v[156:159], v[188:191], v[14:17]
	v_mfma_f32_16x16x32_bf16 v[10:13], v[164:167], v[188:191], v[10:13]
	v_mfma_f32_16x16x32_bf16 v[6:9], v[156:159], v[204:207], v[6:9]
	v_mfma_f32_16x16x32_bf16 v[2:5], v[164:167], v[204:207], v[2:5]
	v_mfma_f32_16x16x32_bf16 v[46:49], v[160:163], v[176:179], v[46:49]
	v_mfma_f32_16x16x32_bf16 v[42:45], v[168:171], v[176:179], v[42:45]
	v_mfma_f32_16x16x32_bf16 v[30:33], v[160:163], v[184:187], v[30:33]
	v_mfma_f32_16x16x32_bf16 v[26:29], v[168:171], v[184:187], v[26:29]
	v_mfma_f32_16x16x32_bf16 v[14:17], v[160:163], v[192:195], v[14:17]
	v_mfma_f32_16x16x32_bf16 v[10:13], v[168:171], v[192:195], v[10:13]
	v_mfma_f32_16x16x32_bf16 v[6:9], v[160:163], v[208:211], v[6:9]
	v_mfma_f32_16x16x32_bf16 v[2:5], v[168:171], v[208:211], v[2:5]
	s_setprio 0
	s_barrier
	v_add_u32_e32 v139, s56, v1
	ds_read_b128 v[140:143], v139
	ds_read_b128 v[144:147], v139 offset:1024
	ds_read_b128 v[148:151], v139 offset:2048
	ds_read_b128 v[152:155], v139 offset:3072
	v_add_u32_e32 v139, s55, v1
	ds_read_b128 v[156:159], v139
	ds_read_b128 v[160:163], v139 offset:1024
	ds_read_b128 v[164:167], v139 offset:2048
	ds_read_b128 v[168:171], v139 offset:3072
	s_mov_b32 m0, s46
	v_lshl_add_u64 v[230:231], s[14:15], 0, v[130:131]
	ds_read_b128 v[172:175], v138 offset:32768
	ds_read_b128 v[176:179], v138 offset:33792
	ds_read_b128 v[180:183], v138 offset:34816
	ds_read_b128 v[184:187], v138 offset:35840
	ds_read_b128 v[188:191], v138 offset:36864
	ds_read_b128 v[192:195], v138 offset:37888
	ds_read_b128 v[204:207], v138 offset:38912
	ds_read_b128 v[208:211], v138 offset:39936
	global_load_lds_dwordx4 v[230:231], off
	v_lshl_add_u64 v[230:231], s[14:15], 0, v[134:135]
	s_mov_b32 m0, s47
	s_nop 0
	global_load_lds_dwordx4 v[230:231], off
	s_waitcnt vmcnt(8)
	s_waitcnt lgkmcnt(0)
	s_barrier
	s_setprio 1
	v_mfma_f32_16x16x32_bf16 v[126:129], v[140:143], v[172:175], v[126:129]
	v_mfma_f32_16x16x32_bf16 v[122:125], v[148:151], v[172:175], v[122:125]
	v_mfma_f32_16x16x32_bf16 v[118:121], v[140:143], v[180:183], v[118:121]
	v_mfma_f32_16x16x32_bf16 v[114:117], v[148:151], v[180:183], v[114:117]
	v_mfma_f32_16x16x32_bf16 v[102:105], v[140:143], v[188:191], v[102:105]
	v_mfma_f32_16x16x32_bf16 v[98:101], v[148:151], v[188:191], v[98:101]
	v_mfma_f32_16x16x32_bf16 v[86:89], v[140:143], v[204:207], v[86:89]
	v_mfma_f32_16x16x32_bf16 v[82:85], v[148:151], v[204:207], v[82:85]
	v_mfma_f32_16x16x32_bf16 v[126:129], v[144:147], v[176:179], v[126:129]
	v_mfma_f32_16x16x32_bf16 v[122:125], v[152:155], v[176:179], v[122:125]
	v_mfma_f32_16x16x32_bf16 v[118:121], v[144:147], v[184:187], v[118:121]
	v_mfma_f32_16x16x32_bf16 v[114:117], v[152:155], v[184:187], v[114:117]
	v_mfma_f32_16x16x32_bf16 v[102:105], v[144:147], v[192:195], v[102:105]
	v_mfma_f32_16x16x32_bf16 v[98:101], v[152:155], v[192:195], v[98:101]
	v_mfma_f32_16x16x32_bf16 v[86:89], v[144:147], v[208:211], v[86:89]
	v_mfma_f32_16x16x32_bf16 v[82:85], v[152:155], v[208:211], v[82:85]
	v_mfma_f32_16x16x32_bf16 v[110:113], v[156:159], v[172:175], v[110:113]
	v_mfma_f32_16x16x32_bf16 v[106:109], v[164:167], v[172:175], v[106:109]
	v_mfma_f32_16x16x32_bf16 v[94:97], v[156:159], v[180:183], v[94:97]
	v_mfma_f32_16x16x32_bf16 v[90:93], v[164:167], v[180:183], v[90:93]
	v_mfma_f32_16x16x32_bf16 v[78:81], v[156:159], v[188:191], v[78:81]
	v_mfma_f32_16x16x32_bf16 v[74:77], v[164:167], v[188:191], v[74:77]
	v_mfma_f32_16x16x32_bf16 v[70:73], v[156:159], v[204:207], v[70:73]
	v_mfma_f32_16x16x32_bf16 v[66:69], v[164:167], v[204:207], v[66:69]
	v_mfma_f32_16x16x32_bf16 v[110:113], v[160:163], v[176:179], v[110:113]
	v_mfma_f32_16x16x32_bf16 v[106:109], v[168:171], v[176:179], v[106:109]
	v_mfma_f32_16x16x32_bf16 v[94:97], v[160:163], v[184:187], v[94:97]
	v_mfma_f32_16x16x32_bf16 v[90:93], v[168:171], v[184:187], v[90:93]
	v_mfma_f32_16x16x32_bf16 v[78:81], v[160:163], v[192:195], v[78:81]
	v_mfma_f32_16x16x32_bf16 v[74:77], v[168:171], v[192:195], v[74:77]
	v_mfma_f32_16x16x32_bf16 v[70:73], v[160:163], v[208:211], v[70:73]
	v_mfma_f32_16x16x32_bf16 v[66:69], v[168:171], v[208:211], v[66:69]
	s_setprio 0
	s_barrier
	s_mov_b32 m0, s54
	v_lshl_add_u64 v[212:213], v[212:213], 0, s[64:65]
	ds_read_b128 v[172:175], v138 offset:49152
	ds_read_b128 v[176:179], v138 offset:50176
	ds_read_b128 v[180:183], v138 offset:51200
	ds_read_b128 v[184:187], v138 offset:52224
	ds_read_b128 v[188:191], v138 offset:53248
	ds_read_b128 v[192:195], v138 offset:54272
	ds_read_b128 v[204:207], v138 offset:55296
	ds_read_b128 v[208:211], v138 offset:56320
	global_load_lds_dwordx4 v[212:213], off
	v_lshl_add_u64 v[212:213], v[214:215], 0, s[64:65]
	s_mov_b32 m0, s53
	s_nop 0
	global_load_lds_dwordx4 v[212:213], off
	v_lshl_add_u64 v[212:213], s[12:13], 0, v[132:133]
	s_mov_b32 m0, s62
	s_nop 0
	global_load_lds_dwordx4 v[212:213], off
	v_lshl_add_u64 v[212:213], s[12:13], 0, v[136:137]
	s_mov_b32 m0, s61
	s_nop 0
	global_load_lds_dwordx4 v[212:213], off
	v_lshl_add_u64 v[212:213], v[216:217], 0, s[94:95]
	s_mov_b32 m0, s51
	s_nop 0
	global_load_lds_dwordx4 v[212:213], off
	v_lshl_add_u64 v[212:213], v[228:229], 0, s[94:95]
	s_mov_b32 m0, s52
	s_nop 0
	global_load_lds_dwordx4 v[212:213], off
	s_waitcnt vmcnt(8)
	s_waitcnt lgkmcnt(0)
	s_barrier
	s_setprio 1
	v_mfma_f32_16x16x32_bf16 v[62:65], v[140:143], v[172:175], v[62:65]
	v_mfma_f32_16x16x32_bf16 v[58:61], v[148:151], v[172:175], v[58:61]
	v_mfma_f32_16x16x32_bf16 v[54:57], v[140:143], v[180:183], v[54:57]
	v_mfma_f32_16x16x32_bf16 v[50:53], v[148:151], v[180:183], v[50:53]
	v_mfma_f32_16x16x32_bf16 v[38:41], v[140:143], v[188:191], v[38:41]
	v_mfma_f32_16x16x32_bf16 v[34:37], v[148:151], v[188:191], v[34:37]
	v_mfma_f32_16x16x32_bf16 v[22:25], v[140:143], v[204:207], v[22:25]
	v_mfma_f32_16x16x32_bf16 v[18:21], v[148:151], v[204:207], v[18:21]
	v_mfma_f32_16x16x32_bf16 v[62:65], v[144:147], v[176:179], v[62:65]
	v_mfma_f32_16x16x32_bf16 v[58:61], v[152:155], v[176:179], v[58:61]
	v_mfma_f32_16x16x32_bf16 v[54:57], v[144:147], v[184:187], v[54:57]
	v_mfma_f32_16x16x32_bf16 v[50:53], v[152:155], v[184:187], v[50:53]
	v_mfma_f32_16x16x32_bf16 v[38:41], v[144:147], v[192:195], v[38:41]
	v_mfma_f32_16x16x32_bf16 v[34:37], v[152:155], v[192:195], v[34:37]
	v_mfma_f32_16x16x32_bf16 v[22:25], v[144:147], v[208:211], v[22:25]
	v_mfma_f32_16x16x32_bf16 v[18:21], v[152:155], v[208:211], v[18:21]
	v_mfma_f32_16x16x32_bf16 v[46:49], v[156:159], v[172:175], v[46:49]
	v_mfma_f32_16x16x32_bf16 v[42:45], v[164:167], v[172:175], v[42:45]
	v_mfma_f32_16x16x32_bf16 v[30:33], v[156:159], v[180:183], v[30:33]
	v_mfma_f32_16x16x32_bf16 v[26:29], v[164:167], v[180:183], v[26:29]
	v_mfma_f32_16x16x32_bf16 v[14:17], v[156:159], v[188:191], v[14:17]
	v_mfma_f32_16x16x32_bf16 v[10:13], v[164:167], v[188:191], v[10:13]
	v_mfma_f32_16x16x32_bf16 v[6:9], v[156:159], v[204:207], v[6:9]
	v_mfma_f32_16x16x32_bf16 v[2:5], v[164:167], v[204:207], v[2:5]
	v_mfma_f32_16x16x32_bf16 v[46:49], v[160:163], v[176:179], v[46:49]
	v_mfma_f32_16x16x32_bf16 v[42:45], v[168:171], v[176:179], v[42:45]
	v_mfma_f32_16x16x32_bf16 v[30:33], v[160:163], v[184:187], v[30:33]
	v_mfma_f32_16x16x32_bf16 v[26:29], v[168:171], v[184:187], v[26:29]
	v_mfma_f32_16x16x32_bf16 v[14:17], v[160:163], v[192:195], v[14:17]
	v_mfma_f32_16x16x32_bf16 v[10:13], v[168:171], v[192:195], v[10:13]
	v_mfma_f32_16x16x32_bf16 v[6:9], v[160:163], v[208:211], v[6:9]
	v_mfma_f32_16x16x32_bf16 v[2:5], v[168:171], v[208:211], v[2:5]
	s_setprio 0
	s_barrier
	s_andn2_b64 vcc, exec, s[8:9]
	s_mov_b64 s[12:13], -1
	s_mov_b64 s[8:9], 0
	s_movk_i32 s14, 0x100
	s_cbranch_vccz .LBB0_252
	s_cmpk_lt_u32 s42, 0x100
	s_cbranch_scc0 .LBB0_255
	s_barrier

.LBB0_260:
	s_add_i32 s15, s14, 0x100
	s_and_b64 s[12:13], s[12:13], exec
	s_cselect_b32 s13, 0, s15
	s_cselect_b32 s12, 0, 0
	s_add_u32 s16, s2, s13
	s_addc_u32 s17, s3, s12
	s_add_i32 s56, 0, 0x10000
	s_add_u32 s18, s4, s13
	s_addc_u32 s19, s5, s12
	s_add_i32 s13, 0, 0x14000
	s_add_u32 s22, s6, s14
	s_addc_u32 s23, s7, 0
	s_add_i32 s55, s56, s39
	s_add_i32 m0, s40, 0xc000
	s_add_i32 s58, s40, 0xe000
	s_add_i32 s52, s55, 0x2000
	v_add_u32_e32 v139, s56, v1
	s_add_u32 s20, s18, 0x40000
	ds_read_b128 v[140:143], v139
	ds_read_b128 v[144:147], v139 offset:1024
	ds_read_b128 v[148:151], v139 offset:2048
	ds_read_b128 v[152:155], v139 offset:3072
	v_add_u32_e32 v139, s13, v1
	s_addc_u32 s21, s19, 0
	s_add_i32 s54, s13, s39
	ds_read_b128 v[156:159], v139
	ds_read_b128 v[160:163], v139 offset:1024
	ds_read_b128 v[164:167], v139 offset:2048
	ds_read_b128 v[168:171], v139 offset:3072
	s_add_i32 s53, s54, 0x2000
	s_add_i32 s51, 0, 0x18000
	s_add_i32 s50, 0, 0x1c000
	s_add_u32 s14, s16, 0x80000
	s_addc_u32 s15, s17, 0
	s_add_i32 s49, s51, s39
	s_add_i32 s48, s49, 0x2000
	s_add_u32 s12, s18, 0x40080
	s_addc_u32 s13, s19, 0
	s_add_i32 s57, s50, s39
	s_add_i32 s56, s57, 0x2000
	v_lshl_add_u64 v[212:213], s[22:23], 0, v[130:131]
	v_lshl_add_u64 v[212:213], v[212:213], 0, s[94:95]
	ds_read_b128 v[172:175], v138
	ds_read_b128 v[176:179], v138 offset:1024
	ds_read_b128 v[180:183], v138 offset:2048
	ds_read_b128 v[184:187], v138 offset:3072
	ds_read_b128 v[188:191], v138 offset:4096
	ds_read_b128 v[192:195], v138 offset:5120
	ds_read_b128 v[204:207], v138 offset:6144
	ds_read_b128 v[208:211], v138 offset:7168
	global_load_lds_dwordx4 v[212:213], off
	v_lshl_add_u64 v[212:213], s[22:23], 0, v[134:135]
	v_lshl_add_u64 v[212:213], v[212:213], 0, s[94:95]
	s_mov_b32 m0, s58
	s_nop 0
	global_load_lds_dwordx4 v[212:213], off
	s_waitcnt vmcnt(8)
	s_waitcnt lgkmcnt(0)
	s_barrier
	s_setprio 1
	v_mfma_f32_16x16x32_bf16 v[126:129], v[140:143], v[172:175], v[126:129]
	v_mfma_f32_16x16x32_bf16 v[122:125], v[148:151], v[172:175], v[122:125]
	v_mfma_f32_16x16x32_bf16 v[118:121], v[140:143], v[180:183], v[118:121]
	v_mfma_f32_16x16x32_bf16 v[114:117], v[148:151], v[180:183], v[114:117]
	v_mfma_f32_16x16x32_bf16 v[102:105], v[140:143], v[188:191], v[102:105]
	v_mfma_f32_16x16x32_bf16 v[98:101], v[148:151], v[188:191], v[98:101]
	v_mfma_f32_16x16x32_bf16 v[86:89], v[140:143], v[204:207], v[86:89]
	v_mfma_f32_16x16x32_bf16 v[82:85], v[148:151], v[204:207], v[82:85]
	v_mfma_f32_16x16x32_bf16 v[126:129], v[144:147], v[176:179], v[126:129]
	v_mfma_f32_16x16x32_bf16 v[122:125], v[152:155], v[176:179], v[122:125]
	v_mfma_f32_16x16x32_bf16 v[118:121], v[144:147], v[184:187], v[118:121]
	v_mfma_f32_16x16x32_bf16 v[114:117], v[152:155], v[184:187], v[114:117]
	v_mfma_f32_16x16x32_bf16 v[102:105], v[144:147], v[192:195], v[102:105]
	v_mfma_f32_16x16x32_bf16 v[98:101], v[152:155], v[192:195], v[98:101]
	v_mfma_f32_16x16x32_bf16 v[86:89], v[144:147], v[208:211], v[86:89]
	v_mfma_f32_16x16x32_bf16 v[82:85], v[152:155], v[208:211], v[82:85]
	v_mfma_f32_16x16x32_bf16 v[110:113], v[156:159], v[172:175], v[110:113]
	v_mfma_f32_16x16x32_bf16 v[106:109], v[164:167], v[172:175], v[106:109]
	v_mfma_f32_16x16x32_bf16 v[94:97], v[156:159], v[180:183], v[94:97]
	v_mfma_f32_16x16x32_bf16 v[90:93], v[164:167], v[180:183], v[90:93]
	v_mfma_f32_16x16x32_bf16 v[78:81], v[156:159], v[188:191], v[78:81]
	v_mfma_f32_16x16x32_bf16 v[74:77], v[164:167], v[188:191], v[74:77]
	v_mfma_f32_16x16x32_bf16 v[70:73], v[156:159], v[204:207], v[70:73]
	v_mfma_f32_16x16x32_bf16 v[66:69], v[164:167], v[204:207], v[66:69]
	v_mfma_f32_16x16x32_bf16 v[110:113], v[160:163], v[176:179], v[110:113]
	v_mfma_f32_16x16x32_bf16 v[106:109], v[168:171], v[176:179], v[106:109]
	v_mfma_f32_16x16x32_bf16 v[94:97], v[160:163], v[184:187], v[94:97]
	v_mfma_f32_16x16x32_bf16 v[90:93], v[168:171], v[184:187], v[90:93]
	v_mfma_f32_16x16x32_bf16 v[78:81], v[160:163], v[192:195], v[78:81]
	v_mfma_f32_16x16x32_bf16 v[74:77], v[168:171], v[192:195], v[74:77]
	v_mfma_f32_16x16x32_bf16 v[70:73], v[160:163], v[208:211], v[70:73]
	v_mfma_f32_16x16x32_bf16 v[66:69], v[168:171], v[208:211], v[66:69]
	s_setprio 0
	s_barrier
	s_mov_b32 m0, s55
	v_lshl_add_u64 v[212:213], s[18:19], 0, v[132:133]
	ds_read_b128 v[172:175], v138 offset:16384
	ds_read_b128 v[176:179], v138 offset:17408
	ds_read_b128 v[180:183], v138 offset:18432
	ds_read_b128 v[184:187], v138 offset:19456
	ds_read_b128 v[188:191], v138 offset:20480
	ds_read_b128 v[192:195], v138 offset:21504
	ds_read_b128 v[204:207], v138 offset:22528
	ds_read_b128 v[208:211], v138 offset:23552
	global_load_lds_dwordx4 v[212:213], off
	v_lshl_add_u64 v[214:215], s[18:19], 0, v[136:137]
	s_mov_b32 m0, s52
	v_lshl_add_u64 v[216:217], s[20:21], 0, v[132:133]
	global_load_lds_dwordx4 v[214:215], off
	s_mov_b32 m0, s54
	v_lshl_add_u64 v[228:229], s[16:17], 0, v[134:135]
	global_load_lds_dwordx4 v[216:217], off
	v_lshl_add_u64 v[216:217], s[20:21], 0, v[136:137]
	s_mov_b32 m0, s53
	s_nop 0
	global_load_lds_dwordx4 v[216:217], off
	v_lshl_add_u64 v[216:217], s[16:17], 0, v[130:131]
	s_mov_b32 m0, s40
	s_nop 0
	global_load_lds_dwordx4 v[216:217], off
	s_mov_b32 m0, s41
	s_nop 0
	global_load_lds_dwordx4 v[228:229], off
	s_waitcnt vmcnt(8)
	s_waitcnt lgkmcnt(0)
	s_barrier
	s_setprio 1
	v_mfma_f32_16x16x32_bf16 v[62:65], v[140:143], v[172:175], v[62:65]
	v_mfma_f32_16x16x32_bf16 v[58:61], v[148:151], v[172:175], v[58:61]
	v_mfma_f32_16x16x32_bf16 v[54:57], v[140:143], v[180:183], v[54:57]
	v_mfma_f32_16x16x32_bf16 v[50:53], v[148:151], v[180:183], v[50:53]
	v_mfma_f32_16x16x32_bf16 v[38:41], v[140:143], v[188:191], v[38:41]
	v_mfma_f32_16x16x32_bf16 v[34:37], v[148:151], v[188:191], v[34:37]
	v_mfma_f32_16x16x32_bf16 v[22:25], v[140:143], v[204:207], v[22:25]
	v_mfma_f32_16x16x32_bf16 v[18:21], v[148:151], v[204:207], v[18:21]
	v_mfma_f32_16x16x32_bf16 v[62:65], v[144:147], v[176:179], v[62:65]
	v_mfma_f32_16x16x32_bf16 v[58:61], v[152:155], v[176:179], v[58:61]
	v_mfma_f32_16x16x32_bf16 v[54:57], v[144:147], v[184:187], v[54:57]
	v_mfma_f32_16x16x32_bf16 v[50:53], v[152:155], v[184:187], v[50:53]
	v_mfma_f32_16x16x32_bf16 v[38:41], v[144:147], v[192:195], v[38:41]
	v_mfma_f32_16x16x32_bf16 v[34:37], v[152:155], v[192:195], v[34:37]
	v_mfma_f32_16x16x32_bf16 v[22:25], v[144:147], v[208:211], v[22:25]
	v_mfma_f32_16x16x32_bf16 v[18:21], v[152:155], v[208:211], v[18:21]
	v_mfma_f32_16x16x32_bf16 v[46:49], v[156:159], v[172:175], v[46:49]
	v_mfma_f32_16x16x32_bf16 v[42:45], v[164:167], v[172:175], v[42:45]
	v_mfma_f32_16x16x32_bf16 v[30:33], v[156:159], v[180:183], v[30:33]
	v_mfma_f32_16x16x32_bf16 v[26:29], v[164:167], v[180:183], v[26:29]
	v_mfma_f32_16x16x32_bf16 v[14:17], v[156:159], v[188:191], v[14:17]
	v_mfma_f32_16x16x32_bf16 v[10:13], v[164:167], v[188:191], v[10:13]
	v_mfma_f32_16x16x32_bf16 v[6:9], v[156:159], v[204:207], v[6:9]
	v_mfma_f32_16x16x32_bf16 v[2:5], v[164:167], v[204:207], v[2:5]
	v_mfma_f32_16x16x32_bf16 v[46:49], v[160:163], v[176:179], v[46:49]
	v_mfma_f32_16x16x32_bf16 v[42:45], v[168:171], v[176:179], v[42:45]
	v_mfma_f32_16x16x32_bf16 v[30:33], v[160:163], v[184:187], v[30:33]
	v_mfma_f32_16x16x32_bf16 v[26:29], v[168:171], v[184:187], v[26:29]
	v_mfma_f32_16x16x32_bf16 v[14:17], v[160:163], v[192:195], v[14:17]
	v_mfma_f32_16x16x32_bf16 v[10:13], v[168:171], v[192:195], v[10:13]
	v_mfma_f32_16x16x32_bf16 v[6:9], v[160:163], v[208:211], v[6:9]
	v_mfma_f32_16x16x32_bf16 v[2:5], v[168:171], v[208:211], v[2:5]
	s_setprio 0
	s_barrier
	v_add_u32_e32 v139, s51, v1
	ds_read_b128 v[140:143], v139
	ds_read_b128 v[144:147], v139 offset:1024
	ds_read_b128 v[148:151], v139 offset:2048
	ds_read_b128 v[152:155], v139 offset:3072
	v_add_u32_e32 v139, s50, v1
	ds_read_b128 v[156:159], v139
	ds_read_b128 v[160:163], v139 offset:1024
	ds_read_b128 v[164:167], v139 offset:2048
	ds_read_b128 v[168:171], v139 offset:3072
	s_mov_b32 m0, s42
	v_lshl_add_u64 v[230:231], s[14:15], 0, v[130:131]
	ds_read_b128 v[172:175], v138 offset:32768
	ds_read_b128 v[176:179], v138 offset:33792
	ds_read_b128 v[180:183], v138 offset:34816
	ds_read_b128 v[184:187], v138 offset:35840
	ds_read_b128 v[188:191], v138 offset:36864
	ds_read_b128 v[192:195], v138 offset:37888
	ds_read_b128 v[204:207], v138 offset:38912
	ds_read_b128 v[208:211], v138 offset:39936
	global_load_lds_dwordx4 v[230:231], off
	v_lshl_add_u64 v[230:231], s[14:15], 0, v[134:135]
	s_mov_b32 m0, s43
	s_nop 0
	global_load_lds_dwordx4 v[230:231], off
	s_waitcnt vmcnt(8)
	s_waitcnt lgkmcnt(0)
	s_barrier
	s_setprio 1
	v_mfma_f32_16x16x32_bf16 v[126:129], v[140:143], v[172:175], v[126:129]
	v_mfma_f32_16x16x32_bf16 v[122:125], v[148:151], v[172:175], v[122:125]
	v_mfma_f32_16x16x32_bf16 v[118:121], v[140:143], v[180:183], v[118:121]
	v_mfma_f32_16x16x32_bf16 v[114:117], v[148:151], v[180:183], v[114:117]
	v_mfma_f32_16x16x32_bf16 v[102:105], v[140:143], v[188:191], v[102:105]
	v_mfma_f32_16x16x32_bf16 v[98:101], v[148:151], v[188:191], v[98:101]
	v_mfma_f32_16x16x32_bf16 v[86:89], v[140:143], v[204:207], v[86:89]
	v_mfma_f32_16x16x32_bf16 v[82:85], v[148:151], v[204:207], v[82:85]
	v_mfma_f32_16x16x32_bf16 v[126:129], v[144:147], v[176:179], v[126:129]
	v_mfma_f32_16x16x32_bf16 v[122:125], v[152:155], v[176:179], v[122:125]
	v_mfma_f32_16x16x32_bf16 v[118:121], v[144:147], v[184:187], v[118:121]
	v_mfma_f32_16x16x32_bf16 v[114:117], v[152:155], v[184:187], v[114:117]
	v_mfma_f32_16x16x32_bf16 v[102:105], v[144:147], v[192:195], v[102:105]
	v_mfma_f32_16x16x32_bf16 v[98:101], v[152:155], v[192:195], v[98:101]
	v_mfma_f32_16x16x32_bf16 v[86:89], v[144:147], v[208:211], v[86:89]
	v_mfma_f32_16x16x32_bf16 v[82:85], v[152:155], v[208:211], v[82:85]
	v_mfma_f32_16x16x32_bf16 v[110:113], v[156:159], v[172:175], v[110:113]
	v_mfma_f32_16x16x32_bf16 v[106:109], v[164:167], v[172:175], v[106:109]
	v_mfma_f32_16x16x32_bf16 v[94:97], v[156:159], v[180:183], v[94:97]
	v_mfma_f32_16x16x32_bf16 v[90:93], v[164:167], v[180:183], v[90:93]
	v_mfma_f32_16x16x32_bf16 v[78:81], v[156:159], v[188:191], v[78:81]
	v_mfma_f32_16x16x32_bf16 v[74:77], v[164:167], v[188:191], v[74:77]
	v_mfma_f32_16x16x32_bf16 v[70:73], v[156:159], v[204:207], v[70:73]
	v_mfma_f32_16x16x32_bf16 v[66:69], v[164:167], v[204:207], v[66:69]
	v_mfma_f32_16x16x32_bf16 v[110:113], v[160:163], v[176:179], v[110:113]
	v_mfma_f32_16x16x32_bf16 v[106:109], v[168:171], v[176:179], v[106:109]
	v_mfma_f32_16x16x32_bf16 v[94:97], v[160:163], v[184:187], v[94:97]
	v_mfma_f32_16x16x32_bf16 v[90:93], v[168:171], v[184:187], v[90:93]
	v_mfma_f32_16x16x32_bf16 v[78:81], v[160:163], v[192:195], v[78:81]
	v_mfma_f32_16x16x32_bf16 v[74:77], v[168:171], v[192:195], v[74:77]
	v_mfma_f32_16x16x32_bf16 v[70:73], v[160:163], v[208:211], v[70:73]
	v_mfma_f32_16x16x32_bf16 v[66:69], v[168:171], v[208:211], v[66:69]
	s_setprio 0
	s_barrier
	s_mov_b32 m0, s49
	v_lshl_add_u64 v[212:213], v[212:213], 0, s[94:95]
	ds_read_b128 v[172:175], v138 offset:49152
	ds_read_b128 v[176:179], v138 offset:50176
	ds_read_b128 v[180:183], v138 offset:51200
	ds_read_b128 v[184:187], v138 offset:52224
	ds_read_b128 v[188:191], v138 offset:53248
	ds_read_b128 v[192:195], v138 offset:54272
	ds_read_b128 v[204:207], v138 offset:55296
	ds_read_b128 v[208:211], v138 offset:56320
	global_load_lds_dwordx4 v[212:213], off
	v_lshl_add_u64 v[212:213], v[214:215], 0, s[94:95]
	s_mov_b32 m0, s48
	s_nop 0
	global_load_lds_dwordx4 v[212:213], off
	v_lshl_add_u64 v[212:213], s[12:13], 0, v[132:133]
	s_mov_b32 m0, s57
	s_nop 0
	global_load_lds_dwordx4 v[212:213], off
	v_lshl_add_u64 v[212:213], s[12:13], 0, v[136:137]
	s_mov_b32 m0, s56
	s_nop 0
	global_load_lds_dwordx4 v[212:213], off
	v_lshl_add_u64 v[212:213], v[216:217], 0, s[94:95]
	s_mov_b32 m0, s46
	s_nop 0
	global_load_lds_dwordx4 v[212:213], off
	v_lshl_add_u64 v[212:213], v[228:229], 0, s[94:95]
	s_mov_b32 m0, s47
	s_nop 0
	global_load_lds_dwordx4 v[212:213], off
	s_waitcnt vmcnt(8)
	s_waitcnt lgkmcnt(0)
	s_barrier
	s_setprio 1
	v_mfma_f32_16x16x32_bf16 v[62:65], v[140:143], v[172:175], v[62:65]
	v_mfma_f32_16x16x32_bf16 v[58:61], v[148:151], v[172:175], v[58:61]
	v_mfma_f32_16x16x32_bf16 v[54:57], v[140:143], v[180:183], v[54:57]
	v_mfma_f32_16x16x32_bf16 v[50:53], v[148:151], v[180:183], v[50:53]
	v_mfma_f32_16x16x32_bf16 v[38:41], v[140:143], v[188:191], v[38:41]
	v_mfma_f32_16x16x32_bf16 v[34:37], v[148:151], v[188:191], v[34:37]
	v_mfma_f32_16x16x32_bf16 v[22:25], v[140:143], v[204:207], v[22:25]
	v_mfma_f32_16x16x32_bf16 v[18:21], v[148:151], v[204:207], v[18:21]
	v_mfma_f32_16x16x32_bf16 v[62:65], v[144:147], v[176:179], v[62:65]
	v_mfma_f32_16x16x32_bf16 v[58:61], v[152:155], v[176:179], v[58:61]
	v_mfma_f32_16x16x32_bf16 v[54:57], v[144:147], v[184:187], v[54:57]
	v_mfma_f32_16x16x32_bf16 v[50:53], v[152:155], v[184:187], v[50:53]
	v_mfma_f32_16x16x32_bf16 v[38:41], v[144:147], v[192:195], v[38:41]
	v_mfma_f32_16x16x32_bf16 v[34:37], v[152:155], v[192:195], v[34:37]
	v_mfma_f32_16x16x32_bf16 v[22:25], v[144:147], v[208:211], v[22:25]
	v_mfma_f32_16x16x32_bf16 v[18:21], v[152:155], v[208:211], v[18:21]
	v_mfma_f32_16x16x32_bf16 v[46:49], v[156:159], v[172:175], v[46:49]
	v_mfma_f32_16x16x32_bf16 v[42:45], v[164:167], v[172:175], v[42:45]
	v_mfma_f32_16x16x32_bf16 v[30:33], v[156:159], v[180:183], v[30:33]
	v_mfma_f32_16x16x32_bf16 v[26:29], v[164:167], v[180:183], v[26:29]
	v_mfma_f32_16x16x32_bf16 v[14:17], v[156:159], v[188:191], v[14:17]
	v_mfma_f32_16x16x32_bf16 v[10:13], v[164:167], v[188:191], v[10:13]
	v_mfma_f32_16x16x32_bf16 v[6:9], v[156:159], v[204:207], v[6:9]
	v_mfma_f32_16x16x32_bf16 v[2:5], v[164:167], v[204:207], v[2:5]
	v_mfma_f32_16x16x32_bf16 v[46:49], v[160:163], v[176:179], v[46:49]
	v_mfma_f32_16x16x32_bf16 v[42:45], v[168:171], v[176:179], v[42:45]
	v_mfma_f32_16x16x32_bf16 v[30:33], v[160:163], v[184:187], v[30:33]
	v_mfma_f32_16x16x32_bf16 v[26:29], v[168:171], v[184:187], v[26:29]
	v_mfma_f32_16x16x32_bf16 v[14:17], v[160:163], v[192:195], v[14:17]
	v_mfma_f32_16x16x32_bf16 v[10:13], v[168:171], v[192:195], v[10:13]
	v_mfma_f32_16x16x32_bf16 v[6:9], v[160:163], v[208:211], v[6:9]
	v_mfma_f32_16x16x32_bf16 v[2:5], v[168:171], v[208:211], v[2:5]
	s_setprio 0
	s_barrier
	s_andn2_b64 vcc, exec, s[8:9]
	s_mov_b64 s[12:13], -1
	s_mov_b64 s[8:9], 0
	s_movk_i32 s14, 0x100
	s_cbranch_vccz .LBB0_260
	s_cmpk_lt_u32 s38, 0x100
	s_cbranch_scc0 .LBB0_246
	s_barrier
	s_branch .LBB0_246

.LBB0_326:
	s_add_u32 s30, s28, 0xfffc0080
	s_addc_u32 s31, s29, -1
	s_add_i32 s72, 0, 0x10000
	s_cmp_eq_u32 s71, 12
	s_cselect_b32 s35, s5, s31
	s_cselect_b32 s34, s21, s30
	s_cselect_b32 s31, s19, s70
	s_cselect_b32 s30, s36, s37
	s_add_i32 s74, 0, 0x14000
	v_add_u32_e32 v154, s72, v1
	v_add_u32_e32 v167, s74, v1
	ds_read_b128 v[142:145], v154
	ds_read_b128 v[146:149], v154 offset:1024
	ds_read_b128 v[150:153], v154 offset:2048
	ds_read_b128 v[154:157], v154 offset:3072
	ds_read_b128 v[158:161], v167
	ds_read_b128 v[162:165], v167 offset:1024
	ds_read_b128 v[168:171], v167 offset:2048
	ds_read_b128 v[172:175], v167 offset:3072
	v_lshl_add_u64 v[216:217], s[28:29], 0, v[138:139]
	s_add_i32 m0, s27, 0xc000
	ds_read_b128 v[176:179], v166
	ds_read_b128 v[180:183], v166 offset:1024
	ds_read_b128 v[184:187], v166 offset:2048
	ds_read_b128 v[188:191], v166 offset:3072
	ds_read_b128 v[192:195], v166 offset:4096
	ds_read_b128 v[204:207], v166 offset:5120
	ds_read_b128 v[208:211], v166 offset:6144
	ds_read_b128 v[212:215], v166 offset:7168
	global_load_lds_dwordx4 v[216:217], off
	v_lshl_add_u64 v[216:217], s[28:29], 0, v[140:141]
	s_add_i32 m0, s27, 0xe000
	s_nop 0
	global_load_lds_dwordx4 v[216:217], off
	s_waitcnt vmcnt(8)
	s_waitcnt lgkmcnt(0)
	s_barrier
	s_setprio 1
	v_mfma_f32_16x16x32_bf16 v[126:129], v[142:145], v[176:179], v[126:129]
	v_mfma_f32_16x16x32_bf16 v[122:125], v[150:153], v[176:179], v[122:125]
	v_mfma_f32_16x16x32_bf16 v[110:113], v[142:145], v[184:187], v[110:113]
	v_mfma_f32_16x16x32_bf16 v[106:109], v[150:153], v[184:187], v[106:109]
	v_mfma_f32_16x16x32_bf16 v[94:97], v[142:145], v[192:195], v[94:97]
	v_mfma_f32_16x16x32_bf16 v[90:93], v[150:153], v[192:195], v[90:93]
	v_mfma_f32_16x16x32_bf16 v[78:81], v[142:145], v[208:211], v[78:81]
	v_mfma_f32_16x16x32_bf16 v[74:77], v[150:153], v[208:211], v[74:77]
	v_mfma_f32_16x16x32_bf16 v[126:129], v[146:149], v[180:183], v[126:129]
	v_mfma_f32_16x16x32_bf16 v[122:125], v[154:157], v[180:183], v[122:125]
	v_mfma_f32_16x16x32_bf16 v[110:113], v[146:149], v[188:191], v[110:113]
	v_mfma_f32_16x16x32_bf16 v[106:109], v[154:157], v[188:191], v[106:109]
	v_mfma_f32_16x16x32_bf16 v[94:97], v[146:149], v[204:207], v[94:97]
	v_mfma_f32_16x16x32_bf16 v[90:93], v[154:157], v[204:207], v[90:93]
	v_mfma_f32_16x16x32_bf16 v[78:81], v[146:149], v[212:215], v[78:81]
	v_mfma_f32_16x16x32_bf16 v[74:77], v[154:157], v[212:215], v[74:77]
	v_mfma_f32_16x16x32_bf16 v[118:121], v[158:161], v[176:179], v[118:121]
	v_mfma_f32_16x16x32_bf16 v[114:117], v[168:171], v[176:179], v[114:117]
	v_mfma_f32_16x16x32_bf16 v[102:105], v[158:161], v[184:187], v[102:105]
	v_mfma_f32_16x16x32_bf16 v[98:101], v[168:171], v[184:187], v[98:101]
	v_mfma_f32_16x16x32_bf16 v[86:89], v[158:161], v[192:195], v[86:89]
	v_mfma_f32_16x16x32_bf16 v[82:85], v[168:171], v[192:195], v[82:85]
	v_mfma_f32_16x16x32_bf16 v[70:73], v[158:161], v[208:211], v[70:73]
	v_mfma_f32_16x16x32_bf16 v[66:69], v[168:171], v[208:211], v[66:69]
	v_mfma_f32_16x16x32_bf16 v[118:121], v[162:165], v[180:183], v[118:121]
	v_mfma_f32_16x16x32_bf16 v[114:117], v[172:175], v[180:183], v[114:117]
	v_mfma_f32_16x16x32_bf16 v[102:105], v[162:165], v[188:191], v[102:105]
	v_mfma_f32_16x16x32_bf16 v[98:101], v[172:175], v[188:191], v[98:101]
	v_mfma_f32_16x16x32_bf16 v[86:89], v[162:165], v[204:207], v[86:89]
	v_mfma_f32_16x16x32_bf16 v[82:85], v[172:175], v[204:207], v[82:85]
	v_mfma_f32_16x16x32_bf16 v[70:73], v[162:165], v[212:215], v[70:73]
	v_mfma_f32_16x16x32_bf16 v[66:69], v[172:175], v[212:215], v[66:69]
	s_setprio 0
	s_barrier
	s_add_i32 s72, s72, s44
	v_lshl_add_u64 v[216:217], s[30:31], 0, v[132:133]
	s_mov_b32 m0, s72
	ds_read_b128 v[176:179], v166 offset:16384
	ds_read_b128 v[180:183], v166 offset:17408
	ds_read_b128 v[184:187], v166 offset:18432
	ds_read_b128 v[188:191], v166 offset:19456
	ds_read_b128 v[192:195], v166 offset:20480
	ds_read_b128 v[204:207], v166 offset:21504
	ds_read_b128 v[208:211], v166 offset:22528
	ds_read_b128 v[212:215], v166 offset:23552
	global_load_lds_dwordx4 v[216:217], off
	s_add_i32 m0, s72, 0x2000
	s_add_u32 s72, s30, 0x40000
	v_lshl_add_u64 v[228:229], s[30:31], 0, v[136:137]
	s_addc_u32 s73, s31, 0
	s_add_i32 s74, s74, s44
	global_load_lds_dwordx4 v[228:229], off
	v_lshl_add_u64 v[230:231], s[72:73], 0, v[132:133]
	s_mov_b32 m0, s74
	v_lshl_add_u64 v[232:233], s[34:35], 0, v[134:135]
	global_load_lds_dwordx4 v[230:231], off
	v_lshl_add_u64 v[230:231], s[72:73], 0, v[136:137]
	s_add_i32 m0, s74, 0x2000
	s_nop 0
	global_load_lds_dwordx4 v[230:231], off
	v_lshl_add_u64 v[230:231], s[34:35], 0, v[130:131]
	s_mov_b32 m0, s27
	s_nop 0
	global_load_lds_dwordx4 v[230:231], off
	s_mov_b32 m0, s45
	s_nop 0
	global_load_lds_dwordx4 v[232:233], off
	s_waitcnt vmcnt(8)
	s_waitcnt lgkmcnt(0)
	s_barrier
	s_setprio 1
	v_mfma_f32_16x16x32_bf16 v[62:65], v[142:145], v[176:179], v[62:65]
	v_mfma_f32_16x16x32_bf16 v[58:61], v[150:153], v[176:179], v[58:61]
	v_mfma_f32_16x16x32_bf16 v[46:49], v[142:145], v[184:187], v[46:49]
	v_mfma_f32_16x16x32_bf16 v[42:45], v[150:153], v[184:187], v[42:45]
	v_mfma_f32_16x16x32_bf16 v[30:33], v[142:145], v[192:195], v[30:33]
	v_mfma_f32_16x16x32_bf16 v[26:29], v[150:153], v[192:195], v[26:29]
	v_mfma_f32_16x16x32_bf16 v[14:17], v[142:145], v[208:211], v[14:17]
	v_mfma_f32_16x16x32_bf16 v[10:13], v[150:153], v[208:211], v[10:13]
	v_mfma_f32_16x16x32_bf16 v[62:65], v[146:149], v[180:183], v[62:65]
	v_mfma_f32_16x16x32_bf16 v[58:61], v[154:157], v[180:183], v[58:61]
	v_mfma_f32_16x16x32_bf16 v[46:49], v[146:149], v[188:191], v[46:49]
	v_mfma_f32_16x16x32_bf16 v[42:45], v[154:157], v[188:191], v[42:45]
	v_mfma_f32_16x16x32_bf16 v[30:33], v[146:149], v[204:207], v[30:33]
	v_mfma_f32_16x16x32_bf16 v[26:29], v[154:157], v[204:207], v[26:29]
	v_mfma_f32_16x16x32_bf16 v[14:17], v[146:149], v[212:215], v[14:17]
	v_mfma_f32_16x16x32_bf16 v[10:13], v[154:157], v[212:215], v[10:13]
	v_mfma_f32_16x16x32_bf16 v[54:57], v[158:161], v[176:179], v[54:57]
	v_mfma_f32_16x16x32_bf16 v[50:53], v[168:171], v[176:179], v[50:53]
	v_mfma_f32_16x16x32_bf16 v[38:41], v[158:161], v[184:187], v[38:41]
	v_mfma_f32_16x16x32_bf16 v[34:37], v[168:171], v[184:187], v[34:37]
	v_mfma_f32_16x16x32_bf16 v[22:25], v[158:161], v[192:195], v[22:25]
	v_mfma_f32_16x16x32_bf16 v[18:21], v[168:171], v[192:195], v[18:21]
	v_mfma_f32_16x16x32_bf16 v[6:9], v[158:161], v[208:211], v[6:9]
	v_mfma_f32_16x16x32_bf16 v[2:5], v[168:171], v[208:211], v[2:5]
	v_mfma_f32_16x16x32_bf16 v[54:57], v[162:165], v[180:183], v[54:57]
	v_mfma_f32_16x16x32_bf16 v[50:53], v[172:175], v[180:183], v[50:53]
	v_mfma_f32_16x16x32_bf16 v[38:41], v[162:165], v[188:191], v[38:41]
	v_mfma_f32_16x16x32_bf16 v[34:37], v[172:175], v[188:191], v[34:37]
	v_mfma_f32_16x16x32_bf16 v[22:25], v[162:165], v[204:207], v[22:25]
	v_mfma_f32_16x16x32_bf16 v[18:21], v[172:175], v[204:207], v[18:21]
	v_mfma_f32_16x16x32_bf16 v[6:9], v[162:165], v[212:215], v[6:9]
	v_mfma_f32_16x16x32_bf16 v[2:5], v[172:175], v[212:215], v[2:5]
	s_setprio 0
	s_barrier
	s_add_i32 s72, 0, 0x18000
	s_add_i32 s73, 0, 0x1c000
	v_add_u32_e32 v154, s72, v1
	v_add_u32_e32 v167, s73, v1
	ds_read_b128 v[142:145], v154
	ds_read_b128 v[146:149], v154 offset:1024
	ds_read_b128 v[150:153], v154 offset:2048
	ds_read_b128 v[154:157], v154 offset:3072
	ds_read_b128 v[158:161], v167
	ds_read_b128 v[162:165], v167 offset:1024
	ds_read_b128 v[168:171], v167 offset:2048
	ds_read_b128 v[172:175], v167 offset:3072
	s_add_u32 s34, s34, 0x40000
	s_addc_u32 s35, s35, 0
	s_mov_b32 m0, s46
	v_lshl_add_u64 v[234:235], s[34:35], 0, v[130:131]
	ds_read_b128 v[176:179], v166 offset:32768
	ds_read_b128 v[180:183], v166 offset:33792
	ds_read_b128 v[184:187], v166 offset:34816
	ds_read_b128 v[188:191], v166 offset:35840
	ds_read_b128 v[192:195], v166 offset:36864
	ds_read_b128 v[204:207], v166 offset:37888
	ds_read_b128 v[208:211], v166 offset:38912
	ds_read_b128 v[212:215], v166 offset:39936
	global_load_lds_dwordx4 v[234:235], off
	v_lshl_add_u64 v[234:235], s[34:35], 0, v[134:135]
	s_mov_b32 m0, s47
	s_nop 0
	global_load_lds_dwordx4 v[234:235], off
	s_waitcnt vmcnt(8)
	s_waitcnt lgkmcnt(0)
	s_barrier
	s_setprio 1
	v_mfma_f32_16x16x32_bf16 v[126:129], v[142:145], v[176:179], v[126:129]
	v_mfma_f32_16x16x32_bf16 v[122:125], v[150:153], v[176:179], v[122:125]
	v_mfma_f32_16x16x32_bf16 v[110:113], v[142:145], v[184:187], v[110:113]
	v_mfma_f32_16x16x32_bf16 v[106:109], v[150:153], v[184:187], v[106:109]
	v_mfma_f32_16x16x32_bf16 v[94:97], v[142:145], v[192:195], v[94:97]
	v_mfma_f32_16x16x32_bf16 v[90:93], v[150:153], v[192:195], v[90:93]
	v_mfma_f32_16x16x32_bf16 v[78:81], v[142:145], v[208:211], v[78:81]
	v_mfma_f32_16x16x32_bf16 v[74:77], v[150:153], v[208:211], v[74:77]
	v_mfma_f32_16x16x32_bf16 v[126:129], v[146:149], v[180:183], v[126:129]
	v_mfma_f32_16x16x32_bf16 v[122:125], v[154:157], v[180:183], v[122:125]
	v_mfma_f32_16x16x32_bf16 v[110:113], v[146:149], v[188:191], v[110:113]
	v_mfma_f32_16x16x32_bf16 v[106:109], v[154:157], v[188:191], v[106:109]
	v_mfma_f32_16x16x32_bf16 v[94:97], v[146:149], v[204:207], v[94:97]
	v_mfma_f32_16x16x32_bf16 v[90:93], v[154:157], v[204:207], v[90:93]
	v_mfma_f32_16x16x32_bf16 v[78:81], v[146:149], v[212:215], v[78:81]
	v_mfma_f32_16x16x32_bf16 v[74:77], v[154:157], v[212:215], v[74:77]
	v_mfma_f32_16x16x32_bf16 v[118:121], v[158:161], v[176:179], v[118:121]
	v_mfma_f32_16x16x32_bf16 v[114:117], v[168:171], v[176:179], v[114:117]
	v_mfma_f32_16x16x32_bf16 v[102:105], v[158:161], v[184:187], v[102:105]
	v_mfma_f32_16x16x32_bf16 v[98:101], v[168:171], v[184:187], v[98:101]
	v_mfma_f32_16x16x32_bf16 v[86:89], v[158:161], v[192:195], v[86:89]
	v_mfma_f32_16x16x32_bf16 v[82:85], v[168:171], v[192:195], v[82:85]
	v_mfma_f32_16x16x32_bf16 v[70:73], v[158:161], v[208:211], v[70:73]
	v_mfma_f32_16x16x32_bf16 v[66:69], v[168:171], v[208:211], v[66:69]
	v_mfma_f32_16x16x32_bf16 v[118:121], v[162:165], v[180:183], v[118:121]
	v_mfma_f32_16x16x32_bf16 v[114:117], v[172:175], v[180:183], v[114:117]
	v_mfma_f32_16x16x32_bf16 v[102:105], v[162:165], v[188:191], v[102:105]
	v_mfma_f32_16x16x32_bf16 v[98:101], v[172:175], v[188:191], v[98:101]
	v_mfma_f32_16x16x32_bf16 v[86:89], v[162:165], v[204:207], v[86:89]
	v_mfma_f32_16x16x32_bf16 v[82:85], v[172:175], v[204:207], v[82:85]
	v_mfma_f32_16x16x32_bf16 v[70:73], v[162:165], v[212:215], v[70:73]
	v_mfma_f32_16x16x32_bf16 v[66:69], v[172:175], v[212:215], v[66:69]
	s_setprio 0
	s_barrier
	s_add_i32 s34, s72, s44
	v_lshl_add_u64 v[216:217], v[216:217], 0, s[94:95]
	s_mov_b32 m0, s34
	ds_read_b128 v[176:179], v166 offset:49152
	ds_read_b128 v[180:183], v166 offset:50176
	ds_read_b128 v[184:187], v166 offset:51200
	ds_read_b128 v[188:191], v166 offset:52224
	ds_read_b128 v[192:195], v166 offset:53248
	ds_read_b128 v[204:207], v166 offset:54272
	ds_read_b128 v[208:211], v166 offset:55296
	ds_read_b128 v[212:215], v166 offset:56320
	global_load_lds_dwordx4 v[216:217], off
	s_add_i32 m0, s34, 0x2000
	s_add_u32 s30, s30, 0x40080
	v_lshl_add_u64 v[216:217], v[228:229], 0, s[94:95]
	s_addc_u32 s31, s31, 0
	s_add_i32 s34, s73, s44
	global_load_lds_dwordx4 v[216:217], off
	v_lshl_add_u64 v[216:217], s[30:31], 0, v[132:133]
	s_mov_b32 m0, s34
	s_nop 0
	global_load_lds_dwordx4 v[216:217], off
	v_lshl_add_u64 v[216:217], s[30:31], 0, v[136:137]
	s_add_i32 m0, s34, 0x2000
	s_nop 0
	global_load_lds_dwordx4 v[216:217], off
	v_lshl_add_u64 v[216:217], v[230:231], 0, s[94:95]
	s_mov_b32 m0, s60
	s_nop 0
	global_load_lds_dwordx4 v[216:217], off
	v_lshl_add_u64 v[216:217], v[232:233], 0, s[94:95]
	s_mov_b32 m0, s61
	s_nop 0
	global_load_lds_dwordx4 v[216:217], off
	s_waitcnt vmcnt(8)
	s_waitcnt lgkmcnt(0)
	s_barrier
	s_setprio 1
	v_mfma_f32_16x16x32_bf16 v[62:65], v[142:145], v[176:179], v[62:65]
	v_mfma_f32_16x16x32_bf16 v[58:61], v[150:153], v[176:179], v[58:61]
	v_mfma_f32_16x16x32_bf16 v[46:49], v[142:145], v[184:187], v[46:49]
	v_mfma_f32_16x16x32_bf16 v[42:45], v[150:153], v[184:187], v[42:45]
	v_mfma_f32_16x16x32_bf16 v[30:33], v[142:145], v[192:195], v[30:33]
	v_mfma_f32_16x16x32_bf16 v[26:29], v[150:153], v[192:195], v[26:29]
	v_mfma_f32_16x16x32_bf16 v[14:17], v[142:145], v[208:211], v[14:17]
	v_mfma_f32_16x16x32_bf16 v[10:13], v[150:153], v[208:211], v[10:13]
	v_mfma_f32_16x16x32_bf16 v[62:65], v[146:149], v[180:183], v[62:65]
	v_mfma_f32_16x16x32_bf16 v[58:61], v[154:157], v[180:183], v[58:61]
	v_mfma_f32_16x16x32_bf16 v[46:49], v[146:149], v[188:191], v[46:49]
	v_mfma_f32_16x16x32_bf16 v[42:45], v[154:157], v[188:191], v[42:45]
	v_mfma_f32_16x16x32_bf16 v[30:33], v[146:149], v[204:207], v[30:33]
	v_mfma_f32_16x16x32_bf16 v[26:29], v[154:157], v[204:207], v[26:29]
	v_mfma_f32_16x16x32_bf16 v[14:17], v[146:149], v[212:215], v[14:17]
	v_mfma_f32_16x16x32_bf16 v[10:13], v[154:157], v[212:215], v[10:13]
	v_mfma_f32_16x16x32_bf16 v[54:57], v[158:161], v[176:179], v[54:57]
	v_mfma_f32_16x16x32_bf16 v[50:53], v[168:171], v[176:179], v[50:53]
	v_mfma_f32_16x16x32_bf16 v[38:41], v[158:161], v[184:187], v[38:41]
	v_mfma_f32_16x16x32_bf16 v[34:37], v[168:171], v[184:187], v[34:37]
	v_mfma_f32_16x16x32_bf16 v[22:25], v[158:161], v[192:195], v[22:25]
	v_mfma_f32_16x16x32_bf16 v[18:21], v[168:171], v[192:195], v[18:21]
	v_mfma_f32_16x16x32_bf16 v[6:9], v[158:161], v[208:211], v[6:9]
	v_mfma_f32_16x16x32_bf16 v[2:5], v[168:171], v[208:211], v[2:5]
	v_mfma_f32_16x16x32_bf16 v[54:57], v[162:165], v[180:183], v[54:57]
	v_mfma_f32_16x16x32_bf16 v[50:53], v[172:175], v[180:183], v[50:53]
	v_mfma_f32_16x16x32_bf16 v[38:41], v[162:165], v[188:191], v[38:41]
	v_mfma_f32_16x16x32_bf16 v[34:37], v[172:175], v[188:191], v[34:37]
	v_mfma_f32_16x16x32_bf16 v[22:25], v[162:165], v[204:207], v[22:25]
	v_mfma_f32_16x16x32_bf16 v[18:21], v[172:175], v[204:207], v[18:21]
	v_mfma_f32_16x16x32_bf16 v[6:9], v[162:165], v[212:215], v[6:9]
	v_mfma_f32_16x16x32_bf16 v[2:5], v[172:175], v[212:215], v[2:5]
	s_setprio 0
	s_barrier
	s_add_i32 s71, s71, 2
	s_add_u32 s28, s28, 0x100
	s_addc_u32 s29, s29, 0
	s_add_u32 s37, s37, 0x100
	s_addc_u32 s70, s70, 0
	s_cmp_gt_u32 s71, 13
	s_cbranch_scc0 .LBB0_326
	s_and_b64 vcc, exec, s[14:15]
	s_cbranch_vccz .LBB0_329
	s_barrier

.LBB0_807:
	s_add_u32 s36, s26, s34
	s_addc_u32 s37, s27, s35
	s_add_u32 s36, s36, 0x100
	s_addc_u32 s37, s37, 0
	s_add_u32 s65, s62, s34
	s_addc_u32 s66, s63, s35
	s_add_i32 s67, 0, 0x10000
	s_cmpk_eq_i32 s34, 0x700
	s_cselect_b32 s39, s19, s37
	s_cselect_b32 s38, s25, s36
	s_cselect_b32 s37, s17, s66
	s_cselect_b32 s36, s60, s65
	s_add_i32 s65, 0, 0x14000
	v_add_u32_e32 v142, s67, v1
	v_add_u32_e32 v158, s65, v1
	ds_read_b128 v[130:133], v142
	ds_read_b128 v[134:137], v142 offset:1024
	ds_read_b128 v[138:141], v142 offset:2048
	ds_read_b128 v[142:145], v142 offset:3072
	ds_read_b128 v[146:149], v158
	ds_read_b128 v[150:153], v158 offset:1024
	ds_read_b128 v[154:157], v158 offset:2048
	ds_read_b128 v[158:161], v158 offset:3072
	v_lshl_add_u64 v[196:197], v[206:207], 0, s[34:35]
	s_add_i32 m0, s46, 0xc000
	ds_read_b128 v[162:165], v228
	ds_read_b128 v[166:169], v228 offset:1024
	ds_read_b128 v[170:173], v228 offset:2048
	ds_read_b128 v[174:177], v228 offset:3072
	ds_read_b128 v[178:181], v228 offset:4096
	ds_read_b128 v[182:185], v228 offset:5120
	ds_read_b128 v[210:213], v228 offset:6144
	ds_read_b128 v[214:217], v228 offset:7168
	global_load_lds_dwordx4 v[196:197], off
	v_lshl_add_u64 v[196:197], v[208:209], 0, s[34:35]
	s_add_i32 m0, s46, 0xe000
	s_nop 0
	global_load_lds_dwordx4 v[196:197], off
	s_waitcnt vmcnt(8)
	s_waitcnt lgkmcnt(0)
	s_barrier
	s_setprio 1
	v_mfma_f32_16x16x32_bf16 v[126:129], v[130:133], v[162:165], v[126:129]
	v_mfma_f32_16x16x32_bf16 v[122:125], v[138:141], v[162:165], v[122:125]
	v_mfma_f32_16x16x32_bf16 v[110:113], v[130:133], v[170:173], v[110:113]
	v_mfma_f32_16x16x32_bf16 v[106:109], v[138:141], v[170:173], v[106:109]
	v_mfma_f32_16x16x32_bf16 v[94:97], v[130:133], v[178:181], v[94:97]
	v_mfma_f32_16x16x32_bf16 v[90:93], v[138:141], v[178:181], v[90:93]
	v_mfma_f32_16x16x32_bf16 v[78:81], v[130:133], v[210:213], v[78:81]
	v_mfma_f32_16x16x32_bf16 v[74:77], v[138:141], v[210:213], v[74:77]
	v_mfma_f32_16x16x32_bf16 v[126:129], v[134:137], v[166:169], v[126:129]
	v_mfma_f32_16x16x32_bf16 v[122:125], v[142:145], v[166:169], v[122:125]
	v_mfma_f32_16x16x32_bf16 v[110:113], v[134:137], v[174:177], v[110:113]
	v_mfma_f32_16x16x32_bf16 v[106:109], v[142:145], v[174:177], v[106:109]
	v_mfma_f32_16x16x32_bf16 v[94:97], v[134:137], v[182:185], v[94:97]
	v_mfma_f32_16x16x32_bf16 v[90:93], v[142:145], v[182:185], v[90:93]
	v_mfma_f32_16x16x32_bf16 v[78:81], v[134:137], v[214:217], v[78:81]
	v_mfma_f32_16x16x32_bf16 v[74:77], v[142:145], v[214:217], v[74:77]
	v_mfma_f32_16x16x32_bf16 v[118:121], v[146:149], v[162:165], v[118:121]
	v_mfma_f32_16x16x32_bf16 v[114:117], v[154:157], v[162:165], v[114:117]
	v_mfma_f32_16x16x32_bf16 v[102:105], v[146:149], v[170:173], v[102:105]
	v_mfma_f32_16x16x32_bf16 v[98:101], v[154:157], v[170:173], v[98:101]
	v_mfma_f32_16x16x32_bf16 v[86:89], v[146:149], v[178:181], v[86:89]
	v_mfma_f32_16x16x32_bf16 v[82:85], v[154:157], v[178:181], v[82:85]
	v_mfma_f32_16x16x32_bf16 v[70:73], v[146:149], v[210:213], v[70:73]
	v_mfma_f32_16x16x32_bf16 v[66:69], v[154:157], v[210:213], v[66:69]
	v_mfma_f32_16x16x32_bf16 v[118:121], v[150:153], v[166:169], v[118:121]
	v_mfma_f32_16x16x32_bf16 v[114:117], v[158:161], v[166:169], v[114:117]
	v_mfma_f32_16x16x32_bf16 v[102:105], v[150:153], v[174:177], v[102:105]
	v_mfma_f32_16x16x32_bf16 v[98:101], v[158:161], v[174:177], v[98:101]
	v_mfma_f32_16x16x32_bf16 v[86:89], v[150:153], v[182:185], v[86:89]
	v_mfma_f32_16x16x32_bf16 v[82:85], v[158:161], v[182:185], v[82:85]
	v_mfma_f32_16x16x32_bf16 v[70:73], v[150:153], v[214:217], v[70:73]
	v_mfma_f32_16x16x32_bf16 v[66:69], v[158:161], v[214:217], v[66:69]
	s_setprio 0
	s_barrier
	s_add_i32 s66, s67, s45
	v_lshl_add_u64 v[196:197], s[36:37], 0, v[190:191]
	s_mov_b32 m0, s66
	ds_read_b128 v[162:165], v228 offset:16384
	ds_read_b128 v[166:169], v228 offset:17408
	ds_read_b128 v[170:173], v228 offset:18432
	ds_read_b128 v[174:177], v228 offset:19456
	ds_read_b128 v[178:181], v228 offset:20480
	ds_read_b128 v[182:185], v228 offset:21504
	ds_read_b128 v[210:213], v228 offset:22528
	ds_read_b128 v[214:217], v228 offset:23552
	global_load_lds_dwordx4 v[196:197], off
	s_add_i32 m0, s66, 0x2000
	s_add_u32 s66, s36, 0x40000
	v_lshl_add_u64 v[198:199], s[36:37], 0, v[186:187]
	s_addc_u32 s67, s37, 0
	s_add_i32 s65, s65, s45
	global_load_lds_dwordx4 v[198:199], off
	v_lshl_add_u64 v[220:221], s[66:67], 0, v[190:191]
	s_mov_b32 m0, s65
	v_lshl_add_u64 v[222:223], s[38:39], 0, v[188:189]
	global_load_lds_dwordx4 v[220:221], off
	v_lshl_add_u64 v[220:221], s[66:67], 0, v[186:187]
	s_add_i32 m0, s65, 0x2000
	s_nop 0
	global_load_lds_dwordx4 v[220:221], off
	v_lshl_add_u64 v[220:221], s[38:39], 0, v[192:193]
	s_mov_b32 m0, s46
	s_nop 0
	global_load_lds_dwordx4 v[220:221], off
	s_mov_b32 m0, s47
	s_nop 0
	global_load_lds_dwordx4 v[222:223], off
	s_waitcnt vmcnt(8)
	s_waitcnt lgkmcnt(0)
	s_barrier
	s_setprio 1
	v_mfma_f32_16x16x32_bf16 v[62:65], v[130:133], v[162:165], v[62:65]
	v_mfma_f32_16x16x32_bf16 v[58:61], v[138:141], v[162:165], v[58:61]
	v_mfma_f32_16x16x32_bf16 v[46:49], v[130:133], v[170:173], v[46:49]
	v_mfma_f32_16x16x32_bf16 v[42:45], v[138:141], v[170:173], v[42:45]
	v_mfma_f32_16x16x32_bf16 v[30:33], v[130:133], v[178:181], v[30:33]
	v_mfma_f32_16x16x32_bf16 v[26:29], v[138:141], v[178:181], v[26:29]
	v_mfma_f32_16x16x32_bf16 v[14:17], v[130:133], v[210:213], v[14:17]
	v_mfma_f32_16x16x32_bf16 v[10:13], v[138:141], v[210:213], v[10:13]
	v_mfma_f32_16x16x32_bf16 v[62:65], v[134:137], v[166:169], v[62:65]
	v_mfma_f32_16x16x32_bf16 v[58:61], v[142:145], v[166:169], v[58:61]
	v_mfma_f32_16x16x32_bf16 v[46:49], v[134:137], v[174:177], v[46:49]
	v_mfma_f32_16x16x32_bf16 v[42:45], v[142:145], v[174:177], v[42:45]
	v_mfma_f32_16x16x32_bf16 v[30:33], v[134:137], v[182:185], v[30:33]
	v_mfma_f32_16x16x32_bf16 v[26:29], v[142:145], v[182:185], v[26:29]
	v_mfma_f32_16x16x32_bf16 v[14:17], v[134:137], v[214:217], v[14:17]
	v_mfma_f32_16x16x32_bf16 v[10:13], v[142:145], v[214:217], v[10:13]
	v_mfma_f32_16x16x32_bf16 v[54:57], v[146:149], v[162:165], v[54:57]
	v_mfma_f32_16x16x32_bf16 v[50:53], v[154:157], v[162:165], v[50:53]
	v_mfma_f32_16x16x32_bf16 v[38:41], v[146:149], v[170:173], v[38:41]
	v_mfma_f32_16x16x32_bf16 v[34:37], v[154:157], v[170:173], v[34:37]
	v_mfma_f32_16x16x32_bf16 v[22:25], v[146:149], v[178:181], v[22:25]
	v_mfma_f32_16x16x32_bf16 v[18:21], v[154:157], v[178:181], v[18:21]
	v_mfma_f32_16x16x32_bf16 v[6:9], v[146:149], v[210:213], v[6:9]
	v_mfma_f32_16x16x32_bf16 v[2:5], v[154:157], v[210:213], v[2:5]
	v_mfma_f32_16x16x32_bf16 v[54:57], v[150:153], v[166:169], v[54:57]
	v_mfma_f32_16x16x32_bf16 v[50:53], v[158:161], v[166:169], v[50:53]
	v_mfma_f32_16x16x32_bf16 v[38:41], v[150:153], v[174:177], v[38:41]
	v_mfma_f32_16x16x32_bf16 v[34:37], v[158:161], v[174:177], v[34:37]
	v_mfma_f32_16x16x32_bf16 v[22:25], v[150:153], v[182:185], v[22:25]
	v_mfma_f32_16x16x32_bf16 v[18:21], v[158:161], v[182:185], v[18:21]
	v_mfma_f32_16x16x32_bf16 v[6:9], v[150:153], v[214:217], v[6:9]
	v_mfma_f32_16x16x32_bf16 v[2:5], v[158:161], v[214:217], v[2:5]
	s_setprio 0
	s_barrier
	s_add_i32 s65, 0, 0x18000
	s_add_i32 s66, 0, 0x1c000
	v_add_u32_e32 v142, s65, v1
	v_add_u32_e32 v158, s66, v1
	ds_read_b128 v[130:133], v142
	ds_read_b128 v[134:137], v142 offset:1024
	ds_read_b128 v[138:141], v142 offset:2048
	ds_read_b128 v[142:145], v142 offset:3072
	ds_read_b128 v[146:149], v158
	ds_read_b128 v[150:153], v158 offset:1024
	ds_read_b128 v[154:157], v158 offset:2048
	ds_read_b128 v[158:161], v158 offset:3072
	s_add_u32 s38, s38, 0x40000
	s_addc_u32 s39, s39, 0
	s_mov_b32 m0, s48
	v_lshl_add_u64 v[230:231], s[38:39], 0, v[192:193]
	ds_read_b128 v[162:165], v228 offset:32768
	ds_read_b128 v[166:169], v228 offset:33792
	ds_read_b128 v[170:173], v228 offset:34816
	ds_read_b128 v[174:177], v228 offset:35840
	ds_read_b128 v[178:181], v228 offset:36864
	ds_read_b128 v[182:185], v228 offset:37888
	ds_read_b128 v[210:213], v228 offset:38912
	ds_read_b128 v[214:217], v228 offset:39936
	global_load_lds_dwordx4 v[230:231], off
	v_lshl_add_u64 v[230:231], s[38:39], 0, v[188:189]
	s_mov_b32 m0, s49
	s_nop 0
	global_load_lds_dwordx4 v[230:231], off
	s_waitcnt vmcnt(8)
	s_waitcnt lgkmcnt(0)
	s_barrier
	s_setprio 1
	v_mfma_f32_16x16x32_bf16 v[126:129], v[130:133], v[162:165], v[126:129]
	v_mfma_f32_16x16x32_bf16 v[122:125], v[138:141], v[162:165], v[122:125]
	v_mfma_f32_16x16x32_bf16 v[110:113], v[130:133], v[170:173], v[110:113]
	v_mfma_f32_16x16x32_bf16 v[106:109], v[138:141], v[170:173], v[106:109]
	v_mfma_f32_16x16x32_bf16 v[94:97], v[130:133], v[178:181], v[94:97]
	v_mfma_f32_16x16x32_bf16 v[90:93], v[138:141], v[178:181], v[90:93]
	v_mfma_f32_16x16x32_bf16 v[78:81], v[130:133], v[210:213], v[78:81]
	v_mfma_f32_16x16x32_bf16 v[74:77], v[138:141], v[210:213], v[74:77]
	v_mfma_f32_16x16x32_bf16 v[126:129], v[134:137], v[166:169], v[126:129]
	v_mfma_f32_16x16x32_bf16 v[122:125], v[142:145], v[166:169], v[122:125]
	v_mfma_f32_16x16x32_bf16 v[110:113], v[134:137], v[174:177], v[110:113]
	v_mfma_f32_16x16x32_bf16 v[106:109], v[142:145], v[174:177], v[106:109]
	v_mfma_f32_16x16x32_bf16 v[94:97], v[134:137], v[182:185], v[94:97]
	v_mfma_f32_16x16x32_bf16 v[90:93], v[142:145], v[182:185], v[90:93]
	v_mfma_f32_16x16x32_bf16 v[78:81], v[134:137], v[214:217], v[78:81]
	v_mfma_f32_16x16x32_bf16 v[74:77], v[142:145], v[214:217], v[74:77]
	v_mfma_f32_16x16x32_bf16 v[118:121], v[146:149], v[162:165], v[118:121]
	v_mfma_f32_16x16x32_bf16 v[114:117], v[154:157], v[162:165], v[114:117]
	v_mfma_f32_16x16x32_bf16 v[102:105], v[146:149], v[170:173], v[102:105]
	v_mfma_f32_16x16x32_bf16 v[98:101], v[154:157], v[170:173], v[98:101]
	v_mfma_f32_16x16x32_bf16 v[86:89], v[146:149], v[178:181], v[86:89]
	v_mfma_f32_16x16x32_bf16 v[82:85], v[154:157], v[178:181], v[82:85]
	v_mfma_f32_16x16x32_bf16 v[70:73], v[146:149], v[210:213], v[70:73]
	v_mfma_f32_16x16x32_bf16 v[66:69], v[154:157], v[210:213], v[66:69]
	v_mfma_f32_16x16x32_bf16 v[118:121], v[150:153], v[166:169], v[118:121]
	v_mfma_f32_16x16x32_bf16 v[114:117], v[158:161], v[166:169], v[114:117]
	v_mfma_f32_16x16x32_bf16 v[102:105], v[150:153], v[174:177], v[102:105]
	v_mfma_f32_16x16x32_bf16 v[98:101], v[158:161], v[174:177], v[98:101]
	v_mfma_f32_16x16x32_bf16 v[86:89], v[150:153], v[182:185], v[86:89]
	v_mfma_f32_16x16x32_bf16 v[82:85], v[158:161], v[182:185], v[82:85]
	v_mfma_f32_16x16x32_bf16 v[70:73], v[150:153], v[214:217], v[70:73]
	v_mfma_f32_16x16x32_bf16 v[66:69], v[158:161], v[214:217], v[66:69]
	s_setprio 0
	s_barrier
	s_add_i32 s38, s65, s45
	v_lshl_add_u64 v[196:197], v[196:197], 0, s[94:95]
	s_mov_b32 m0, s38
	ds_read_b128 v[162:165], v228 offset:49152
	ds_read_b128 v[166:169], v228 offset:50176
	ds_read_b128 v[170:173], v228 offset:51200
	ds_read_b128 v[174:177], v228 offset:52224
	ds_read_b128 v[178:181], v228 offset:53248
	ds_read_b128 v[182:185], v228 offset:54272
	ds_read_b128 v[210:213], v228 offset:55296
	ds_read_b128 v[214:217], v228 offset:56320
	global_load_lds_dwordx4 v[196:197], off
	s_add_i32 m0, s38, 0x2000
	s_add_u32 s36, s36, 0x40080
	v_lshl_add_u64 v[196:197], v[198:199], 0, s[94:95]
	s_addc_u32 s37, s37, 0
	s_add_i32 s38, s66, s45
	global_load_lds_dwordx4 v[196:197], off
	v_lshl_add_u64 v[196:197], s[36:37], 0, v[190:191]
	s_mov_b32 m0, s38
	s_nop 0
	global_load_lds_dwordx4 v[196:197], off
	v_lshl_add_u64 v[196:197], s[36:37], 0, v[186:187]
	s_add_i32 m0, s38, 0x2000
	s_nop 0
	global_load_lds_dwordx4 v[196:197], off
	v_lshl_add_u64 v[196:197], v[220:221], 0, s[94:95]
	s_mov_b32 m0, s55
	s_nop 0
	global_load_lds_dwordx4 v[196:197], off
	v_lshl_add_u64 v[196:197], v[222:223], 0, s[94:95]
	s_mov_b32 m0, s56
	s_nop 0
	global_load_lds_dwordx4 v[196:197], off
	s_waitcnt vmcnt(8)
	s_waitcnt lgkmcnt(0)
	s_barrier
	s_setprio 1
	v_mfma_f32_16x16x32_bf16 v[62:65], v[130:133], v[162:165], v[62:65]
	v_mfma_f32_16x16x32_bf16 v[58:61], v[138:141], v[162:165], v[58:61]
	v_mfma_f32_16x16x32_bf16 v[46:49], v[130:133], v[170:173], v[46:49]
	v_mfma_f32_16x16x32_bf16 v[42:45], v[138:141], v[170:173], v[42:45]
	v_mfma_f32_16x16x32_bf16 v[30:33], v[130:133], v[178:181], v[30:33]
	v_mfma_f32_16x16x32_bf16 v[26:29], v[138:141], v[178:181], v[26:29]
	v_mfma_f32_16x16x32_bf16 v[14:17], v[130:133], v[210:213], v[14:17]
	v_mfma_f32_16x16x32_bf16 v[10:13], v[138:141], v[210:213], v[10:13]
	v_mfma_f32_16x16x32_bf16 v[62:65], v[134:137], v[166:169], v[62:65]
	v_mfma_f32_16x16x32_bf16 v[58:61], v[142:145], v[166:169], v[58:61]
	v_mfma_f32_16x16x32_bf16 v[46:49], v[134:137], v[174:177], v[46:49]
	v_mfma_f32_16x16x32_bf16 v[42:45], v[142:145], v[174:177], v[42:45]
	v_mfma_f32_16x16x32_bf16 v[30:33], v[134:137], v[182:185], v[30:33]
	v_mfma_f32_16x16x32_bf16 v[26:29], v[142:145], v[182:185], v[26:29]
	v_mfma_f32_16x16x32_bf16 v[14:17], v[134:137], v[214:217], v[14:17]
	v_mfma_f32_16x16x32_bf16 v[10:13], v[142:145], v[214:217], v[10:13]
	v_mfma_f32_16x16x32_bf16 v[54:57], v[146:149], v[162:165], v[54:57]
	v_mfma_f32_16x16x32_bf16 v[50:53], v[154:157], v[162:165], v[50:53]
	v_mfma_f32_16x16x32_bf16 v[38:41], v[146:149], v[170:173], v[38:41]
	v_mfma_f32_16x16x32_bf16 v[34:37], v[154:157], v[170:173], v[34:37]
	v_mfma_f32_16x16x32_bf16 v[22:25], v[146:149], v[178:181], v[22:25]
	v_mfma_f32_16x16x32_bf16 v[18:21], v[154:157], v[178:181], v[18:21]
	v_mfma_f32_16x16x32_bf16 v[6:9], v[146:149], v[210:213], v[6:9]
	v_mfma_f32_16x16x32_bf16 v[2:5], v[154:157], v[210:213], v[2:5]
	v_mfma_f32_16x16x32_bf16 v[54:57], v[150:153], v[166:169], v[54:57]
	v_mfma_f32_16x16x32_bf16 v[50:53], v[158:161], v[166:169], v[50:53]
	v_mfma_f32_16x16x32_bf16 v[38:41], v[150:153], v[174:177], v[38:41]
	v_mfma_f32_16x16x32_bf16 v[34:37], v[158:161], v[174:177], v[34:37]
	v_mfma_f32_16x16x32_bf16 v[22:25], v[150:153], v[182:185], v[22:25]
	v_mfma_f32_16x16x32_bf16 v[18:21], v[158:161], v[182:185], v[18:21]
	v_mfma_f32_16x16x32_bf16 v[6:9], v[150:153], v[214:217], v[6:9]
	v_mfma_f32_16x16x32_bf16 v[2:5], v[158:161], v[214:217], v[2:5]
	s_setprio 0
	s_barrier
	s_add_i32 s36, s64, 2
	s_add_u32 s34, s34, 0x100
	s_addc_u32 s35, s35, 0
	s_cmp_gt_u32 s64, 13
	s_mov_b32 s64, s36
	s_cbranch_scc1 .LBB0_812

.LBB0_890:
	s_add_u32 s28, s26, 0xfffc0080
	s_addc_u32 s29, s27, -1
	s_add_i32 s55, 0, 0x10000
	s_cmp_eq_u32 s54, 12
	s_cselect_b32 s31, s17, s29
	s_cselect_b32 s30, s23, s28
	s_cselect_b32 s29, s15, s53
	s_cselect_b32 s28, s51, s52
	s_add_i32 s58, 0, 0x14000
	v_add_u32_e32 v134, s55, v1
	v_add_u32_e32 v154, s58, v1
	ds_read_b128 v[110:113], v134
	ds_read_b128 v[118:121], v134 offset:1024
	ds_read_b128 v[122:125], v134 offset:2048
	ds_read_b128 v[134:137], v134 offset:3072
	ds_read_b128 v[138:141], v154
	ds_read_b128 v[142:145], v154 offset:1024
	ds_read_b128 v[146:149], v154 offset:2048
	ds_read_b128 v[154:157], v154 offset:3072
	v_lshl_add_u64 v[196:197], s[26:27], 0, v[206:207]
	s_add_i32 m0, s25, 0xc000
	ds_read_b128 v[162:165], v214
	ds_read_b128 v[166:169], v214 offset:1024
	ds_read_b128 v[170:173], v214 offset:2048
	ds_read_b128 v[174:177], v214 offset:3072
	ds_read_b128 v[178:181], v214 offset:4096
	ds_read_b128 v[182:185], v214 offset:5120
	ds_read_b128 v[186:189], v214 offset:6144
	ds_read_b128 v[210:213], v214 offset:7168
	global_load_lds_dwordx4 v[196:197], off
	v_lshl_add_u64 v[196:197], s[26:27], 0, v[208:209]
	s_add_i32 m0, s25, 0xe000
	s_nop 0
	global_load_lds_dwordx4 v[196:197], off
	s_waitcnt vmcnt(8)
	s_waitcnt lgkmcnt(0)
	s_barrier
	s_setprio 1
	v_mfma_f32_16x16x32_bf16 v[158:161], v[110:113], v[162:165], v[158:161]
	v_mfma_f32_16x16x32_bf16 v[150:153], v[122:125], v[162:165], v[150:153]
	v_mfma_f32_16x16x32_bf16 v[114:117], v[110:113], v[170:173], v[114:117]
	v_mfma_f32_16x16x32_bf16 v[106:109], v[122:125], v[170:173], v[106:109]
	v_mfma_f32_16x16x32_bf16 v[94:97], v[110:113], v[178:181], v[94:97]
	v_mfma_f32_16x16x32_bf16 v[90:93], v[122:125], v[178:181], v[90:93]
	v_mfma_f32_16x16x32_bf16 v[78:81], v[110:113], v[186:189], v[78:81]
	v_mfma_f32_16x16x32_bf16 v[74:77], v[122:125], v[186:189], v[74:77]
	v_mfma_f32_16x16x32_bf16 v[158:161], v[118:121], v[166:169], v[158:161]
	v_mfma_f32_16x16x32_bf16 v[150:153], v[134:137], v[166:169], v[150:153]
	v_mfma_f32_16x16x32_bf16 v[114:117], v[118:121], v[174:177], v[114:117]
	v_mfma_f32_16x16x32_bf16 v[106:109], v[134:137], v[174:177], v[106:109]
	v_mfma_f32_16x16x32_bf16 v[94:97], v[118:121], v[182:185], v[94:97]
	v_mfma_f32_16x16x32_bf16 v[90:93], v[134:137], v[182:185], v[90:93]
	v_mfma_f32_16x16x32_bf16 v[78:81], v[118:121], v[210:213], v[78:81]
	v_mfma_f32_16x16x32_bf16 v[74:77], v[134:137], v[210:213], v[74:77]
	v_mfma_f32_16x16x32_bf16 v[130:133], v[138:141], v[162:165], v[130:133]
	v_mfma_f32_16x16x32_bf16 v[126:129], v[146:149], v[162:165], v[126:129]
	v_mfma_f32_16x16x32_bf16 v[102:105], v[138:141], v[170:173], v[102:105]
	v_mfma_f32_16x16x32_bf16 v[98:101], v[146:149], v[170:173], v[98:101]
	v_mfma_f32_16x16x32_bf16 v[86:89], v[138:141], v[178:181], v[86:89]
	v_mfma_f32_16x16x32_bf16 v[82:85], v[146:149], v[178:181], v[82:85]
	v_mfma_f32_16x16x32_bf16 v[70:73], v[138:141], v[186:189], v[70:73]
	v_mfma_f32_16x16x32_bf16 v[66:69], v[146:149], v[186:189], v[66:69]
	v_mfma_f32_16x16x32_bf16 v[130:133], v[142:145], v[166:169], v[130:133]
	v_mfma_f32_16x16x32_bf16 v[126:129], v[154:157], v[166:169], v[126:129]
	v_mfma_f32_16x16x32_bf16 v[102:105], v[142:145], v[174:177], v[102:105]
	v_mfma_f32_16x16x32_bf16 v[98:101], v[154:157], v[174:177], v[98:101]
	v_mfma_f32_16x16x32_bf16 v[86:89], v[142:145], v[182:185], v[86:89]
	v_mfma_f32_16x16x32_bf16 v[82:85], v[154:157], v[182:185], v[82:85]
	v_mfma_f32_16x16x32_bf16 v[70:73], v[142:145], v[210:213], v[70:73]
	v_mfma_f32_16x16x32_bf16 v[66:69], v[154:157], v[210:213], v[66:69]
	s_setprio 0
	s_barrier
	s_add_i32 s55, s55, s40
	v_lshl_add_u64 v[196:197], s[28:29], 0, v[192:193]
	s_mov_b32 m0, s55
	ds_read_b128 v[162:165], v214 offset:16384
	ds_read_b128 v[166:169], v214 offset:17408
	ds_read_b128 v[170:173], v214 offset:18432
	ds_read_b128 v[174:177], v214 offset:19456
	ds_read_b128 v[178:181], v214 offset:20480
	ds_read_b128 v[182:185], v214 offset:21504
	ds_read_b128 v[186:189], v214 offset:22528
	ds_read_b128 v[210:213], v214 offset:23552
	global_load_lds_dwordx4 v[196:197], off
	s_add_i32 m0, s55, 0x2000
	s_add_u32 s56, s28, 0x40000
	v_lshl_add_u64 v[198:199], s[28:29], 0, v[204:205]
	s_addc_u32 s57, s29, 0
	s_add_i32 s55, s58, s40
	global_load_lds_dwordx4 v[198:199], off
	v_lshl_add_u64 v[216:217], s[56:57], 0, v[192:193]
	s_mov_b32 m0, s55
	v_lshl_add_u64 v[220:221], s[30:31], 0, v[194:195]
	global_load_lds_dwordx4 v[216:217], off
	v_lshl_add_u64 v[216:217], s[56:57], 0, v[204:205]
	s_add_i32 m0, s55, 0x2000
	s_nop 0
	global_load_lds_dwordx4 v[216:217], off
	v_lshl_add_u64 v[216:217], s[30:31], 0, v[190:191]
	s_mov_b32 m0, s25
	s_nop 0
	global_load_lds_dwordx4 v[216:217], off
	s_mov_b32 m0, s41
	s_nop 0
	global_load_lds_dwordx4 v[220:221], off
	s_waitcnt vmcnt(8)
	s_waitcnt lgkmcnt(0)
	s_barrier
	s_setprio 1
	v_mfma_f32_16x16x32_bf16 v[62:65], v[110:113], v[162:165], v[62:65]
	v_mfma_f32_16x16x32_bf16 v[58:61], v[122:125], v[162:165], v[58:61]
	v_mfma_f32_16x16x32_bf16 v[46:49], v[110:113], v[170:173], v[46:49]
	v_mfma_f32_16x16x32_bf16 v[42:45], v[122:125], v[170:173], v[42:45]
	v_mfma_f32_16x16x32_bf16 v[30:33], v[110:113], v[178:181], v[30:33]
	v_mfma_f32_16x16x32_bf16 v[26:29], v[122:125], v[178:181], v[26:29]
	v_mfma_f32_16x16x32_bf16 v[14:17], v[110:113], v[186:189], v[14:17]
	v_mfma_f32_16x16x32_bf16 v[10:13], v[122:125], v[186:189], v[10:13]
	v_mfma_f32_16x16x32_bf16 v[62:65], v[118:121], v[166:169], v[62:65]
	v_mfma_f32_16x16x32_bf16 v[58:61], v[134:137], v[166:169], v[58:61]
	v_mfma_f32_16x16x32_bf16 v[46:49], v[118:121], v[174:177], v[46:49]
	v_mfma_f32_16x16x32_bf16 v[42:45], v[134:137], v[174:177], v[42:45]
	v_mfma_f32_16x16x32_bf16 v[30:33], v[118:121], v[182:185], v[30:33]
	v_mfma_f32_16x16x32_bf16 v[26:29], v[134:137], v[182:185], v[26:29]
	v_mfma_f32_16x16x32_bf16 v[14:17], v[118:121], v[210:213], v[14:17]
	v_mfma_f32_16x16x32_bf16 v[10:13], v[134:137], v[210:213], v[10:13]
	v_mfma_f32_16x16x32_bf16 v[54:57], v[138:141], v[162:165], v[54:57]
	v_mfma_f32_16x16x32_bf16 v[50:53], v[146:149], v[162:165], v[50:53]
	v_mfma_f32_16x16x32_bf16 v[38:41], v[138:141], v[170:173], v[38:41]
	v_mfma_f32_16x16x32_bf16 v[34:37], v[146:149], v[170:173], v[34:37]
	v_mfma_f32_16x16x32_bf16 v[22:25], v[138:141], v[178:181], v[22:25]
	v_mfma_f32_16x16x32_bf16 v[18:21], v[146:149], v[178:181], v[18:21]
	v_mfma_f32_16x16x32_bf16 v[6:9], v[138:141], v[186:189], v[6:9]
	v_mfma_f32_16x16x32_bf16 v[2:5], v[146:149], v[186:189], v[2:5]
	v_mfma_f32_16x16x32_bf16 v[54:57], v[142:145], v[166:169], v[54:57]
	v_mfma_f32_16x16x32_bf16 v[50:53], v[154:157], v[166:169], v[50:53]
	v_mfma_f32_16x16x32_bf16 v[38:41], v[142:145], v[174:177], v[38:41]
	v_mfma_f32_16x16x32_bf16 v[34:37], v[154:157], v[174:177], v[34:37]
	v_mfma_f32_16x16x32_bf16 v[22:25], v[142:145], v[182:185], v[22:25]
	v_mfma_f32_16x16x32_bf16 v[18:21], v[154:157], v[182:185], v[18:21]
	v_mfma_f32_16x16x32_bf16 v[6:9], v[142:145], v[210:213], v[6:9]
	v_mfma_f32_16x16x32_bf16 v[2:5], v[154:157], v[210:213], v[2:5]
	s_setprio 0
	s_barrier
	s_add_i32 s55, 0, 0x18000
	s_add_i32 s56, 0, 0x1c000
	v_add_u32_e32 v134, s55, v1
	v_add_u32_e32 v154, s56, v1
	ds_read_b128 v[110:113], v134
	ds_read_b128 v[118:121], v134 offset:1024
	ds_read_b128 v[122:125], v134 offset:2048
	ds_read_b128 v[134:137], v134 offset:3072
	ds_read_b128 v[138:141], v154
	ds_read_b128 v[142:145], v154 offset:1024
	ds_read_b128 v[146:149], v154 offset:2048
	ds_read_b128 v[154:157], v154 offset:3072
	s_add_u32 s30, s30, 0x40000
	s_addc_u32 s31, s31, 0
	s_mov_b32 m0, s42
	v_lshl_add_u64 v[222:223], s[30:31], 0, v[190:191]
	ds_read_b128 v[162:165], v214 offset:32768
	ds_read_b128 v[166:169], v214 offset:33792
	ds_read_b128 v[170:173], v214 offset:34816
	ds_read_b128 v[174:177], v214 offset:35840
	ds_read_b128 v[178:181], v214 offset:36864
	ds_read_b128 v[182:185], v214 offset:37888
	ds_read_b128 v[186:189], v214 offset:38912
	ds_read_b128 v[210:213], v214 offset:39936
	global_load_lds_dwordx4 v[222:223], off
	v_lshl_add_u64 v[222:223], s[30:31], 0, v[194:195]
	s_mov_b32 m0, s43
	s_nop 0
	global_load_lds_dwordx4 v[222:223], off
	s_waitcnt vmcnt(8)
	s_waitcnt lgkmcnt(0)
	s_barrier
	s_setprio 1
	v_mfma_f32_16x16x32_bf16 v[158:161], v[110:113], v[162:165], v[158:161]
	v_mfma_f32_16x16x32_bf16 v[150:153], v[122:125], v[162:165], v[150:153]
	v_mfma_f32_16x16x32_bf16 v[114:117], v[110:113], v[170:173], v[114:117]
	v_mfma_f32_16x16x32_bf16 v[106:109], v[122:125], v[170:173], v[106:109]
	v_mfma_f32_16x16x32_bf16 v[94:97], v[110:113], v[178:181], v[94:97]
	v_mfma_f32_16x16x32_bf16 v[90:93], v[122:125], v[178:181], v[90:93]
	v_mfma_f32_16x16x32_bf16 v[78:81], v[110:113], v[186:189], v[78:81]
	v_mfma_f32_16x16x32_bf16 v[74:77], v[122:125], v[186:189], v[74:77]
	v_mfma_f32_16x16x32_bf16 v[158:161], v[118:121], v[166:169], v[158:161]
	v_mfma_f32_16x16x32_bf16 v[150:153], v[134:137], v[166:169], v[150:153]
	v_mfma_f32_16x16x32_bf16 v[114:117], v[118:121], v[174:177], v[114:117]
	v_mfma_f32_16x16x32_bf16 v[106:109], v[134:137], v[174:177], v[106:109]
	v_mfma_f32_16x16x32_bf16 v[94:97], v[118:121], v[182:185], v[94:97]
	v_mfma_f32_16x16x32_bf16 v[90:93], v[134:137], v[182:185], v[90:93]
	v_mfma_f32_16x16x32_bf16 v[78:81], v[118:121], v[210:213], v[78:81]
	v_mfma_f32_16x16x32_bf16 v[74:77], v[134:137], v[210:213], v[74:77]
	v_mfma_f32_16x16x32_bf16 v[130:133], v[138:141], v[162:165], v[130:133]
	v_mfma_f32_16x16x32_bf16 v[126:129], v[146:149], v[162:165], v[126:129]
	v_mfma_f32_16x16x32_bf16 v[102:105], v[138:141], v[170:173], v[102:105]
	v_mfma_f32_16x16x32_bf16 v[98:101], v[146:149], v[170:173], v[98:101]
	v_mfma_f32_16x16x32_bf16 v[86:89], v[138:141], v[178:181], v[86:89]
	v_mfma_f32_16x16x32_bf16 v[82:85], v[146:149], v[178:181], v[82:85]
	v_mfma_f32_16x16x32_bf16 v[70:73], v[138:141], v[186:189], v[70:73]
	v_mfma_f32_16x16x32_bf16 v[66:69], v[146:149], v[186:189], v[66:69]
	v_mfma_f32_16x16x32_bf16 v[130:133], v[142:145], v[166:169], v[130:133]
	v_mfma_f32_16x16x32_bf16 v[126:129], v[154:157], v[166:169], v[126:129]
	v_mfma_f32_16x16x32_bf16 v[102:105], v[142:145], v[174:177], v[102:105]
	v_mfma_f32_16x16x32_bf16 v[98:101], v[154:157], v[174:177], v[98:101]
	v_mfma_f32_16x16x32_bf16 v[86:89], v[142:145], v[182:185], v[86:89]
	v_mfma_f32_16x16x32_bf16 v[82:85], v[154:157], v[182:185], v[82:85]
	v_mfma_f32_16x16x32_bf16 v[70:73], v[142:145], v[210:213], v[70:73]
	v_mfma_f32_16x16x32_bf16 v[66:69], v[154:157], v[210:213], v[66:69]
	s_setprio 0
	s_barrier
	s_add_i32 s30, s55, s40
	v_lshl_add_u64 v[196:197], v[196:197], 0, s[94:95]
	s_mov_b32 m0, s30
	ds_read_b128 v[162:165], v214 offset:49152
	ds_read_b128 v[166:169], v214 offset:50176
	ds_read_b128 v[170:173], v214 offset:51200
	ds_read_b128 v[174:177], v214 offset:52224
	ds_read_b128 v[178:181], v214 offset:53248
	ds_read_b128 v[182:185], v214 offset:54272
	ds_read_b128 v[186:189], v214 offset:55296
	ds_read_b128 v[210:213], v214 offset:56320
	global_load_lds_dwordx4 v[196:197], off
	s_add_i32 m0, s30, 0x2000
	s_add_u32 s28, s28, 0x40080
	v_lshl_add_u64 v[196:197], v[198:199], 0, s[94:95]
	s_addc_u32 s29, s29, 0
	s_add_i32 s30, s56, s40
	global_load_lds_dwordx4 v[196:197], off
	v_lshl_add_u64 v[196:197], s[28:29], 0, v[192:193]
	s_mov_b32 m0, s30
	s_nop 0
	global_load_lds_dwordx4 v[196:197], off
	v_lshl_add_u64 v[196:197], s[28:29], 0, v[204:205]
	s_add_i32 m0, s30, 0x2000
	s_nop 0
	global_load_lds_dwordx4 v[196:197], off
	v_lshl_add_u64 v[196:197], v[216:217], 0, s[94:95]
	s_mov_b32 m0, s46
	s_nop 0
	global_load_lds_dwordx4 v[196:197], off
	v_lshl_add_u64 v[196:197], v[220:221], 0, s[94:95]
	s_mov_b32 m0, s47
	s_nop 0
	global_load_lds_dwordx4 v[196:197], off
	s_waitcnt vmcnt(8)
	s_waitcnt lgkmcnt(0)
	s_barrier
	s_setprio 1
	v_mfma_f32_16x16x32_bf16 v[62:65], v[110:113], v[162:165], v[62:65]
	v_mfma_f32_16x16x32_bf16 v[58:61], v[122:125], v[162:165], v[58:61]
	v_mfma_f32_16x16x32_bf16 v[46:49], v[110:113], v[170:173], v[46:49]
	v_mfma_f32_16x16x32_bf16 v[42:45], v[122:125], v[170:173], v[42:45]
	v_mfma_f32_16x16x32_bf16 v[30:33], v[110:113], v[178:181], v[30:33]
	v_mfma_f32_16x16x32_bf16 v[26:29], v[122:125], v[178:181], v[26:29]
	v_mfma_f32_16x16x32_bf16 v[14:17], v[110:113], v[186:189], v[14:17]
	v_mfma_f32_16x16x32_bf16 v[10:13], v[122:125], v[186:189], v[10:13]
	v_mfma_f32_16x16x32_bf16 v[62:65], v[118:121], v[166:169], v[62:65]
	v_mfma_f32_16x16x32_bf16 v[58:61], v[134:137], v[166:169], v[58:61]
	v_mfma_f32_16x16x32_bf16 v[46:49], v[118:121], v[174:177], v[46:49]
	v_mfma_f32_16x16x32_bf16 v[42:45], v[134:137], v[174:177], v[42:45]
	v_mfma_f32_16x16x32_bf16 v[30:33], v[118:121], v[182:185], v[30:33]
	v_mfma_f32_16x16x32_bf16 v[26:29], v[134:137], v[182:185], v[26:29]
	v_mfma_f32_16x16x32_bf16 v[14:17], v[118:121], v[210:213], v[14:17]
	v_mfma_f32_16x16x32_bf16 v[10:13], v[134:137], v[210:213], v[10:13]
	v_mfma_f32_16x16x32_bf16 v[54:57], v[138:141], v[162:165], v[54:57]
	v_mfma_f32_16x16x32_bf16 v[50:53], v[146:149], v[162:165], v[50:53]
	v_mfma_f32_16x16x32_bf16 v[38:41], v[138:141], v[170:173], v[38:41]
	v_mfma_f32_16x16x32_bf16 v[34:37], v[146:149], v[170:173], v[34:37]
	v_mfma_f32_16x16x32_bf16 v[22:25], v[138:141], v[178:181], v[22:25]
	v_mfma_f32_16x16x32_bf16 v[18:21], v[146:149], v[178:181], v[18:21]
	v_mfma_f32_16x16x32_bf16 v[6:9], v[138:141], v[186:189], v[6:9]
	v_mfma_f32_16x16x32_bf16 v[2:5], v[146:149], v[186:189], v[2:5]
	v_mfma_f32_16x16x32_bf16 v[54:57], v[142:145], v[166:169], v[54:57]
	v_mfma_f32_16x16x32_bf16 v[50:53], v[154:157], v[166:169], v[50:53]
	v_mfma_f32_16x16x32_bf16 v[38:41], v[142:145], v[174:177], v[38:41]
	v_mfma_f32_16x16x32_bf16 v[34:37], v[154:157], v[174:177], v[34:37]
	v_mfma_f32_16x16x32_bf16 v[22:25], v[142:145], v[182:185], v[22:25]
	v_mfma_f32_16x16x32_bf16 v[18:21], v[154:157], v[182:185], v[18:21]
	v_mfma_f32_16x16x32_bf16 v[6:9], v[142:145], v[210:213], v[6:9]
	v_mfma_f32_16x16x32_bf16 v[2:5], v[154:157], v[210:213], v[2:5]
	s_setprio 0
	s_barrier
	s_add_i32 s54, s54, 2
	s_add_u32 s26, s26, 0x100
	s_addc_u32 s27, s27, 0
	s_add_u32 s52, s52, 0x100
	s_addc_u32 s53, s53, 0
	s_cmp_gt_u32 s54, 13
	s_cbranch_scc0 .LBB0_890
	s_and_b64 vcc, exec, s[12:13]
	s_cbranch_vccz .LBB0_893
	s_barrier

.LBB0_984:
	s_add_u32 s28, s4, 0xfffc0080
	s_addc_u32 s29, s5, -1
	s_add_i32 s58, 0, 0x10000
	s_cmp_eq_u32 s57, 12
	s_cselect_b32 s31, s19, s29
	s_cselect_b32 s30, s53, s28
	s_cselect_b32 s29, s17, s56
	s_cselect_b32 s28, s54, s55
	s_add_i32 s60, 0, 0x14000
	v_add_u32_e32 v154, s58, v1
	v_add_u32_e32 v170, s60, v1
	ds_read_b128 v[142:145], v154
	ds_read_b128 v[146:149], v154 offset:1024
	ds_read_b128 v[150:153], v154 offset:2048
	ds_read_b128 v[154:157], v154 offset:3072
	ds_read_b128 v[158:161], v170
	ds_read_b128 v[162:165], v170 offset:1024
	ds_read_b128 v[166:169], v170 offset:2048
	ds_read_b128 v[170:173], v170 offset:3072
	v_lshl_add_u64 v[196:197], s[4:5], 0, v[138:139]
	s_add_i32 m0, s25, 0xc000
	ds_read_b128 v[174:177], v190
	ds_read_b128 v[178:181], v190 offset:1024
	ds_read_b128 v[182:185], v190 offset:2048
	ds_read_b128 v[186:189], v190 offset:3072
	ds_read_b128 v[192:195], v190 offset:4096
	ds_read_b128 v[204:207], v190 offset:5120
	ds_read_b128 v[208:211], v190 offset:6144
	ds_read_b128 v[212:215], v190 offset:7168
	global_load_lds_dwordx4 v[196:197], off
	v_lshl_add_u64 v[196:197], s[4:5], 0, v[140:141]
	s_add_i32 m0, s25, 0xe000
	s_nop 0
	global_load_lds_dwordx4 v[196:197], off
	s_waitcnt vmcnt(8)
	s_waitcnt lgkmcnt(0)
	s_barrier
	s_setprio 1
	v_mfma_f32_16x16x32_bf16 v[126:129], v[142:145], v[174:177], v[126:129]
	v_mfma_f32_16x16x32_bf16 v[122:125], v[150:153], v[174:177], v[122:125]
	v_mfma_f32_16x16x32_bf16 v[110:113], v[142:145], v[182:185], v[110:113]
	v_mfma_f32_16x16x32_bf16 v[106:109], v[150:153], v[182:185], v[106:109]
	v_mfma_f32_16x16x32_bf16 v[94:97], v[142:145], v[192:195], v[94:97]
	v_mfma_f32_16x16x32_bf16 v[90:93], v[150:153], v[192:195], v[90:93]
	v_mfma_f32_16x16x32_bf16 v[78:81], v[142:145], v[208:211], v[78:81]
	v_mfma_f32_16x16x32_bf16 v[74:77], v[150:153], v[208:211], v[74:77]
	v_mfma_f32_16x16x32_bf16 v[126:129], v[146:149], v[178:181], v[126:129]
	v_mfma_f32_16x16x32_bf16 v[122:125], v[154:157], v[178:181], v[122:125]
	v_mfma_f32_16x16x32_bf16 v[110:113], v[146:149], v[186:189], v[110:113]
	v_mfma_f32_16x16x32_bf16 v[106:109], v[154:157], v[186:189], v[106:109]
	v_mfma_f32_16x16x32_bf16 v[94:97], v[146:149], v[204:207], v[94:97]
	v_mfma_f32_16x16x32_bf16 v[90:93], v[154:157], v[204:207], v[90:93]
	v_mfma_f32_16x16x32_bf16 v[78:81], v[146:149], v[212:215], v[78:81]
	v_mfma_f32_16x16x32_bf16 v[74:77], v[154:157], v[212:215], v[74:77]
	v_mfma_f32_16x16x32_bf16 v[118:121], v[158:161], v[174:177], v[118:121]
	v_mfma_f32_16x16x32_bf16 v[114:117], v[166:169], v[174:177], v[114:117]
	v_mfma_f32_16x16x32_bf16 v[102:105], v[158:161], v[182:185], v[102:105]
	v_mfma_f32_16x16x32_bf16 v[98:101], v[166:169], v[182:185], v[98:101]
	v_mfma_f32_16x16x32_bf16 v[86:89], v[158:161], v[192:195], v[86:89]
	v_mfma_f32_16x16x32_bf16 v[82:85], v[166:169], v[192:195], v[82:85]
	v_mfma_f32_16x16x32_bf16 v[70:73], v[158:161], v[208:211], v[70:73]
	v_mfma_f32_16x16x32_bf16 v[66:69], v[166:169], v[208:211], v[66:69]
	v_mfma_f32_16x16x32_bf16 v[118:121], v[162:165], v[178:181], v[118:121]
	v_mfma_f32_16x16x32_bf16 v[114:117], v[170:173], v[178:181], v[114:117]
	v_mfma_f32_16x16x32_bf16 v[102:105], v[162:165], v[186:189], v[102:105]
	v_mfma_f32_16x16x32_bf16 v[98:101], v[170:173], v[186:189], v[98:101]
	v_mfma_f32_16x16x32_bf16 v[86:89], v[162:165], v[204:207], v[86:89]
	v_mfma_f32_16x16x32_bf16 v[82:85], v[170:173], v[204:207], v[82:85]
	v_mfma_f32_16x16x32_bf16 v[70:73], v[162:165], v[212:215], v[70:73]
	v_mfma_f32_16x16x32_bf16 v[66:69], v[170:173], v[212:215], v[66:69]
	s_setprio 0
	s_barrier
	s_add_i32 s58, s58, s40
	v_lshl_add_u64 v[196:197], s[28:29], 0, v[132:133]
	s_mov_b32 m0, s58
	ds_read_b128 v[174:177], v190 offset:16384
	ds_read_b128 v[178:181], v190 offset:17408
	ds_read_b128 v[182:185], v190 offset:18432
	ds_read_b128 v[186:189], v190 offset:19456
	ds_read_b128 v[192:195], v190 offset:20480
	ds_read_b128 v[204:207], v190 offset:21504
	ds_read_b128 v[208:211], v190 offset:22528
	ds_read_b128 v[212:215], v190 offset:23552
	global_load_lds_dwordx4 v[196:197], off
	s_add_i32 m0, s58, 0x2000
	s_add_u32 s58, s28, 0x40000
	v_lshl_add_u64 v[198:199], s[28:29], 0, v[136:137]
	s_addc_u32 s59, s29, 0
	s_add_i32 s60, s60, s40
	global_load_lds_dwordx4 v[198:199], off
	v_lshl_add_u64 v[216:217], s[58:59], 0, v[132:133]
	s_mov_b32 m0, s60
	v_lshl_add_u64 v[220:221], s[30:31], 0, v[134:135]
	global_load_lds_dwordx4 v[216:217], off
	v_lshl_add_u64 v[216:217], s[58:59], 0, v[136:137]
	s_add_i32 m0, s60, 0x2000
	s_nop 0
	global_load_lds_dwordx4 v[216:217], off
	v_lshl_add_u64 v[216:217], s[30:31], 0, v[130:131]
	s_mov_b32 m0, s25
	s_nop 0
	global_load_lds_dwordx4 v[216:217], off
	s_mov_b32 m0, s27
	s_nop 0
	global_load_lds_dwordx4 v[220:221], off
	s_waitcnt vmcnt(8)
	s_waitcnt lgkmcnt(0)
	s_barrier
	s_setprio 1
	v_mfma_f32_16x16x32_bf16 v[62:65], v[142:145], v[174:177], v[62:65]
	v_mfma_f32_16x16x32_bf16 v[58:61], v[150:153], v[174:177], v[58:61]
	v_mfma_f32_16x16x32_bf16 v[46:49], v[142:145], v[182:185], v[46:49]
	v_mfma_f32_16x16x32_bf16 v[42:45], v[150:153], v[182:185], v[42:45]
	v_mfma_f32_16x16x32_bf16 v[30:33], v[142:145], v[192:195], v[30:33]
	v_mfma_f32_16x16x32_bf16 v[26:29], v[150:153], v[192:195], v[26:29]
	v_mfma_f32_16x16x32_bf16 v[14:17], v[142:145], v[208:211], v[14:17]
	v_mfma_f32_16x16x32_bf16 v[10:13], v[150:153], v[208:211], v[10:13]
	v_mfma_f32_16x16x32_bf16 v[62:65], v[146:149], v[178:181], v[62:65]
	v_mfma_f32_16x16x32_bf16 v[58:61], v[154:157], v[178:181], v[58:61]
	v_mfma_f32_16x16x32_bf16 v[46:49], v[146:149], v[186:189], v[46:49]
	v_mfma_f32_16x16x32_bf16 v[42:45], v[154:157], v[186:189], v[42:45]
	v_mfma_f32_16x16x32_bf16 v[30:33], v[146:149], v[204:207], v[30:33]
	v_mfma_f32_16x16x32_bf16 v[26:29], v[154:157], v[204:207], v[26:29]
	v_mfma_f32_16x16x32_bf16 v[14:17], v[146:149], v[212:215], v[14:17]
	v_mfma_f32_16x16x32_bf16 v[10:13], v[154:157], v[212:215], v[10:13]
	v_mfma_f32_16x16x32_bf16 v[54:57], v[158:161], v[174:177], v[54:57]
	v_mfma_f32_16x16x32_bf16 v[50:53], v[166:169], v[174:177], v[50:53]
	v_mfma_f32_16x16x32_bf16 v[38:41], v[158:161], v[182:185], v[38:41]
	v_mfma_f32_16x16x32_bf16 v[34:37], v[166:169], v[182:185], v[34:37]
	v_mfma_f32_16x16x32_bf16 v[22:25], v[158:161], v[192:195], v[22:25]
	v_mfma_f32_16x16x32_bf16 v[18:21], v[166:169], v[192:195], v[18:21]
	v_mfma_f32_16x16x32_bf16 v[6:9], v[158:161], v[208:211], v[6:9]
	v_mfma_f32_16x16x32_bf16 v[2:5], v[166:169], v[208:211], v[2:5]
	v_mfma_f32_16x16x32_bf16 v[54:57], v[162:165], v[178:181], v[54:57]
	v_mfma_f32_16x16x32_bf16 v[50:53], v[170:173], v[178:181], v[50:53]
	v_mfma_f32_16x16x32_bf16 v[38:41], v[162:165], v[186:189], v[38:41]
	v_mfma_f32_16x16x32_bf16 v[34:37], v[170:173], v[186:189], v[34:37]
	v_mfma_f32_16x16x32_bf16 v[22:25], v[162:165], v[204:207], v[22:25]
	v_mfma_f32_16x16x32_bf16 v[18:21], v[170:173], v[204:207], v[18:21]
	v_mfma_f32_16x16x32_bf16 v[6:9], v[162:165], v[212:215], v[6:9]
	v_mfma_f32_16x16x32_bf16 v[2:5], v[170:173], v[212:215], v[2:5]
	s_setprio 0
	s_barrier
	s_add_i32 s58, 0, 0x18000
	s_add_i32 s59, 0, 0x1c000
	v_add_u32_e32 v154, s58, v1
	v_add_u32_e32 v170, s59, v1
	ds_read_b128 v[142:145], v154
	ds_read_b128 v[146:149], v154 offset:1024
	ds_read_b128 v[150:153], v154 offset:2048
	ds_read_b128 v[154:157], v154 offset:3072
	ds_read_b128 v[158:161], v170
	ds_read_b128 v[162:165], v170 offset:1024
	ds_read_b128 v[166:169], v170 offset:2048
	ds_read_b128 v[170:173], v170 offset:3072
	s_add_u32 s30, s30, 0x40000
	s_addc_u32 s31, s31, 0
	s_mov_b32 m0, s41
	v_lshl_add_u64 v[222:223], s[30:31], 0, v[130:131]
	ds_read_b128 v[174:177], v190 offset:32768
	ds_read_b128 v[178:181], v190 offset:33792
	ds_read_b128 v[182:185], v190 offset:34816
	ds_read_b128 v[186:189], v190 offset:35840
	ds_read_b128 v[192:195], v190 offset:36864
	ds_read_b128 v[204:207], v190 offset:37888
	ds_read_b128 v[208:211], v190 offset:38912
	ds_read_b128 v[212:215], v190 offset:39936
	global_load_lds_dwordx4 v[222:223], off
	v_lshl_add_u64 v[222:223], s[30:31], 0, v[134:135]
	s_mov_b32 m0, s42
	s_nop 0
	global_load_lds_dwordx4 v[222:223], off
	s_waitcnt vmcnt(8)
	s_waitcnt lgkmcnt(0)
	s_barrier
	s_setprio 1
	v_mfma_f32_16x16x32_bf16 v[126:129], v[142:145], v[174:177], v[126:129]
	v_mfma_f32_16x16x32_bf16 v[122:125], v[150:153], v[174:177], v[122:125]
	v_mfma_f32_16x16x32_bf16 v[110:113], v[142:145], v[182:185], v[110:113]
	v_mfma_f32_16x16x32_bf16 v[106:109], v[150:153], v[182:185], v[106:109]
	v_mfma_f32_16x16x32_bf16 v[94:97], v[142:145], v[192:195], v[94:97]
	v_mfma_f32_16x16x32_bf16 v[90:93], v[150:153], v[192:195], v[90:93]
	v_mfma_f32_16x16x32_bf16 v[78:81], v[142:145], v[208:211], v[78:81]
	v_mfma_f32_16x16x32_bf16 v[74:77], v[150:153], v[208:211], v[74:77]
	v_mfma_f32_16x16x32_bf16 v[126:129], v[146:149], v[178:181], v[126:129]
	v_mfma_f32_16x16x32_bf16 v[122:125], v[154:157], v[178:181], v[122:125]
	v_mfma_f32_16x16x32_bf16 v[110:113], v[146:149], v[186:189], v[110:113]
	v_mfma_f32_16x16x32_bf16 v[106:109], v[154:157], v[186:189], v[106:109]
	v_mfma_f32_16x16x32_bf16 v[94:97], v[146:149], v[204:207], v[94:97]
	v_mfma_f32_16x16x32_bf16 v[90:93], v[154:157], v[204:207], v[90:93]
	v_mfma_f32_16x16x32_bf16 v[78:81], v[146:149], v[212:215], v[78:81]
	v_mfma_f32_16x16x32_bf16 v[74:77], v[154:157], v[212:215], v[74:77]
	v_mfma_f32_16x16x32_bf16 v[118:121], v[158:161], v[174:177], v[118:121]
	v_mfma_f32_16x16x32_bf16 v[114:117], v[166:169], v[174:177], v[114:117]
	v_mfma_f32_16x16x32_bf16 v[102:105], v[158:161], v[182:185], v[102:105]
	v_mfma_f32_16x16x32_bf16 v[98:101], v[166:169], v[182:185], v[98:101]
	v_mfma_f32_16x16x32_bf16 v[86:89], v[158:161], v[192:195], v[86:89]
	v_mfma_f32_16x16x32_bf16 v[82:85], v[166:169], v[192:195], v[82:85]
	v_mfma_f32_16x16x32_bf16 v[70:73], v[158:161], v[208:211], v[70:73]
	v_mfma_f32_16x16x32_bf16 v[66:69], v[166:169], v[208:211], v[66:69]
	v_mfma_f32_16x16x32_bf16 v[118:121], v[162:165], v[178:181], v[118:121]
	v_mfma_f32_16x16x32_bf16 v[114:117], v[170:173], v[178:181], v[114:117]
	v_mfma_f32_16x16x32_bf16 v[102:105], v[162:165], v[186:189], v[102:105]
	v_mfma_f32_16x16x32_bf16 v[98:101], v[170:173], v[186:189], v[98:101]
	v_mfma_f32_16x16x32_bf16 v[86:89], v[162:165], v[204:207], v[86:89]
	v_mfma_f32_16x16x32_bf16 v[82:85], v[170:173], v[204:207], v[82:85]
	v_mfma_f32_16x16x32_bf16 v[70:73], v[162:165], v[212:215], v[70:73]
	v_mfma_f32_16x16x32_bf16 v[66:69], v[170:173], v[212:215], v[66:69]
	s_setprio 0
	s_barrier
	s_add_i32 s30, s58, s40
	v_lshl_add_u64 v[196:197], v[196:197], 0, s[94:95]
	s_mov_b32 m0, s30
	ds_read_b128 v[174:177], v190 offset:49152
	ds_read_b128 v[178:181], v190 offset:50176
	ds_read_b128 v[182:185], v190 offset:51200
	ds_read_b128 v[186:189], v190 offset:52224
	ds_read_b128 v[192:195], v190 offset:53248
	ds_read_b128 v[204:207], v190 offset:54272
	ds_read_b128 v[208:211], v190 offset:55296
	ds_read_b128 v[212:215], v190 offset:56320
	global_load_lds_dwordx4 v[196:197], off
	s_add_i32 m0, s30, 0x2000
	s_add_u32 s28, s28, 0x40080
	v_lshl_add_u64 v[196:197], v[198:199], 0, s[94:95]
	s_addc_u32 s29, s29, 0
	s_add_i32 s30, s59, s40
	global_load_lds_dwordx4 v[196:197], off
	v_lshl_add_u64 v[196:197], s[28:29], 0, v[132:133]
	s_mov_b32 m0, s30
	s_nop 0
	global_load_lds_dwordx4 v[196:197], off
	v_lshl_add_u64 v[196:197], s[28:29], 0, v[136:137]
	s_add_i32 m0, s30, 0x2000
	s_nop 0
	global_load_lds_dwordx4 v[196:197], off
	v_lshl_add_u64 v[196:197], v[216:217], 0, s[94:95]
	s_mov_b32 m0, s45
	s_nop 0
	global_load_lds_dwordx4 v[196:197], off
	v_lshl_add_u64 v[196:197], v[220:221], 0, s[94:95]
	s_mov_b32 m0, s46
	s_nop 0
	global_load_lds_dwordx4 v[196:197], off
	s_waitcnt vmcnt(8)
	s_waitcnt lgkmcnt(0)
	s_barrier
	s_setprio 1
	v_mfma_f32_16x16x32_bf16 v[62:65], v[142:145], v[174:177], v[62:65]
	v_mfma_f32_16x16x32_bf16 v[58:61], v[150:153], v[174:177], v[58:61]
	v_mfma_f32_16x16x32_bf16 v[46:49], v[142:145], v[182:185], v[46:49]
	v_mfma_f32_16x16x32_bf16 v[42:45], v[150:153], v[182:185], v[42:45]
	v_mfma_f32_16x16x32_bf16 v[30:33], v[142:145], v[192:195], v[30:33]
	v_mfma_f32_16x16x32_bf16 v[26:29], v[150:153], v[192:195], v[26:29]
	v_mfma_f32_16x16x32_bf16 v[14:17], v[142:145], v[208:211], v[14:17]
	v_mfma_f32_16x16x32_bf16 v[10:13], v[150:153], v[208:211], v[10:13]
	v_mfma_f32_16x16x32_bf16 v[62:65], v[146:149], v[178:181], v[62:65]
	v_mfma_f32_16x16x32_bf16 v[58:61], v[154:157], v[178:181], v[58:61]
	v_mfma_f32_16x16x32_bf16 v[46:49], v[146:149], v[186:189], v[46:49]
	v_mfma_f32_16x16x32_bf16 v[42:45], v[154:157], v[186:189], v[42:45]
	v_mfma_f32_16x16x32_bf16 v[30:33], v[146:149], v[204:207], v[30:33]
	v_mfma_f32_16x16x32_bf16 v[26:29], v[154:157], v[204:207], v[26:29]
	v_mfma_f32_16x16x32_bf16 v[14:17], v[146:149], v[212:215], v[14:17]
	v_mfma_f32_16x16x32_bf16 v[10:13], v[154:157], v[212:215], v[10:13]
	v_mfma_f32_16x16x32_bf16 v[54:57], v[158:161], v[174:177], v[54:57]
	v_mfma_f32_16x16x32_bf16 v[50:53], v[166:169], v[174:177], v[50:53]
	v_mfma_f32_16x16x32_bf16 v[38:41], v[158:161], v[182:185], v[38:41]
	v_mfma_f32_16x16x32_bf16 v[34:37], v[166:169], v[182:185], v[34:37]
	v_mfma_f32_16x16x32_bf16 v[22:25], v[158:161], v[192:195], v[22:25]
	v_mfma_f32_16x16x32_bf16 v[18:21], v[166:169], v[192:195], v[18:21]
	v_mfma_f32_16x16x32_bf16 v[6:9], v[158:161], v[208:211], v[6:9]
	v_mfma_f32_16x16x32_bf16 v[2:5], v[166:169], v[208:211], v[2:5]
	v_mfma_f32_16x16x32_bf16 v[54:57], v[162:165], v[178:181], v[54:57]
	v_mfma_f32_16x16x32_bf16 v[50:53], v[170:173], v[178:181], v[50:53]
	v_mfma_f32_16x16x32_bf16 v[38:41], v[162:165], v[186:189], v[38:41]
	v_mfma_f32_16x16x32_bf16 v[34:37], v[170:173], v[186:189], v[34:37]
	v_mfma_f32_16x16x32_bf16 v[22:25], v[162:165], v[204:207], v[22:25]
	v_mfma_f32_16x16x32_bf16 v[18:21], v[170:173], v[204:207], v[18:21]
	v_mfma_f32_16x16x32_bf16 v[6:9], v[162:165], v[212:215], v[6:9]
	v_mfma_f32_16x16x32_bf16 v[2:5], v[170:173], v[212:215], v[2:5]
	s_setprio 0
	s_barrier
	s_add_i32 s57, s57, 2
	s_add_u32 s4, s4, 0x100
	s_addc_u32 s5, s5, 0
	s_add_u32 s55, s55, 0x100
	s_addc_u32 s56, s56, 0
	s_cmp_gt_u32 s57, 13
	s_cbranch_scc0 .LBB0_984
	s_and_b64 vcc, exec, s[14:15]
	s_cbranch_vccz .LBB0_987
	s_barrier

.LBB0_1096:
	s_add_u32 s28, s4, 0xfffc0080
	s_addc_u32 s29, s5, -1
	s_add_i32 s53, 0, 0x10000
	s_cmp_eq_u32 s52, 12
	s_cselect_b32 s31, s17, s29
	s_cselect_b32 s30, s19, s28
	s_cselect_b32 s29, s21, s51
	s_cselect_b32 s28, s20, s50
	s_add_i32 s56, 0, 0x14000
	v_add_u32_e32 v134, s53, v1
	v_add_u32_e32 v154, s56, v1
	ds_read_b128 v[110:113], v134
	ds_read_b128 v[118:121], v134 offset:1024
	ds_read_b128 v[122:125], v134 offset:2048
	ds_read_b128 v[134:137], v134 offset:3072
	ds_read_b128 v[138:141], v154
	ds_read_b128 v[142:145], v154 offset:1024
	ds_read_b128 v[146:149], v154 offset:2048
	ds_read_b128 v[154:157], v154 offset:3072
	v_lshl_add_u64 v[196:197], s[4:5], 0, v[206:207]
	s_add_i32 m0, s25, 0xc000
	ds_read_b128 v[162:165], v214
	ds_read_b128 v[166:169], v214 offset:1024
	ds_read_b128 v[170:173], v214 offset:2048
	ds_read_b128 v[174:177], v214 offset:3072
	ds_read_b128 v[178:181], v214 offset:4096
	ds_read_b128 v[182:185], v214 offset:5120
	ds_read_b128 v[186:189], v214 offset:6144
	ds_read_b128 v[210:213], v214 offset:7168
	global_load_lds_dwordx4 v[196:197], off
	v_lshl_add_u64 v[196:197], s[4:5], 0, v[208:209]
	s_add_i32 m0, s25, 0xe000
	s_nop 0
	global_load_lds_dwordx4 v[196:197], off
	s_waitcnt vmcnt(8)
	s_waitcnt lgkmcnt(0)
	s_barrier
	s_setprio 1
	v_mfma_f32_16x16x32_bf16 v[158:161], v[110:113], v[162:165], v[158:161]
	v_mfma_f32_16x16x32_bf16 v[150:153], v[122:125], v[162:165], v[150:153]
	v_mfma_f32_16x16x32_bf16 v[114:117], v[110:113], v[170:173], v[114:117]
	v_mfma_f32_16x16x32_bf16 v[106:109], v[122:125], v[170:173], v[106:109]
	v_mfma_f32_16x16x32_bf16 v[94:97], v[110:113], v[178:181], v[94:97]
	v_mfma_f32_16x16x32_bf16 v[90:93], v[122:125], v[178:181], v[90:93]
	v_mfma_f32_16x16x32_bf16 v[78:81], v[110:113], v[186:189], v[78:81]
	v_mfma_f32_16x16x32_bf16 v[74:77], v[122:125], v[186:189], v[74:77]
	v_mfma_f32_16x16x32_bf16 v[158:161], v[118:121], v[166:169], v[158:161]
	v_mfma_f32_16x16x32_bf16 v[150:153], v[134:137], v[166:169], v[150:153]
	v_mfma_f32_16x16x32_bf16 v[114:117], v[118:121], v[174:177], v[114:117]
	v_mfma_f32_16x16x32_bf16 v[106:109], v[134:137], v[174:177], v[106:109]
	v_mfma_f32_16x16x32_bf16 v[94:97], v[118:121], v[182:185], v[94:97]
	v_mfma_f32_16x16x32_bf16 v[90:93], v[134:137], v[182:185], v[90:93]
	v_mfma_f32_16x16x32_bf16 v[78:81], v[118:121], v[210:213], v[78:81]
	v_mfma_f32_16x16x32_bf16 v[74:77], v[134:137], v[210:213], v[74:77]
	v_mfma_f32_16x16x32_bf16 v[130:133], v[138:141], v[162:165], v[130:133]
	v_mfma_f32_16x16x32_bf16 v[126:129], v[146:149], v[162:165], v[126:129]
	v_mfma_f32_16x16x32_bf16 v[102:105], v[138:141], v[170:173], v[102:105]
	v_mfma_f32_16x16x32_bf16 v[98:101], v[146:149], v[170:173], v[98:101]
	v_mfma_f32_16x16x32_bf16 v[86:89], v[138:141], v[178:181], v[86:89]
	v_mfma_f32_16x16x32_bf16 v[82:85], v[146:149], v[178:181], v[82:85]
	v_mfma_f32_16x16x32_bf16 v[70:73], v[138:141], v[186:189], v[70:73]
	v_mfma_f32_16x16x32_bf16 v[66:69], v[146:149], v[186:189], v[66:69]
	v_mfma_f32_16x16x32_bf16 v[130:133], v[142:145], v[166:169], v[130:133]
	v_mfma_f32_16x16x32_bf16 v[126:129], v[154:157], v[166:169], v[126:129]
	v_mfma_f32_16x16x32_bf16 v[102:105], v[142:145], v[174:177], v[102:105]
	v_mfma_f32_16x16x32_bf16 v[98:101], v[154:157], v[174:177], v[98:101]
	v_mfma_f32_16x16x32_bf16 v[86:89], v[142:145], v[182:185], v[86:89]
	v_mfma_f32_16x16x32_bf16 v[82:85], v[154:157], v[182:185], v[82:85]
	v_mfma_f32_16x16x32_bf16 v[70:73], v[142:145], v[210:213], v[70:73]
	v_mfma_f32_16x16x32_bf16 v[66:69], v[154:157], v[210:213], v[66:69]
	s_setprio 0
	s_barrier
	s_add_i32 s53, s53, s40
	v_lshl_add_u64 v[196:197], s[28:29], 0, v[192:193]
	s_mov_b32 m0, s53
	ds_read_b128 v[162:165], v214 offset:16384
	ds_read_b128 v[166:169], v214 offset:17408
	ds_read_b128 v[170:173], v214 offset:18432
	ds_read_b128 v[174:177], v214 offset:19456
	ds_read_b128 v[178:181], v214 offset:20480
	ds_read_b128 v[182:185], v214 offset:21504
	ds_read_b128 v[186:189], v214 offset:22528
	ds_read_b128 v[210:213], v214 offset:23552
	global_load_lds_dwordx4 v[196:197], off
	s_add_i32 m0, s53, 0x2000
	s_add_u32 s54, s28, 0x40000
	v_lshl_add_u64 v[198:199], s[28:29], 0, v[204:205]
	s_addc_u32 s55, s29, 0
	s_add_i32 s53, s56, s40
	global_load_lds_dwordx4 v[198:199], off
	v_lshl_add_u64 v[216:217], s[54:55], 0, v[192:193]
	s_mov_b32 m0, s53
	v_lshl_add_u64 v[220:221], s[30:31], 0, v[194:195]
	global_load_lds_dwordx4 v[216:217], off
	v_lshl_add_u64 v[216:217], s[54:55], 0, v[204:205]
	s_add_i32 m0, s53, 0x2000
	s_nop 0
	global_load_lds_dwordx4 v[216:217], off
	v_lshl_add_u64 v[216:217], s[30:31], 0, v[190:191]
	s_mov_b32 m0, s25
	s_nop 0
	global_load_lds_dwordx4 v[216:217], off
	s_mov_b32 m0, s27
	s_nop 0
	global_load_lds_dwordx4 v[220:221], off
	s_waitcnt vmcnt(8)
	s_waitcnt lgkmcnt(0)
	s_barrier
	s_setprio 1
	v_mfma_f32_16x16x32_bf16 v[62:65], v[110:113], v[162:165], v[62:65]
	v_mfma_f32_16x16x32_bf16 v[58:61], v[122:125], v[162:165], v[58:61]
	v_mfma_f32_16x16x32_bf16 v[46:49], v[110:113], v[170:173], v[46:49]
	v_mfma_f32_16x16x32_bf16 v[42:45], v[122:125], v[170:173], v[42:45]
	v_mfma_f32_16x16x32_bf16 v[30:33], v[110:113], v[178:181], v[30:33]
	v_mfma_f32_16x16x32_bf16 v[26:29], v[122:125], v[178:181], v[26:29]
	v_mfma_f32_16x16x32_bf16 v[14:17], v[110:113], v[186:189], v[14:17]
	v_mfma_f32_16x16x32_bf16 v[10:13], v[122:125], v[186:189], v[10:13]
	v_mfma_f32_16x16x32_bf16 v[62:65], v[118:121], v[166:169], v[62:65]
	v_mfma_f32_16x16x32_bf16 v[58:61], v[134:137], v[166:169], v[58:61]
	v_mfma_f32_16x16x32_bf16 v[46:49], v[118:121], v[174:177], v[46:49]
	v_mfma_f32_16x16x32_bf16 v[42:45], v[134:137], v[174:177], v[42:45]
	v_mfma_f32_16x16x32_bf16 v[30:33], v[118:121], v[182:185], v[30:33]
	v_mfma_f32_16x16x32_bf16 v[26:29], v[134:137], v[182:185], v[26:29]
	v_mfma_f32_16x16x32_bf16 v[14:17], v[118:121], v[210:213], v[14:17]
	v_mfma_f32_16x16x32_bf16 v[10:13], v[134:137], v[210:213], v[10:13]
	v_mfma_f32_16x16x32_bf16 v[54:57], v[138:141], v[162:165], v[54:57]
	v_mfma_f32_16x16x32_bf16 v[50:53], v[146:149], v[162:165], v[50:53]
	v_mfma_f32_16x16x32_bf16 v[38:41], v[138:141], v[170:173], v[38:41]
	v_mfma_f32_16x16x32_bf16 v[34:37], v[146:149], v[170:173], v[34:37]
	v_mfma_f32_16x16x32_bf16 v[22:25], v[138:141], v[178:181], v[22:25]
	v_mfma_f32_16x16x32_bf16 v[18:21], v[146:149], v[178:181], v[18:21]
	v_mfma_f32_16x16x32_bf16 v[6:9], v[138:141], v[186:189], v[6:9]
	v_mfma_f32_16x16x32_bf16 v[2:5], v[146:149], v[186:189], v[2:5]
	v_mfma_f32_16x16x32_bf16 v[54:57], v[142:145], v[166:169], v[54:57]
	v_mfma_f32_16x16x32_bf16 v[50:53], v[154:157], v[166:169], v[50:53]
	v_mfma_f32_16x16x32_bf16 v[38:41], v[142:145], v[174:177], v[38:41]
	v_mfma_f32_16x16x32_bf16 v[34:37], v[154:157], v[174:177], v[34:37]
	v_mfma_f32_16x16x32_bf16 v[22:25], v[142:145], v[182:185], v[22:25]
	v_mfma_f32_16x16x32_bf16 v[18:21], v[154:157], v[182:185], v[18:21]
	v_mfma_f32_16x16x32_bf16 v[6:9], v[142:145], v[210:213], v[6:9]
	v_mfma_f32_16x16x32_bf16 v[2:5], v[154:157], v[210:213], v[2:5]
	s_setprio 0
	s_barrier
	s_add_i32 s53, 0, 0x18000
	s_add_i32 s54, 0, 0x1c000
	v_add_u32_e32 v134, s53, v1
	v_add_u32_e32 v154, s54, v1
	ds_read_b128 v[110:113], v134
	ds_read_b128 v[118:121], v134 offset:1024
	ds_read_b128 v[122:125], v134 offset:2048
	ds_read_b128 v[134:137], v134 offset:3072
	ds_read_b128 v[138:141], v154
	ds_read_b128 v[142:145], v154 offset:1024
	ds_read_b128 v[146:149], v154 offset:2048
	ds_read_b128 v[154:157], v154 offset:3072
	s_add_u32 s30, s30, 0x40000
	s_addc_u32 s31, s31, 0
	s_mov_b32 m0, s41
	v_lshl_add_u64 v[222:223], s[30:31], 0, v[190:191]
	ds_read_b128 v[162:165], v214 offset:32768
	ds_read_b128 v[166:169], v214 offset:33792
	ds_read_b128 v[170:173], v214 offset:34816
	ds_read_b128 v[174:177], v214 offset:35840
	ds_read_b128 v[178:181], v214 offset:36864
	ds_read_b128 v[182:185], v214 offset:37888
	ds_read_b128 v[186:189], v214 offset:38912
	ds_read_b128 v[210:213], v214 offset:39936
	global_load_lds_dwordx4 v[222:223], off
	v_lshl_add_u64 v[222:223], s[30:31], 0, v[194:195]
	s_mov_b32 m0, s42
	s_nop 0
	global_load_lds_dwordx4 v[222:223], off
	s_waitcnt vmcnt(8)
	s_waitcnt lgkmcnt(0)
	s_barrier
	s_setprio 1
	v_mfma_f32_16x16x32_bf16 v[158:161], v[110:113], v[162:165], v[158:161]
	v_mfma_f32_16x16x32_bf16 v[150:153], v[122:125], v[162:165], v[150:153]
	v_mfma_f32_16x16x32_bf16 v[114:117], v[110:113], v[170:173], v[114:117]
	v_mfma_f32_16x16x32_bf16 v[106:109], v[122:125], v[170:173], v[106:109]
	v_mfma_f32_16x16x32_bf16 v[94:97], v[110:113], v[178:181], v[94:97]
	v_mfma_f32_16x16x32_bf16 v[90:93], v[122:125], v[178:181], v[90:93]
	v_mfma_f32_16x16x32_bf16 v[78:81], v[110:113], v[186:189], v[78:81]
	v_mfma_f32_16x16x32_bf16 v[74:77], v[122:125], v[186:189], v[74:77]
	v_mfma_f32_16x16x32_bf16 v[158:161], v[118:121], v[166:169], v[158:161]
	v_mfma_f32_16x16x32_bf16 v[150:153], v[134:137], v[166:169], v[150:153]
	v_mfma_f32_16x16x32_bf16 v[114:117], v[118:121], v[174:177], v[114:117]
	v_mfma_f32_16x16x32_bf16 v[106:109], v[134:137], v[174:177], v[106:109]
	v_mfma_f32_16x16x32_bf16 v[94:97], v[118:121], v[182:185], v[94:97]
	v_mfma_f32_16x16x32_bf16 v[90:93], v[134:137], v[182:185], v[90:93]
	v_mfma_f32_16x16x32_bf16 v[78:81], v[118:121], v[210:213], v[78:81]
	v_mfma_f32_16x16x32_bf16 v[74:77], v[134:137], v[210:213], v[74:77]
	v_mfma_f32_16x16x32_bf16 v[130:133], v[138:141], v[162:165], v[130:133]
	v_mfma_f32_16x16x32_bf16 v[126:129], v[146:149], v[162:165], v[126:129]
	v_mfma_f32_16x16x32_bf16 v[102:105], v[138:141], v[170:173], v[102:105]
	v_mfma_f32_16x16x32_bf16 v[98:101], v[146:149], v[170:173], v[98:101]
	v_mfma_f32_16x16x32_bf16 v[86:89], v[138:141], v[178:181], v[86:89]
	v_mfma_f32_16x16x32_bf16 v[82:85], v[146:149], v[178:181], v[82:85]
	v_mfma_f32_16x16x32_bf16 v[70:73], v[138:141], v[186:189], v[70:73]
	v_mfma_f32_16x16x32_bf16 v[66:69], v[146:149], v[186:189], v[66:69]
	v_mfma_f32_16x16x32_bf16 v[130:133], v[142:145], v[166:169], v[130:133]
	v_mfma_f32_16x16x32_bf16 v[126:129], v[154:157], v[166:169], v[126:129]
	v_mfma_f32_16x16x32_bf16 v[102:105], v[142:145], v[174:177], v[102:105]
	v_mfma_f32_16x16x32_bf16 v[98:101], v[154:157], v[174:177], v[98:101]
	v_mfma_f32_16x16x32_bf16 v[86:89], v[142:145], v[182:185], v[86:89]
	v_mfma_f32_16x16x32_bf16 v[82:85], v[154:157], v[182:185], v[82:85]
	v_mfma_f32_16x16x32_bf16 v[70:73], v[142:145], v[210:213], v[70:73]
	v_mfma_f32_16x16x32_bf16 v[66:69], v[154:157], v[210:213], v[66:69]
	s_setprio 0
	s_barrier
	s_add_i32 s30, s53, s40
	v_lshl_add_u64 v[196:197], v[196:197], 0, s[94:95]
	s_mov_b32 m0, s30
	ds_read_b128 v[162:165], v214 offset:49152
	ds_read_b128 v[166:169], v214 offset:50176
	ds_read_b128 v[170:173], v214 offset:51200
	ds_read_b128 v[174:177], v214 offset:52224
	ds_read_b128 v[178:181], v214 offset:53248
	ds_read_b128 v[182:185], v214 offset:54272
	ds_read_b128 v[186:189], v214 offset:55296
	ds_read_b128 v[210:213], v214 offset:56320
	global_load_lds_dwordx4 v[196:197], off
	s_add_i32 m0, s30, 0x2000
	s_add_u32 s28, s28, 0x40080
	v_lshl_add_u64 v[196:197], v[198:199], 0, s[94:95]
	s_addc_u32 s29, s29, 0
	s_add_i32 s30, s54, s40
	global_load_lds_dwordx4 v[196:197], off
	v_lshl_add_u64 v[196:197], s[28:29], 0, v[192:193]
	s_mov_b32 m0, s30
	s_nop 0
	global_load_lds_dwordx4 v[196:197], off
	v_lshl_add_u64 v[196:197], s[28:29], 0, v[204:205]
	s_add_i32 m0, s30, 0x2000
	s_nop 0
	global_load_lds_dwordx4 v[196:197], off
	v_lshl_add_u64 v[196:197], v[216:217], 0, s[94:95]
	s_mov_b32 m0, s45
	s_nop 0
	global_load_lds_dwordx4 v[196:197], off
	v_lshl_add_u64 v[196:197], v[220:221], 0, s[94:95]
	s_mov_b32 m0, s46
	s_nop 0
	global_load_lds_dwordx4 v[196:197], off
	s_waitcnt vmcnt(8)
	s_waitcnt lgkmcnt(0)
	s_barrier
	s_setprio 1
	v_mfma_f32_16x16x32_bf16 v[62:65], v[110:113], v[162:165], v[62:65]
	v_mfma_f32_16x16x32_bf16 v[58:61], v[122:125], v[162:165], v[58:61]
	v_mfma_f32_16x16x32_bf16 v[46:49], v[110:113], v[170:173], v[46:49]
	v_mfma_f32_16x16x32_bf16 v[42:45], v[122:125], v[170:173], v[42:45]
	v_mfma_f32_16x16x32_bf16 v[30:33], v[110:113], v[178:181], v[30:33]
	v_mfma_f32_16x16x32_bf16 v[26:29], v[122:125], v[178:181], v[26:29]
	v_mfma_f32_16x16x32_bf16 v[14:17], v[110:113], v[186:189], v[14:17]
	v_mfma_f32_16x16x32_bf16 v[10:13], v[122:125], v[186:189], v[10:13]
	v_mfma_f32_16x16x32_bf16 v[62:65], v[118:121], v[166:169], v[62:65]
	v_mfma_f32_16x16x32_bf16 v[58:61], v[134:137], v[166:169], v[58:61]
	v_mfma_f32_16x16x32_bf16 v[46:49], v[118:121], v[174:177], v[46:49]
	v_mfma_f32_16x16x32_bf16 v[42:45], v[134:137], v[174:177], v[42:45]
	v_mfma_f32_16x16x32_bf16 v[30:33], v[118:121], v[182:185], v[30:33]
	v_mfma_f32_16x16x32_bf16 v[26:29], v[134:137], v[182:185], v[26:29]
	v_mfma_f32_16x16x32_bf16 v[14:17], v[118:121], v[210:213], v[14:17]
	v_mfma_f32_16x16x32_bf16 v[10:13], v[134:137], v[210:213], v[10:13]
	v_mfma_f32_16x16x32_bf16 v[54:57], v[138:141], v[162:165], v[54:57]
	v_mfma_f32_16x16x32_bf16 v[50:53], v[146:149], v[162:165], v[50:53]
	v_mfma_f32_16x16x32_bf16 v[38:41], v[138:141], v[170:173], v[38:41]
	v_mfma_f32_16x16x32_bf16 v[34:37], v[146:149], v[170:173], v[34:37]
	v_mfma_f32_16x16x32_bf16 v[22:25], v[138:141], v[178:181], v[22:25]
	v_mfma_f32_16x16x32_bf16 v[18:21], v[146:149], v[178:181], v[18:21]
	v_mfma_f32_16x16x32_bf16 v[6:9], v[138:141], v[186:189], v[6:9]
	v_mfma_f32_16x16x32_bf16 v[2:5], v[146:149], v[186:189], v[2:5]
	v_mfma_f32_16x16x32_bf16 v[54:57], v[142:145], v[166:169], v[54:57]
	v_mfma_f32_16x16x32_bf16 v[50:53], v[154:157], v[166:169], v[50:53]
	v_mfma_f32_16x16x32_bf16 v[38:41], v[142:145], v[174:177], v[38:41]
	v_mfma_f32_16x16x32_bf16 v[34:37], v[154:157], v[174:177], v[34:37]
	v_mfma_f32_16x16x32_bf16 v[22:25], v[142:145], v[182:185], v[22:25]
	v_mfma_f32_16x16x32_bf16 v[18:21], v[154:157], v[182:185], v[18:21]
	v_mfma_f32_16x16x32_bf16 v[6:9], v[142:145], v[210:213], v[6:9]
	v_mfma_f32_16x16x32_bf16 v[2:5], v[154:157], v[210:213], v[2:5]
	s_setprio 0
	s_barrier
	s_add_i32 s52, s52, 2
	s_add_u32 s4, s4, 0x100
	s_addc_u32 s5, s5, 0
	s_add_u32 s50, s50, 0x100
	s_addc_u32 s51, s51, 0
	s_cmp_gt_u32 s52, 13
	s_cbranch_scc0 .LBB0_1096
	s_and_b64 vcc, exec, s[14:15]
	s_cbranch_vccz .LBB0_1099
	s_barrier

.LBB0_1180:
	s_add_u32 s26, s24, 0xfffc0080
	s_addc_u32 s27, s25, -1
	s_add_i32 s55, 0, 0x10000
	s_cmp_eq_u32 s54, 12
	s_cselect_b32 s29, s17, s27
	s_cselect_b32 s28, s50, s26
	v_add_u32_e32 v150, s55, v1
	s_cselect_b32 s27, s15, s53
	s_cselect_b32 s26, s51, s52
	s_add_i32 s58, 0, 0x14000
	ds_read_b128 v[142:145], v150
	ds_read_b128 v[146:149], v150 offset:1024
	ds_read_b128 v[154:157], v150 offset:2048
	ds_read_b128 v[158:161], v150 offset:3072
	v_add_u32_e32 v150, s58, v1
	ds_read_b128 v[162:165], v150
	ds_read_b128 v[166:169], v150 offset:1024
	ds_read_b128 v[170:173], v150 offset:2048
	ds_read_b128 v[174:177], v150 offset:3072
	v_lshl_add_u64 v[150:151], s[24:25], 0, v[138:139]
	s_add_i32 m0, s40, 0xc000
	ds_read_b128 v[178:181], v152
	ds_read_b128 v[182:185], v152 offset:1024
	ds_read_b128 v[186:189], v152 offset:2048
	ds_read_b128 v[190:193], v152 offset:3072
	ds_read_b128 v[204:207], v152 offset:4096
	ds_read_b128 v[208:211], v152 offset:5120
	ds_read_b128 v[212:215], v152 offset:6144
	ds_read_b128 v[228:231], v152 offset:7168
	global_load_lds_dwordx4 v[150:151], off
	v_lshl_add_u64 v[150:151], s[24:25], 0, v[140:141]
	s_add_i32 m0, s40, 0xe000
	s_nop 0
	global_load_lds_dwordx4 v[150:151], off
	s_waitcnt vmcnt(8)
	s_waitcnt lgkmcnt(0)
	s_barrier
	s_setprio 1
	v_mfma_f32_16x16x32_bf16 v[126:129], v[142:145], v[178:181], v[126:129]
	v_mfma_f32_16x16x32_bf16 v[122:125], v[154:157], v[178:181], v[122:125]
	v_mfma_f32_16x16x32_bf16 v[110:113], v[142:145], v[186:189], v[110:113]
	v_mfma_f32_16x16x32_bf16 v[106:109], v[154:157], v[186:189], v[106:109]
	v_mfma_f32_16x16x32_bf16 v[94:97], v[142:145], v[204:207], v[94:97]
	v_mfma_f32_16x16x32_bf16 v[90:93], v[154:157], v[204:207], v[90:93]
	v_mfma_f32_16x16x32_bf16 v[78:81], v[142:145], v[212:215], v[78:81]
	v_mfma_f32_16x16x32_bf16 v[74:77], v[154:157], v[212:215], v[74:77]
	v_mfma_f32_16x16x32_bf16 v[126:129], v[146:149], v[182:185], v[126:129]
	v_mfma_f32_16x16x32_bf16 v[122:125], v[158:161], v[182:185], v[122:125]
	v_mfma_f32_16x16x32_bf16 v[110:113], v[146:149], v[190:193], v[110:113]
	v_mfma_f32_16x16x32_bf16 v[106:109], v[158:161], v[190:193], v[106:109]
	v_mfma_f32_16x16x32_bf16 v[94:97], v[146:149], v[208:211], v[94:97]
	v_mfma_f32_16x16x32_bf16 v[90:93], v[158:161], v[208:211], v[90:93]
	v_mfma_f32_16x16x32_bf16 v[78:81], v[146:149], v[228:231], v[78:81]
	v_mfma_f32_16x16x32_bf16 v[74:77], v[158:161], v[228:231], v[74:77]
	v_mfma_f32_16x16x32_bf16 v[118:121], v[162:165], v[178:181], v[118:121]
	v_mfma_f32_16x16x32_bf16 v[114:117], v[170:173], v[178:181], v[114:117]
	v_mfma_f32_16x16x32_bf16 v[102:105], v[162:165], v[186:189], v[102:105]
	v_mfma_f32_16x16x32_bf16 v[98:101], v[170:173], v[186:189], v[98:101]
	v_mfma_f32_16x16x32_bf16 v[86:89], v[162:165], v[204:207], v[86:89]
	v_mfma_f32_16x16x32_bf16 v[82:85], v[170:173], v[204:207], v[82:85]
	v_mfma_f32_16x16x32_bf16 v[70:73], v[162:165], v[212:215], v[70:73]
	v_mfma_f32_16x16x32_bf16 v[66:69], v[170:173], v[212:215], v[66:69]
	v_mfma_f32_16x16x32_bf16 v[118:121], v[166:169], v[182:185], v[118:121]
	v_mfma_f32_16x16x32_bf16 v[114:117], v[174:177], v[182:185], v[114:117]
	v_mfma_f32_16x16x32_bf16 v[102:105], v[166:169], v[190:193], v[102:105]
	v_mfma_f32_16x16x32_bf16 v[98:101], v[174:177], v[190:193], v[98:101]
	v_mfma_f32_16x16x32_bf16 v[86:89], v[166:169], v[208:211], v[86:89]
	v_mfma_f32_16x16x32_bf16 v[82:85], v[174:177], v[208:211], v[82:85]
	v_mfma_f32_16x16x32_bf16 v[70:73], v[166:169], v[228:231], v[70:73]
	v_mfma_f32_16x16x32_bf16 v[66:69], v[174:177], v[228:231], v[66:69]
	s_setprio 0
	s_barrier
	s_add_i32 s55, s55, s39
	v_lshl_add_u64 v[150:151], s[26:27], 0, v[134:135]
	s_mov_b32 m0, s55
	ds_read_b128 v[178:181], v152 offset:16384
	ds_read_b128 v[182:185], v152 offset:17408
	ds_read_b128 v[186:189], v152 offset:18432
	ds_read_b128 v[190:193], v152 offset:19456
	ds_read_b128 v[204:207], v152 offset:20480
	ds_read_b128 v[208:211], v152 offset:21504
	ds_read_b128 v[212:215], v152 offset:22528
	ds_read_b128 v[228:231], v152 offset:23552
	global_load_lds_dwordx4 v[150:151], off
	s_add_i32 m0, s55, 0x2000
	s_add_u32 s56, s26, 0x40000
	v_lshl_add_u64 v[194:195], s[26:27], 0, v[130:131]
	s_addc_u32 s57, s27, 0
	s_add_i32 s55, s58, s39
	global_load_lds_dwordx4 v[194:195], off
	v_lshl_add_u64 v[196:197], s[56:57], 0, v[134:135]
	s_mov_b32 m0, s55
	v_lshl_add_u64 v[198:199], s[28:29], 0, v[132:133]
	global_load_lds_dwordx4 v[196:197], off
	v_lshl_add_u64 v[196:197], s[56:57], 0, v[130:131]
	s_add_i32 m0, s55, 0x2000
	s_nop 0
	global_load_lds_dwordx4 v[196:197], off
	v_lshl_add_u64 v[196:197], s[28:29], 0, v[136:137]
	s_mov_b32 m0, s40
	s_nop 0
	global_load_lds_dwordx4 v[196:197], off
	s_mov_b32 m0, s41
	s_nop 0
	global_load_lds_dwordx4 v[198:199], off
	s_waitcnt vmcnt(8)
	s_waitcnt lgkmcnt(0)
	s_barrier
	s_setprio 1
	v_mfma_f32_16x16x32_bf16 v[62:65], v[142:145], v[178:181], v[62:65]
	v_mfma_f32_16x16x32_bf16 v[58:61], v[154:157], v[178:181], v[58:61]
	v_mfma_f32_16x16x32_bf16 v[46:49], v[142:145], v[186:189], v[46:49]
	v_mfma_f32_16x16x32_bf16 v[42:45], v[154:157], v[186:189], v[42:45]
	v_mfma_f32_16x16x32_bf16 v[30:33], v[142:145], v[204:207], v[30:33]
	v_mfma_f32_16x16x32_bf16 v[26:29], v[154:157], v[204:207], v[26:29]
	v_mfma_f32_16x16x32_bf16 v[14:17], v[142:145], v[212:215], v[14:17]
	v_mfma_f32_16x16x32_bf16 v[10:13], v[154:157], v[212:215], v[10:13]
	v_mfma_f32_16x16x32_bf16 v[62:65], v[146:149], v[182:185], v[62:65]
	v_mfma_f32_16x16x32_bf16 v[58:61], v[158:161], v[182:185], v[58:61]
	v_mfma_f32_16x16x32_bf16 v[46:49], v[146:149], v[190:193], v[46:49]
	v_mfma_f32_16x16x32_bf16 v[42:45], v[158:161], v[190:193], v[42:45]
	v_mfma_f32_16x16x32_bf16 v[30:33], v[146:149], v[208:211], v[30:33]
	v_mfma_f32_16x16x32_bf16 v[26:29], v[158:161], v[208:211], v[26:29]
	v_mfma_f32_16x16x32_bf16 v[14:17], v[146:149], v[228:231], v[14:17]
	v_mfma_f32_16x16x32_bf16 v[10:13], v[158:161], v[228:231], v[10:13]
	v_mfma_f32_16x16x32_bf16 v[54:57], v[162:165], v[178:181], v[54:57]
	v_mfma_f32_16x16x32_bf16 v[50:53], v[170:173], v[178:181], v[50:53]
	v_mfma_f32_16x16x32_bf16 v[38:41], v[162:165], v[186:189], v[38:41]
	v_mfma_f32_16x16x32_bf16 v[34:37], v[170:173], v[186:189], v[34:37]
	v_mfma_f32_16x16x32_bf16 v[22:25], v[162:165], v[204:207], v[22:25]
	v_mfma_f32_16x16x32_bf16 v[18:21], v[170:173], v[204:207], v[18:21]
	v_mfma_f32_16x16x32_bf16 v[6:9], v[162:165], v[212:215], v[6:9]
	v_mfma_f32_16x16x32_bf16 v[2:5], v[170:173], v[212:215], v[2:5]
	v_mfma_f32_16x16x32_bf16 v[54:57], v[166:169], v[182:185], v[54:57]
	v_mfma_f32_16x16x32_bf16 v[50:53], v[174:177], v[182:185], v[50:53]
	v_mfma_f32_16x16x32_bf16 v[38:41], v[166:169], v[190:193], v[38:41]
	v_mfma_f32_16x16x32_bf16 v[34:37], v[174:177], v[190:193], v[34:37]
	v_mfma_f32_16x16x32_bf16 v[22:25], v[166:169], v[208:211], v[22:25]
	v_mfma_f32_16x16x32_bf16 v[18:21], v[174:177], v[208:211], v[18:21]
	v_mfma_f32_16x16x32_bf16 v[6:9], v[166:169], v[228:231], v[6:9]
	v_mfma_f32_16x16x32_bf16 v[2:5], v[174:177], v[228:231], v[2:5]
	s_setprio 0
	s_barrier
	s_add_i32 s55, 0, 0x18000
	v_add_u32_e32 v153, s55, v1
	s_add_i32 s56, 0, 0x1c000
	ds_read_b128 v[142:145], v153
	ds_read_b128 v[146:149], v153 offset:1024
	ds_read_b128 v[154:157], v153 offset:2048
	ds_read_b128 v[158:161], v153 offset:3072
	v_add_u32_e32 v153, s56, v1
	ds_read_b128 v[162:165], v153
	ds_read_b128 v[166:169], v153 offset:1024
	ds_read_b128 v[170:173], v153 offset:2048
	ds_read_b128 v[174:177], v153 offset:3072
	s_add_u32 s28, s28, 0x40000
	s_addc_u32 s29, s29, 0
	s_mov_b32 m0, s42
	v_lshl_add_u64 v[216:217], s[28:29], 0, v[136:137]
	ds_read_b128 v[178:181], v152 offset:32768
	ds_read_b128 v[182:185], v152 offset:33792
	ds_read_b128 v[186:189], v152 offset:34816
	ds_read_b128 v[190:193], v152 offset:35840
	ds_read_b128 v[204:207], v152 offset:36864
	ds_read_b128 v[208:211], v152 offset:37888
	ds_read_b128 v[212:215], v152 offset:38912
	ds_read_b128 v[228:231], v152 offset:39936
	global_load_lds_dwordx4 v[216:217], off
	v_lshl_add_u64 v[216:217], s[28:29], 0, v[132:133]
	s_mov_b32 m0, s43
	s_nop 0
	global_load_lds_dwordx4 v[216:217], off
	s_waitcnt vmcnt(8)
	s_waitcnt lgkmcnt(0)
	s_barrier
	s_setprio 1
	v_mfma_f32_16x16x32_bf16 v[126:129], v[142:145], v[178:181], v[126:129]
	v_mfma_f32_16x16x32_bf16 v[122:125], v[154:157], v[178:181], v[122:125]
	v_mfma_f32_16x16x32_bf16 v[110:113], v[142:145], v[186:189], v[110:113]
	v_mfma_f32_16x16x32_bf16 v[106:109], v[154:157], v[186:189], v[106:109]
	v_mfma_f32_16x16x32_bf16 v[94:97], v[142:145], v[204:207], v[94:97]
	v_mfma_f32_16x16x32_bf16 v[90:93], v[154:157], v[204:207], v[90:93]
	v_mfma_f32_16x16x32_bf16 v[78:81], v[142:145], v[212:215], v[78:81]
	v_mfma_f32_16x16x32_bf16 v[74:77], v[154:157], v[212:215], v[74:77]
	v_mfma_f32_16x16x32_bf16 v[126:129], v[146:149], v[182:185], v[126:129]
	v_mfma_f32_16x16x32_bf16 v[122:125], v[158:161], v[182:185], v[122:125]
	v_mfma_f32_16x16x32_bf16 v[110:113], v[146:149], v[190:193], v[110:113]
	v_mfma_f32_16x16x32_bf16 v[106:109], v[158:161], v[190:193], v[106:109]
	v_mfma_f32_16x16x32_bf16 v[94:97], v[146:149], v[208:211], v[94:97]
	v_mfma_f32_16x16x32_bf16 v[90:93], v[158:161], v[208:211], v[90:93]
	v_mfma_f32_16x16x32_bf16 v[78:81], v[146:149], v[228:231], v[78:81]
	v_mfma_f32_16x16x32_bf16 v[74:77], v[158:161], v[228:231], v[74:77]
	v_mfma_f32_16x16x32_bf16 v[118:121], v[162:165], v[178:181], v[118:121]
	v_mfma_f32_16x16x32_bf16 v[114:117], v[170:173], v[178:181], v[114:117]
	v_mfma_f32_16x16x32_bf16 v[102:105], v[162:165], v[186:189], v[102:105]
	v_mfma_f32_16x16x32_bf16 v[98:101], v[170:173], v[186:189], v[98:101]
	v_mfma_f32_16x16x32_bf16 v[86:89], v[162:165], v[204:207], v[86:89]
	v_mfma_f32_16x16x32_bf16 v[82:85], v[170:173], v[204:207], v[82:85]
	v_mfma_f32_16x16x32_bf16 v[70:73], v[162:165], v[212:215], v[70:73]
	v_mfma_f32_16x16x32_bf16 v[66:69], v[170:173], v[212:215], v[66:69]
	v_mfma_f32_16x16x32_bf16 v[118:121], v[166:169], v[182:185], v[118:121]
	v_mfma_f32_16x16x32_bf16 v[114:117], v[174:177], v[182:185], v[114:117]
	v_mfma_f32_16x16x32_bf16 v[102:105], v[166:169], v[190:193], v[102:105]
	v_mfma_f32_16x16x32_bf16 v[98:101], v[174:177], v[190:193], v[98:101]
	v_mfma_f32_16x16x32_bf16 v[86:89], v[166:169], v[208:211], v[86:89]
	v_mfma_f32_16x16x32_bf16 v[82:85], v[174:177], v[208:211], v[82:85]
	v_mfma_f32_16x16x32_bf16 v[70:73], v[166:169], v[228:231], v[70:73]
	v_mfma_f32_16x16x32_bf16 v[66:69], v[174:177], v[228:231], v[66:69]
	s_setprio 0
	s_barrier
	s_add_i32 s28, s55, s39
	v_lshl_add_u64 v[150:151], v[150:151], 0, s[94:95]
	s_mov_b32 m0, s28
	ds_read_b128 v[178:181], v152 offset:49152
	ds_read_b128 v[182:185], v152 offset:50176
	ds_read_b128 v[186:189], v152 offset:51200
	ds_read_b128 v[190:193], v152 offset:52224
	ds_read_b128 v[204:207], v152 offset:53248
	ds_read_b128 v[208:211], v152 offset:54272
	ds_read_b128 v[212:215], v152 offset:55296
	ds_read_b128 v[228:231], v152 offset:56320
	global_load_lds_dwordx4 v[150:151], off
	s_add_i32 m0, s28, 0x2000
	s_add_u32 s26, s26, 0x40080
	v_lshl_add_u64 v[150:151], v[194:195], 0, s[94:95]
	s_addc_u32 s27, s27, 0
	s_add_i32 s28, s56, s39
	global_load_lds_dwordx4 v[150:151], off
	v_lshl_add_u64 v[150:151], s[26:27], 0, v[134:135]
	s_mov_b32 m0, s28
	s_nop 0
	global_load_lds_dwordx4 v[150:151], off
	v_lshl_add_u64 v[150:151], s[26:27], 0, v[130:131]
	s_add_i32 m0, s28, 0x2000
	s_nop 0
	global_load_lds_dwordx4 v[150:151], off
	v_lshl_add_u64 v[150:151], v[196:197], 0, s[94:95]
	s_mov_b32 m0, s47
	s_nop 0
	global_load_lds_dwordx4 v[150:151], off
	v_lshl_add_u64 v[150:151], v[198:199], 0, s[94:95]
	s_mov_b32 m0, s48
	s_nop 0
	global_load_lds_dwordx4 v[150:151], off
	s_waitcnt vmcnt(8)
	s_waitcnt lgkmcnt(0)
	s_barrier
	s_setprio 1
	v_mfma_f32_16x16x32_bf16 v[62:65], v[142:145], v[178:181], v[62:65]
	v_mfma_f32_16x16x32_bf16 v[58:61], v[154:157], v[178:181], v[58:61]
	v_mfma_f32_16x16x32_bf16 v[46:49], v[142:145], v[186:189], v[46:49]
	v_mfma_f32_16x16x32_bf16 v[42:45], v[154:157], v[186:189], v[42:45]
	v_mfma_f32_16x16x32_bf16 v[30:33], v[142:145], v[204:207], v[30:33]
	v_mfma_f32_16x16x32_bf16 v[26:29], v[154:157], v[204:207], v[26:29]
	v_mfma_f32_16x16x32_bf16 v[14:17], v[142:145], v[212:215], v[14:17]
	v_mfma_f32_16x16x32_bf16 v[10:13], v[154:157], v[212:215], v[10:13]
	v_mfma_f32_16x16x32_bf16 v[62:65], v[146:149], v[182:185], v[62:65]
	v_mfma_f32_16x16x32_bf16 v[58:61], v[158:161], v[182:185], v[58:61]
	v_mfma_f32_16x16x32_bf16 v[46:49], v[146:149], v[190:193], v[46:49]
	v_mfma_f32_16x16x32_bf16 v[42:45], v[158:161], v[190:193], v[42:45]
	v_mfma_f32_16x16x32_bf16 v[30:33], v[146:149], v[208:211], v[30:33]
	v_mfma_f32_16x16x32_bf16 v[26:29], v[158:161], v[208:211], v[26:29]
	v_mfma_f32_16x16x32_bf16 v[14:17], v[146:149], v[228:231], v[14:17]
	v_mfma_f32_16x16x32_bf16 v[10:13], v[158:161], v[228:231], v[10:13]
	v_mfma_f32_16x16x32_bf16 v[54:57], v[162:165], v[178:181], v[54:57]
	v_mfma_f32_16x16x32_bf16 v[50:53], v[170:173], v[178:181], v[50:53]
	v_mfma_f32_16x16x32_bf16 v[38:41], v[162:165], v[186:189], v[38:41]
	v_mfma_f32_16x16x32_bf16 v[34:37], v[170:173], v[186:189], v[34:37]
	v_mfma_f32_16x16x32_bf16 v[22:25], v[162:165], v[204:207], v[22:25]
	v_mfma_f32_16x16x32_bf16 v[18:21], v[170:173], v[204:207], v[18:21]
	v_mfma_f32_16x16x32_bf16 v[6:9], v[162:165], v[212:215], v[6:9]
	v_mfma_f32_16x16x32_bf16 v[2:5], v[170:173], v[212:215], v[2:5]
	v_mfma_f32_16x16x32_bf16 v[54:57], v[166:169], v[182:185], v[54:57]
	v_mfma_f32_16x16x32_bf16 v[50:53], v[174:177], v[182:185], v[50:53]
	v_mfma_f32_16x16x32_bf16 v[38:41], v[166:169], v[190:193], v[38:41]
	v_mfma_f32_16x16x32_bf16 v[34:37], v[174:177], v[190:193], v[34:37]
	v_mfma_f32_16x16x32_bf16 v[22:25], v[166:169], v[208:211], v[22:25]
	v_mfma_f32_16x16x32_bf16 v[18:21], v[174:177], v[208:211], v[18:21]
	v_mfma_f32_16x16x32_bf16 v[6:9], v[166:169], v[228:231], v[6:9]
	v_mfma_f32_16x16x32_bf16 v[2:5], v[174:177], v[228:231], v[2:5]
	s_setprio 0
	s_barrier
	s_add_i32 s54, s54, 2
	s_add_u32 s24, s24, 0x100
	s_addc_u32 s25, s25, 0
	s_add_u32 s52, s52, 0x100
	s_addc_u32 s53, s53, 0
	s_cmp_gt_u32 s54, 13
	s_cbranch_scc0 .LBB0_1180
	s_and_b64 vcc, exec, s[12:13]
	s_cbranch_vccz .LBB0_1183
	s_barrier

.LBB0_1263:
	s_add_u32 s20, s18, 0x100
	s_addc_u32 s21, s19, 0
	s_add_i32 s53, 0, 0x10000
	s_cmp_eq_u32 s52, 40
	s_cselect_b32 s25, s5, s21
	s_cselect_b32 s24, s4, s20
	s_cselect_b32 s23, s17, s51
	s_cselect_b32 s22, s16, s50
	s_add_i32 s54, 0, 0x14000
	v_add_u32_e32 v134, s53, v1
	v_add_u32_e32 v154, s54, v1
	ds_read_b128 v[110:113], v134
	ds_read_b128 v[118:121], v134 offset:1024
	ds_read_b128 v[122:125], v134 offset:2048
	ds_read_b128 v[134:137], v134 offset:3072
	ds_read_b128 v[138:141], v154
	ds_read_b128 v[142:145], v154 offset:1024
	ds_read_b128 v[146:149], v154 offset:2048
	ds_read_b128 v[154:157], v154 offset:3072
	v_lshl_add_u64 v[196:197], s[18:19], 0, v[206:207]
	s_add_i32 m0, s35, 0xc000
	ds_read_b128 v[162:165], v214
	ds_read_b128 v[166:169], v214 offset:1024
	ds_read_b128 v[170:173], v214 offset:2048
	ds_read_b128 v[174:177], v214 offset:3072
	ds_read_b128 v[178:181], v214 offset:4096
	ds_read_b128 v[182:185], v214 offset:5120
	ds_read_b128 v[186:189], v214 offset:6144
	ds_read_b128 v[210:213], v214 offset:7168
	global_load_lds_dwordx4 v[196:197], off
	v_lshl_add_u64 v[196:197], s[18:19], 0, v[208:209]
	s_add_i32 m0, s35, 0xe000
	s_nop 0
	global_load_lds_dwordx4 v[196:197], off
	s_waitcnt vmcnt(8)
	s_waitcnt lgkmcnt(0)
	s_barrier
	s_setprio 1
	v_mfma_f32_16x16x32_bf16 v[158:161], v[110:113], v[162:165], v[158:161]
	v_mfma_f32_16x16x32_bf16 v[150:153], v[122:125], v[162:165], v[150:153]
	v_mfma_f32_16x16x32_bf16 v[114:117], v[110:113], v[170:173], v[114:117]
	v_mfma_f32_16x16x32_bf16 v[106:109], v[122:125], v[170:173], v[106:109]
	v_mfma_f32_16x16x32_bf16 v[94:97], v[110:113], v[178:181], v[94:97]
	v_mfma_f32_16x16x32_bf16 v[90:93], v[122:125], v[178:181], v[90:93]
	v_mfma_f32_16x16x32_bf16 v[78:81], v[110:113], v[186:189], v[78:81]
	v_mfma_f32_16x16x32_bf16 v[74:77], v[122:125], v[186:189], v[74:77]
	v_mfma_f32_16x16x32_bf16 v[158:161], v[118:121], v[166:169], v[158:161]
	v_mfma_f32_16x16x32_bf16 v[150:153], v[134:137], v[166:169], v[150:153]
	v_mfma_f32_16x16x32_bf16 v[114:117], v[118:121], v[174:177], v[114:117]
	v_mfma_f32_16x16x32_bf16 v[106:109], v[134:137], v[174:177], v[106:109]
	v_mfma_f32_16x16x32_bf16 v[94:97], v[118:121], v[182:185], v[94:97]
	v_mfma_f32_16x16x32_bf16 v[90:93], v[134:137], v[182:185], v[90:93]
	v_mfma_f32_16x16x32_bf16 v[78:81], v[118:121], v[210:213], v[78:81]
	v_mfma_f32_16x16x32_bf16 v[74:77], v[134:137], v[210:213], v[74:77]
	v_mfma_f32_16x16x32_bf16 v[130:133], v[138:141], v[162:165], v[130:133]
	v_mfma_f32_16x16x32_bf16 v[126:129], v[146:149], v[162:165], v[126:129]
	v_mfma_f32_16x16x32_bf16 v[102:105], v[138:141], v[170:173], v[102:105]
	v_mfma_f32_16x16x32_bf16 v[98:101], v[146:149], v[170:173], v[98:101]
	v_mfma_f32_16x16x32_bf16 v[86:89], v[138:141], v[178:181], v[86:89]
	v_mfma_f32_16x16x32_bf16 v[82:85], v[146:149], v[178:181], v[82:85]
	v_mfma_f32_16x16x32_bf16 v[70:73], v[138:141], v[186:189], v[70:73]
	v_mfma_f32_16x16x32_bf16 v[66:69], v[146:149], v[186:189], v[66:69]
	v_mfma_f32_16x16x32_bf16 v[130:133], v[142:145], v[166:169], v[130:133]
	v_mfma_f32_16x16x32_bf16 v[126:129], v[154:157], v[166:169], v[126:129]
	v_mfma_f32_16x16x32_bf16 v[102:105], v[142:145], v[174:177], v[102:105]
	v_mfma_f32_16x16x32_bf16 v[98:101], v[154:157], v[174:177], v[98:101]
	v_mfma_f32_16x16x32_bf16 v[86:89], v[142:145], v[182:185], v[86:89]
	v_mfma_f32_16x16x32_bf16 v[82:85], v[154:157], v[182:185], v[82:85]
	v_mfma_f32_16x16x32_bf16 v[70:73], v[142:145], v[210:213], v[70:73]
	v_mfma_f32_16x16x32_bf16 v[66:69], v[154:157], v[210:213], v[66:69]
	s_setprio 0
	s_barrier
	s_add_i32 s18, s53, s34
	v_lshl_add_u64 v[196:197], s[22:23], 0, v[192:193]
	s_mov_b32 m0, s18
	ds_read_b128 v[162:165], v214 offset:16384
	ds_read_b128 v[166:169], v214 offset:17408
	ds_read_b128 v[170:173], v214 offset:18432
	ds_read_b128 v[174:177], v214 offset:19456
	ds_read_b128 v[178:181], v214 offset:20480
	ds_read_b128 v[182:185], v214 offset:21504
	ds_read_b128 v[186:189], v214 offset:22528
	ds_read_b128 v[210:213], v214 offset:23552
	global_load_lds_dwordx4 v[196:197], off
	s_add_i32 m0, s18, 0x2000
	s_add_u32 s18, s22, 0xb0000
	v_lshl_add_u64 v[198:199], s[22:23], 0, v[204:205]
	s_addc_u32 s19, s23, 0
	s_add_i32 s53, s54, s34
	global_load_lds_dwordx4 v[198:199], off
	v_lshl_add_u64 v[216:217], s[18:19], 0, v[192:193]
	s_mov_b32 m0, s53
	v_lshl_add_u64 v[220:221], s[24:25], 0, v[194:195]
	global_load_lds_dwordx4 v[216:217], off
	v_lshl_add_u64 v[216:217], s[18:19], 0, v[204:205]
	s_add_i32 m0, s53, 0x2000
	s_nop 0
	global_load_lds_dwordx4 v[216:217], off
	v_lshl_add_u64 v[216:217], s[24:25], 0, v[190:191]
	s_mov_b32 m0, s35
	s_nop 0
	global_load_lds_dwordx4 v[216:217], off
	s_mov_b32 m0, s36
	s_nop 0
	global_load_lds_dwordx4 v[220:221], off
	s_waitcnt vmcnt(8)
	s_waitcnt lgkmcnt(0)
	s_barrier
	s_setprio 1
	v_mfma_f32_16x16x32_bf16 v[62:65], v[110:113], v[162:165], v[62:65]
	v_mfma_f32_16x16x32_bf16 v[58:61], v[122:125], v[162:165], v[58:61]
	v_mfma_f32_16x16x32_bf16 v[46:49], v[110:113], v[170:173], v[46:49]
	v_mfma_f32_16x16x32_bf16 v[42:45], v[122:125], v[170:173], v[42:45]
	v_mfma_f32_16x16x32_bf16 v[30:33], v[110:113], v[178:181], v[30:33]
	v_mfma_f32_16x16x32_bf16 v[26:29], v[122:125], v[178:181], v[26:29]
	v_mfma_f32_16x16x32_bf16 v[14:17], v[110:113], v[186:189], v[14:17]
	v_mfma_f32_16x16x32_bf16 v[10:13], v[122:125], v[186:189], v[10:13]
	v_mfma_f32_16x16x32_bf16 v[62:65], v[118:121], v[166:169], v[62:65]
	v_mfma_f32_16x16x32_bf16 v[58:61], v[134:137], v[166:169], v[58:61]
	v_mfma_f32_16x16x32_bf16 v[46:49], v[118:121], v[174:177], v[46:49]
	v_mfma_f32_16x16x32_bf16 v[42:45], v[134:137], v[174:177], v[42:45]
	v_mfma_f32_16x16x32_bf16 v[30:33], v[118:121], v[182:185], v[30:33]
	v_mfma_f32_16x16x32_bf16 v[26:29], v[134:137], v[182:185], v[26:29]
	v_mfma_f32_16x16x32_bf16 v[14:17], v[118:121], v[210:213], v[14:17]
	v_mfma_f32_16x16x32_bf16 v[10:13], v[134:137], v[210:213], v[10:13]
	v_mfma_f32_16x16x32_bf16 v[54:57], v[138:141], v[162:165], v[54:57]
	v_mfma_f32_16x16x32_bf16 v[50:53], v[146:149], v[162:165], v[50:53]
	v_mfma_f32_16x16x32_bf16 v[38:41], v[138:141], v[170:173], v[38:41]
	v_mfma_f32_16x16x32_bf16 v[34:37], v[146:149], v[170:173], v[34:37]
	v_mfma_f32_16x16x32_bf16 v[22:25], v[138:141], v[178:181], v[22:25]
	v_mfma_f32_16x16x32_bf16 v[18:21], v[146:149], v[178:181], v[18:21]
	v_mfma_f32_16x16x32_bf16 v[6:9], v[138:141], v[186:189], v[6:9]
	v_mfma_f32_16x16x32_bf16 v[2:5], v[146:149], v[186:189], v[2:5]
	v_mfma_f32_16x16x32_bf16 v[54:57], v[142:145], v[166:169], v[54:57]
	v_mfma_f32_16x16x32_bf16 v[50:53], v[154:157], v[166:169], v[50:53]
	v_mfma_f32_16x16x32_bf16 v[38:41], v[142:145], v[174:177], v[38:41]
	v_mfma_f32_16x16x32_bf16 v[34:37], v[154:157], v[174:177], v[34:37]
	v_mfma_f32_16x16x32_bf16 v[22:25], v[142:145], v[182:185], v[22:25]
	v_mfma_f32_16x16x32_bf16 v[18:21], v[154:157], v[182:185], v[18:21]
	v_mfma_f32_16x16x32_bf16 v[6:9], v[142:145], v[210:213], v[6:9]
	v_mfma_f32_16x16x32_bf16 v[2:5], v[154:157], v[210:213], v[2:5]
	s_setprio 0
	s_barrier
	s_add_i32 s53, 0, 0x18000
	s_add_i32 s54, 0, 0x1c000
	v_add_u32_e32 v134, s53, v1
	v_add_u32_e32 v154, s54, v1
	ds_read_b128 v[110:113], v134
	ds_read_b128 v[118:121], v134 offset:1024
	ds_read_b128 v[122:125], v134 offset:2048
	ds_read_b128 v[134:137], v134 offset:3072
	ds_read_b128 v[138:141], v154
	ds_read_b128 v[142:145], v154 offset:1024
	ds_read_b128 v[146:149], v154 offset:2048
	ds_read_b128 v[154:157], v154 offset:3072
	s_add_u32 s18, s24, 0xb0000
	s_addc_u32 s19, s25, 0
	s_mov_b32 m0, s37
	v_lshl_add_u64 v[222:223], s[18:19], 0, v[190:191]
	ds_read_b128 v[162:165], v214 offset:32768
	ds_read_b128 v[166:169], v214 offset:33792
	ds_read_b128 v[170:173], v214 offset:34816
	ds_read_b128 v[174:177], v214 offset:35840
	ds_read_b128 v[178:181], v214 offset:36864
	ds_read_b128 v[182:185], v214 offset:37888
	ds_read_b128 v[186:189], v214 offset:38912
	ds_read_b128 v[210:213], v214 offset:39936
	global_load_lds_dwordx4 v[222:223], off
	v_lshl_add_u64 v[222:223], s[18:19], 0, v[194:195]
	s_mov_b32 m0, s38
	s_nop 0
	global_load_lds_dwordx4 v[222:223], off
	s_waitcnt vmcnt(8)
	s_waitcnt lgkmcnt(0)
	s_barrier
	s_setprio 1
	v_mfma_f32_16x16x32_bf16 v[158:161], v[110:113], v[162:165], v[158:161]
	v_mfma_f32_16x16x32_bf16 v[150:153], v[122:125], v[162:165], v[150:153]
	v_mfma_f32_16x16x32_bf16 v[114:117], v[110:113], v[170:173], v[114:117]
	v_mfma_f32_16x16x32_bf16 v[106:109], v[122:125], v[170:173], v[106:109]
	v_mfma_f32_16x16x32_bf16 v[94:97], v[110:113], v[178:181], v[94:97]
	v_mfma_f32_16x16x32_bf16 v[90:93], v[122:125], v[178:181], v[90:93]
	v_mfma_f32_16x16x32_bf16 v[78:81], v[110:113], v[186:189], v[78:81]
	v_mfma_f32_16x16x32_bf16 v[74:77], v[122:125], v[186:189], v[74:77]
	v_mfma_f32_16x16x32_bf16 v[158:161], v[118:121], v[166:169], v[158:161]
	v_mfma_f32_16x16x32_bf16 v[150:153], v[134:137], v[166:169], v[150:153]
	v_mfma_f32_16x16x32_bf16 v[114:117], v[118:121], v[174:177], v[114:117]
	v_mfma_f32_16x16x32_bf16 v[106:109], v[134:137], v[174:177], v[106:109]
	v_mfma_f32_16x16x32_bf16 v[94:97], v[118:121], v[182:185], v[94:97]
	v_mfma_f32_16x16x32_bf16 v[90:93], v[134:137], v[182:185], v[90:93]
	v_mfma_f32_16x16x32_bf16 v[78:81], v[118:121], v[210:213], v[78:81]
	v_mfma_f32_16x16x32_bf16 v[74:77], v[134:137], v[210:213], v[74:77]
	v_mfma_f32_16x16x32_bf16 v[130:133], v[138:141], v[162:165], v[130:133]
	v_mfma_f32_16x16x32_bf16 v[126:129], v[146:149], v[162:165], v[126:129]
	v_mfma_f32_16x16x32_bf16 v[102:105], v[138:141], v[170:173], v[102:105]
	v_mfma_f32_16x16x32_bf16 v[98:101], v[146:149], v[170:173], v[98:101]
	v_mfma_f32_16x16x32_bf16 v[86:89], v[138:141], v[178:181], v[86:89]
	v_mfma_f32_16x16x32_bf16 v[82:85], v[146:149], v[178:181], v[82:85]
	v_mfma_f32_16x16x32_bf16 v[70:73], v[138:141], v[186:189], v[70:73]
	v_mfma_f32_16x16x32_bf16 v[66:69], v[146:149], v[186:189], v[66:69]
	v_mfma_f32_16x16x32_bf16 v[130:133], v[142:145], v[166:169], v[130:133]
	v_mfma_f32_16x16x32_bf16 v[126:129], v[154:157], v[166:169], v[126:129]
	v_mfma_f32_16x16x32_bf16 v[102:105], v[142:145], v[174:177], v[102:105]
	v_mfma_f32_16x16x32_bf16 v[98:101], v[154:157], v[174:177], v[98:101]
	v_mfma_f32_16x16x32_bf16 v[86:89], v[142:145], v[182:185], v[86:89]
	v_mfma_f32_16x16x32_bf16 v[82:85], v[154:157], v[182:185], v[82:85]
	v_mfma_f32_16x16x32_bf16 v[70:73], v[142:145], v[210:213], v[70:73]
	v_mfma_f32_16x16x32_bf16 v[66:69], v[154:157], v[210:213], v[66:69]
	s_setprio 0
	s_barrier
	s_add_i32 s18, s53, s34
	v_lshl_add_u64 v[196:197], v[196:197], 0, s[94:95]
	s_mov_b32 m0, s18
	ds_read_b128 v[162:165], v214 offset:49152
	ds_read_b128 v[166:169], v214 offset:50176
	ds_read_b128 v[170:173], v214 offset:51200
	ds_read_b128 v[174:177], v214 offset:52224
	ds_read_b128 v[178:181], v214 offset:53248
	ds_read_b128 v[182:185], v214 offset:54272
	ds_read_b128 v[186:189], v214 offset:55296
	ds_read_b128 v[210:213], v214 offset:56320
	global_load_lds_dwordx4 v[196:197], off
	s_add_i32 m0, s18, 0x2000
	s_add_u32 s18, s22, 0xb0080
	v_lshl_add_u64 v[196:197], v[198:199], 0, s[94:95]
	s_addc_u32 s19, s23, 0
	s_add_i32 s22, s54, s34
	global_load_lds_dwordx4 v[196:197], off
	v_lshl_add_u64 v[196:197], s[18:19], 0, v[192:193]
	s_mov_b32 m0, s22
	s_nop 0
	global_load_lds_dwordx4 v[196:197], off
	v_lshl_add_u64 v[196:197], s[18:19], 0, v[204:205]
	s_add_i32 m0, s22, 0x2000
	s_nop 0
	global_load_lds_dwordx4 v[196:197], off
	v_lshl_add_u64 v[196:197], v[216:217], 0, s[94:95]
	s_mov_b32 m0, s41
	s_nop 0
	global_load_lds_dwordx4 v[196:197], off
	v_lshl_add_u64 v[196:197], v[220:221], 0, s[94:95]
	s_mov_b32 m0, s42
	s_nop 0
	global_load_lds_dwordx4 v[196:197], off
	s_waitcnt vmcnt(8)
	s_waitcnt lgkmcnt(0)
	s_barrier
	s_setprio 1
	v_mfma_f32_16x16x32_bf16 v[62:65], v[110:113], v[162:165], v[62:65]
	v_mfma_f32_16x16x32_bf16 v[58:61], v[122:125], v[162:165], v[58:61]
	v_mfma_f32_16x16x32_bf16 v[46:49], v[110:113], v[170:173], v[46:49]
	v_mfma_f32_16x16x32_bf16 v[42:45], v[122:125], v[170:173], v[42:45]
	v_mfma_f32_16x16x32_bf16 v[30:33], v[110:113], v[178:181], v[30:33]
	v_mfma_f32_16x16x32_bf16 v[26:29], v[122:125], v[178:181], v[26:29]
	v_mfma_f32_16x16x32_bf16 v[14:17], v[110:113], v[186:189], v[14:17]
	v_mfma_f32_16x16x32_bf16 v[10:13], v[122:125], v[186:189], v[10:13]
	v_mfma_f32_16x16x32_bf16 v[62:65], v[118:121], v[166:169], v[62:65]
	v_mfma_f32_16x16x32_bf16 v[58:61], v[134:137], v[166:169], v[58:61]
	v_mfma_f32_16x16x32_bf16 v[46:49], v[118:121], v[174:177], v[46:49]
	v_mfma_f32_16x16x32_bf16 v[42:45], v[134:137], v[174:177], v[42:45]
	v_mfma_f32_16x16x32_bf16 v[30:33], v[118:121], v[182:185], v[30:33]
	v_mfma_f32_16x16x32_bf16 v[26:29], v[134:137], v[182:185], v[26:29]
	v_mfma_f32_16x16x32_bf16 v[14:17], v[118:121], v[210:213], v[14:17]
	v_mfma_f32_16x16x32_bf16 v[10:13], v[134:137], v[210:213], v[10:13]
	v_mfma_f32_16x16x32_bf16 v[54:57], v[138:141], v[162:165], v[54:57]
	v_mfma_f32_16x16x32_bf16 v[50:53], v[146:149], v[162:165], v[50:53]
	v_mfma_f32_16x16x32_bf16 v[38:41], v[138:141], v[170:173], v[38:41]
	v_mfma_f32_16x16x32_bf16 v[34:37], v[146:149], v[170:173], v[34:37]
	v_mfma_f32_16x16x32_bf16 v[22:25], v[138:141], v[178:181], v[22:25]
	v_mfma_f32_16x16x32_bf16 v[18:21], v[146:149], v[178:181], v[18:21]
	v_mfma_f32_16x16x32_bf16 v[6:9], v[138:141], v[186:189], v[6:9]
	v_mfma_f32_16x16x32_bf16 v[2:5], v[146:149], v[186:189], v[2:5]
	v_mfma_f32_16x16x32_bf16 v[54:57], v[142:145], v[166:169], v[54:57]
	v_mfma_f32_16x16x32_bf16 v[50:53], v[154:157], v[166:169], v[50:53]
	v_mfma_f32_16x16x32_bf16 v[38:41], v[142:145], v[174:177], v[38:41]
	v_mfma_f32_16x16x32_bf16 v[34:37], v[154:157], v[174:177], v[34:37]
	v_mfma_f32_16x16x32_bf16 v[22:25], v[142:145], v[182:185], v[22:25]
	v_mfma_f32_16x16x32_bf16 v[18:21], v[154:157], v[182:185], v[18:21]
	v_mfma_f32_16x16x32_bf16 v[6:9], v[142:145], v[210:213], v[6:9]
	v_mfma_f32_16x16x32_bf16 v[2:5], v[154:157], v[210:213], v[2:5]
	s_setprio 0
	s_barrier
	s_add_i32 s52, s52, 2
	s_add_u32 s50, s50, 0x100
	s_addc_u32 s51, s51, 0
	s_cmp_gt_u32 s52, 41
	s_mov_b64 s[18:19], s[20:21]
	s_cbranch_scc0 .LBB0_1263
	s_and_b64 vcc, exec, s[14:15]
	s_cbranch_vccz .LBB0_1266
	s_barrier
